# ph_mod batched loads; scan units permuted so value-slice siblings share an XCD; FG epilogue lb loads hoisted; layer-1 merge tiles mapped 1:1 onto blocks
# speedup vs baseline: 1.0185x; 1.0185x over previous
; __device__ __forceinline__ float siluf_(float x) { return x * __builtin_amdgcn_rcpf(1.f + __expf(-x)); }
; __device__ __forceinline__ int otid() { int t = threadIdx.x; asm volatile("" : "+v"(t)); return t; }
; __device__ void ph_mod(const Params& p, char* smem) {
;   float (*sl)[D] = (float (*)[D])smem;
;   float (*red)[17][64] = (float (*)[17][64])smem;
;   const int tid = otid();
;   const int kq = __builtin_amdgcn_readfirstlane(tid >> 6), cc = tid & 63;
;   for (int u = blockIdx.x; u < 96; u += gridDim.x) {
;     for (int i = tid; i < 17 * D; i += 256) sl[0][i] = siluf_(i < 16 * D ? p.c[i] : p.c_ctx[i - 16 * D]);
;     __syncthreads();
;     int l = u / 48, col = (u % 48) * 64 + cc;
;     float acc[17];
; #pragma unroll
;     for (int r = 0; r < 17; ++r) acc[r] = 0.f;
;     const float* w = p.ada_w + (long)l * D * 3072 + col;
; #pragma unroll 4
;     for (int k = kq * 256; k < kq * 256 + 256; ++k) {
;       float wv = w[(long)k * 3072];
.LBB0_10:
	s_or_b64 exec, exec, s[2:3]
	v_mov_b32_e32 v2, v156
	v_readlane_b32 s0, v242, 2
	s_cmpk_gt_i32 s0, 0x5f
	v_readfirstlane_b32 s2, v2
	s_cbranch_scc1 .LBB0_21
	s_ashr_i32 s14, s2, 6
	s_movk_i32 s2, 0x4400
	v_and_b32_e32 v1, 63, v2
	v_cmp_gt_i32_e32 vcc, s2, v2
	s_mul_i32 s2, s14, 0x1100
	v_readlane_b32 s0, v242, 0
	v_lshl_or_b32 v26, v1, 2, s2
	s_movk_i32 s2, 0x440
	v_readlane_b32 s1, v242, 1
	v_cmp_gt_i32_e64 s[4:5], s2, v2
	s_load_dwordx2 s[6:7], s[0:1], 0x8
	s_load_dwordx4 s[8:11], s[0:1], 0x18
	s_load_dwordx2 s[2:3], s[0:1], 0x28
	s_load_dwordx2 s[12:13], s[0:1], 0xd8
	v_ashrrev_i32_e32 v3, 31, v2
	s_lshl_b32 s15, s14, 8
	s_waitcnt lgkmcnt(0)
	v_lshl_add_u64 v[4:5], v[2:3], 2, s[6:7]
	s_mul_i32 s6, s14, 0x300000
	s_mul_hi_i32 s7, s15, 0x3000
	s_add_u32 s6, s10, s6
	s_addc_u32 s7, s11, s7
	s_add_u32 s28, s6, 0
	s_mov_b32 s10, 0xffff0000
	v_lshlrev_b32_e32 v27, 2, v2
	s_movk_i32 s27, 0x3000
	s_addc_u32 s29, s7, 0
	s_lshl_b32 s30, s14, 10
	s_movk_i32 s31, 0x4000
	v_mov_b32_e32 v7, 0
	s_mov_b32 s11, -1
	s_mov_b64 s[14:15], 0x400
	s_movk_i32 s33, 0x42ff
	s_mov_b32 s34, 0xffff7000
	s_movk_i32 s35, 0xa000
	s_movk_i32 s36, 0xd000
	s_mov_b64 s[18:19], 0x3000
	s_movk_i32 s37, 0x33f
	v_readlane_b32 s38, v242, 2
	s_branch .LBB0_13

; __device__ __forceinline__ float siluf_(float x) { return x * __builtin_amdgcn_rcpf(1.f + __expf(-x)); }
; __device__ __forceinline__ int otid() { int t = threadIdx.x; asm volatile("" : "+v"(t)); return t; }
; __device__ void ph_mod(const Params& p, char* smem) {
;     ...
;   const int tid = otid();
;   const int kq = __builtin_amdgcn_readfirstlane(tid >> 6), cc = tid & 63;
;   for (int u = blockIdx.x; u < 96; u += gridDim.x) {
;     for (int i = tid; i < 17 * D; i += 256) sl[0][i] = siluf_(i < 16 * D ? p.c[i] : p.c_ctx[i - 16 * D]);
.LBB0_13:
	s_and_saveexec_b64 s[20:21], vcc
	s_cbranch_execz .LBB0_16
	v_lshl_add_u64 v[8:9], v[2:3], 2, s[8:9]
	v_mov_b64_e32 v[10:11], v[4:5]
	v_add_u32_e32 v6, 0x10000, v27
	s_mov_b64 s[22:23], 0x1000
	global_load_dword v28, v[10:11], off
	global_load_dword v29, v[10:11], off offset:1024
	global_load_dword v30, v[10:11], off offset:2048
	global_load_dword v31, v[10:11], off offset:3072
	v_lshl_add_u64 v[10:11], v[10:11], 0, s[22:23]
	global_load_dword v32, v[10:11], off
	global_load_dword v33, v[10:11], off offset:1024
	global_load_dword v34, v[10:11], off offset:2048
	global_load_dword v35, v[10:11], off offset:3072
	v_lshl_add_u64 v[10:11], v[10:11], 0, s[22:23]
	global_load_dword v36, v[10:11], off
	global_load_dword v37, v[10:11], off offset:1024
	global_load_dword v38, v[10:11], off offset:2048
	global_load_dword v39, v[10:11], off offset:3072
	v_lshl_add_u64 v[10:11], v[10:11], 0, s[22:23]
	global_load_dword v40, v[10:11], off
	global_load_dword v41, v[10:11], off offset:1024
	global_load_dword v42, v[10:11], off offset:2048
	global_load_dword v43, v[10:11], off offset:3072
	v_lshl_add_u64 v[10:11], v[10:11], 0, s[22:23]
	global_load_dword v44, v[10:11], off
	global_load_dword v45, v[10:11], off offset:1024
	global_load_dword v46, v[10:11], off offset:2048
	global_load_dword v47, v[10:11], off offset:3072
	v_lshl_add_u64 v[10:11], v[10:11], 0, s[22:23]
	global_load_dword v48, v[10:11], off
	global_load_dword v49, v[10:11], off offset:1024
	global_load_dword v50, v[10:11], off offset:2048
	global_load_dword v51, v[10:11], off offset:3072
	v_lshl_add_u64 v[10:11], v[10:11], 0, s[22:23]
	global_load_dword v52, v[10:11], off
	global_load_dword v53, v[10:11], off offset:1024
	global_load_dword v54, v[10:11], off offset:2048
	global_load_dword v55, v[10:11], off offset:3072
	v_lshl_add_u64 v[10:11], v[10:11], 0, s[22:23]
	global_load_dword v56, v[10:11], off
	global_load_dword v57, v[10:11], off offset:1024
	global_load_dword v58, v[10:11], off offset:2048
	global_load_dword v59, v[10:11], off offset:3072
	v_lshl_add_u64 v[10:11], v[10:11], 0, s[22:23]
	global_load_dword v60, v[10:11], off
	global_load_dword v61, v[10:11], off offset:1024
	s_waitcnt vmcnt(33)
	v_mul_f32_e32 v12, 0xbfb8aa3b, v28
	v_exp_f32_e32 v12, v12
	s_nop 0
	v_add_f32_e32 v12, 1.0, v12
	v_rcp_f32_e32 v12, v12
	s_nop 0
	v_mul_f32_e32 v28, v28, v12
	ds_write_b32 v27, v28
	s_waitcnt vmcnt(32)
	v_mul_f32_e32 v12, 0xbfb8aa3b, v29
	v_exp_f32_e32 v12, v12
	s_nop 0
	v_add_f32_e32 v12, 1.0, v12
	v_rcp_f32_e32 v12, v12
	s_nop 0
	v_mul_f32_e32 v29, v29, v12
	ds_write_b32 v27, v29 offset:1024
	s_waitcnt vmcnt(31)
	v_mul_f32_e32 v12, 0xbfb8aa3b, v30
	v_exp_f32_e32 v12, v12
	s_nop 0
	v_add_f32_e32 v12, 1.0, v12
	v_rcp_f32_e32 v12, v12
	s_nop 0
	v_mul_f32_e32 v30, v30, v12
	ds_write_b32 v27, v30 offset:2048
	s_waitcnt vmcnt(30)
	v_mul_f32_e32 v12, 0xbfb8aa3b, v31
	v_exp_f32_e32 v12, v12
	s_nop 0
	v_add_f32_e32 v12, 1.0, v12
	v_rcp_f32_e32 v12, v12
	s_nop 0
	v_mul_f32_e32 v31, v31, v12
	ds_write_b32 v27, v31 offset:3072
	s_waitcnt vmcnt(29)
	v_mul_f32_e32 v12, 0xbfb8aa3b, v32
	v_exp_f32_e32 v12, v12
	s_nop 0
	v_add_f32_e32 v12, 1.0, v12
	v_rcp_f32_e32 v12, v12
	s_nop 0
	v_mul_f32_e32 v32, v32, v12
	ds_write_b32 v27, v32 offset:4096
	s_waitcnt vmcnt(28)
	v_mul_f32_e32 v12, 0xbfb8aa3b, v33
	v_exp_f32_e32 v12, v12
	s_nop 0
	v_add_f32_e32 v12, 1.0, v12
	v_rcp_f32_e32 v12, v12
	s_nop 0
	v_mul_f32_e32 v33, v33, v12
	ds_write_b32 v27, v33 offset:5120
	s_waitcnt vmcnt(27)
	v_mul_f32_e32 v12, 0xbfb8aa3b, v34
	v_exp_f32_e32 v12, v12
	s_nop 0
	v_add_f32_e32 v12, 1.0, v12
	v_rcp_f32_e32 v12, v12
	s_nop 0
	v_mul_f32_e32 v34, v34, v12
	ds_write_b32 v27, v34 offset:6144
	s_waitcnt vmcnt(26)
	v_mul_f32_e32 v12, 0xbfb8aa3b, v35
	v_exp_f32_e32 v12, v12
	s_nop 0
	v_add_f32_e32 v12, 1.0, v12
	v_rcp_f32_e32 v12, v12
	s_nop 0
	v_mul_f32_e32 v35, v35, v12
	ds_write_b32 v27, v35 offset:7168
	s_waitcnt vmcnt(25)
	v_mul_f32_e32 v12, 0xbfb8aa3b, v36
	v_exp_f32_e32 v12, v12
	s_nop 0
	v_add_f32_e32 v12, 1.0, v12
	v_rcp_f32_e32 v12, v12
	s_nop 0
	v_mul_f32_e32 v36, v36, v12
	ds_write_b32 v27, v36 offset:8192
	s_waitcnt vmcnt(24)
	v_mul_f32_e32 v12, 0xbfb8aa3b, v37
	v_exp_f32_e32 v12, v12
	s_nop 0
	v_add_f32_e32 v12, 1.0, v12
	v_rcp_f32_e32 v12, v12
	s_nop 0
	v_mul_f32_e32 v37, v37, v12
	ds_write_b32 v27, v37 offset:9216
	s_waitcnt vmcnt(23)
	v_mul_f32_e32 v12, 0xbfb8aa3b, v38
	v_exp_f32_e32 v12, v12
	s_nop 0
	v_add_f32_e32 v12, 1.0, v12
	v_rcp_f32_e32 v12, v12
	s_nop 0
	v_mul_f32_e32 v38, v38, v12
	ds_write_b32 v27, v38 offset:10240
	s_waitcnt vmcnt(22)
	v_mul_f32_e32 v12, 0xbfb8aa3b, v39
	v_exp_f32_e32 v12, v12
	s_nop 0
	v_add_f32_e32 v12, 1.0, v12
	v_rcp_f32_e32 v12, v12
	s_nop 0
	v_mul_f32_e32 v39, v39, v12
	ds_write_b32 v27, v39 offset:11264
	s_waitcnt vmcnt(21)
	v_mul_f32_e32 v12, 0xbfb8aa3b, v40
	v_exp_f32_e32 v12, v12
	s_nop 0
	v_add_f32_e32 v12, 1.0, v12
	v_rcp_f32_e32 v12, v12
	s_nop 0
	v_mul_f32_e32 v40, v40, v12
	ds_write_b32 v27, v40 offset:12288
	s_waitcnt vmcnt(20)
	v_mul_f32_e32 v12, 0xbfb8aa3b, v41
	v_exp_f32_e32 v12, v12
	s_nop 0
	v_add_f32_e32 v12, 1.0, v12
	v_rcp_f32_e32 v12, v12
	s_nop 0
	v_mul_f32_e32 v41, v41, v12
	ds_write_b32 v27, v41 offset:13312
	s_waitcnt vmcnt(19)
	v_mul_f32_e32 v12, 0xbfb8aa3b, v42
	v_exp_f32_e32 v12, v12
	s_nop 0
	v_add_f32_e32 v12, 1.0, v12
	v_rcp_f32_e32 v12, v12
	s_nop 0
	v_mul_f32_e32 v42, v42, v12
	ds_write_b32 v27, v42 offset:14336
	s_waitcnt vmcnt(18)
	v_mul_f32_e32 v12, 0xbfb8aa3b, v43
	v_exp_f32_e32 v12, v12
	s_nop 0
	v_add_f32_e32 v12, 1.0, v12
	v_rcp_f32_e32 v12, v12
	s_nop 0
	v_mul_f32_e32 v43, v43, v12
	ds_write_b32 v27, v43 offset:15360
	s_waitcnt vmcnt(17)
; __device__ __forceinline__ float siluf_(float x) { return x * __builtin_amdgcn_rcpf(1.f + __expf(-x)); }
; __device__ void ph_mod(const Params& p, char* smem) {
;     ...
;     for (int i = tid; i < 17 * D; i += 256) sl[0][i] = siluf_(i < 16 * D ? p.c[i] : p.c_ctx[i - 16 * D]);
	v_mul_f32_e32 v12, 0xbfb8aa3b, v44
	v_exp_f32_e32 v12, v12
	s_nop 0
	v_add_f32_e32 v12, 1.0, v12
	v_rcp_f32_e32 v12, v12
	s_nop 0
	v_mul_f32_e32 v44, v44, v12
	ds_write_b32 v27, v44 offset:16384
	s_waitcnt vmcnt(16)
	v_mul_f32_e32 v12, 0xbfb8aa3b, v45
	v_exp_f32_e32 v12, v12
	s_nop 0
	v_add_f32_e32 v12, 1.0, v12
	v_rcp_f32_e32 v12, v12
	s_nop 0
	v_mul_f32_e32 v45, v45, v12
	ds_write_b32 v27, v45 offset:17408
	s_waitcnt vmcnt(15)
	v_mul_f32_e32 v12, 0xbfb8aa3b, v46
	v_exp_f32_e32 v12, v12
	s_nop 0
	v_add_f32_e32 v12, 1.0, v12
	v_rcp_f32_e32 v12, v12
	s_nop 0
	v_mul_f32_e32 v46, v46, v12
	ds_write_b32 v27, v46 offset:18432
	s_waitcnt vmcnt(14)
	v_mul_f32_e32 v12, 0xbfb8aa3b, v47
	v_exp_f32_e32 v12, v12
	s_nop 0
	v_add_f32_e32 v12, 1.0, v12
	v_rcp_f32_e32 v12, v12
	s_nop 0
	v_mul_f32_e32 v47, v47, v12
	ds_write_b32 v27, v47 offset:19456
	s_waitcnt vmcnt(13)
	v_mul_f32_e32 v12, 0xbfb8aa3b, v48
	v_exp_f32_e32 v12, v12
	s_nop 0
	v_add_f32_e32 v12, 1.0, v12
	v_rcp_f32_e32 v12, v12
	s_nop 0
	v_mul_f32_e32 v48, v48, v12
	ds_write_b32 v27, v48 offset:20480
	s_waitcnt vmcnt(12)
	v_mul_f32_e32 v12, 0xbfb8aa3b, v49
	v_exp_f32_e32 v12, v12
	s_nop 0
	v_add_f32_e32 v12, 1.0, v12
	v_rcp_f32_e32 v12, v12
	s_nop 0
	v_mul_f32_e32 v49, v49, v12
	ds_write_b32 v27, v49 offset:21504
	s_waitcnt vmcnt(11)
	v_mul_f32_e32 v12, 0xbfb8aa3b, v50
	v_exp_f32_e32 v12, v12
	s_nop 0
	v_add_f32_e32 v12, 1.0, v12
	v_rcp_f32_e32 v12, v12
	s_nop 0
	v_mul_f32_e32 v50, v50, v12
	ds_write_b32 v27, v50 offset:22528
	s_waitcnt vmcnt(10)
	v_mul_f32_e32 v12, 0xbfb8aa3b, v51
	v_exp_f32_e32 v12, v12
	s_nop 0
	v_add_f32_e32 v12, 1.0, v12
	v_rcp_f32_e32 v12, v12
	s_nop 0
	v_mul_f32_e32 v51, v51, v12
	ds_write_b32 v27, v51 offset:23552
	s_waitcnt vmcnt(9)
	v_mul_f32_e32 v12, 0xbfb8aa3b, v52
	v_exp_f32_e32 v12, v12
	s_nop 0
	v_add_f32_e32 v12, 1.0, v12
	v_rcp_f32_e32 v12, v12
	s_nop 0
	v_mul_f32_e32 v52, v52, v12
	ds_write_b32 v27, v52 offset:24576
	s_waitcnt vmcnt(8)
	v_mul_f32_e32 v12, 0xbfb8aa3b, v53
	v_exp_f32_e32 v12, v12
	s_nop 0
	v_add_f32_e32 v12, 1.0, v12
	v_rcp_f32_e32 v12, v12
	s_nop 0
	v_mul_f32_e32 v53, v53, v12
	ds_write_b32 v27, v53 offset:25600
	s_waitcnt vmcnt(7)
	v_mul_f32_e32 v12, 0xbfb8aa3b, v54
	v_exp_f32_e32 v12, v12
	s_nop 0
	v_add_f32_e32 v12, 1.0, v12
	v_rcp_f32_e32 v12, v12
	s_nop 0
	v_mul_f32_e32 v54, v54, v12
	ds_write_b32 v27, v54 offset:26624
	s_waitcnt vmcnt(6)
	v_mul_f32_e32 v12, 0xbfb8aa3b, v55
	v_exp_f32_e32 v12, v12
	s_nop 0
	v_add_f32_e32 v12, 1.0, v12
	v_rcp_f32_e32 v12, v12
	s_nop 0
	v_mul_f32_e32 v55, v55, v12
	ds_write_b32 v27, v55 offset:27648
	s_waitcnt vmcnt(5)
	v_mul_f32_e32 v12, 0xbfb8aa3b, v56
	v_exp_f32_e32 v12, v12
	s_nop 0
	v_add_f32_e32 v12, 1.0, v12
	v_rcp_f32_e32 v12, v12
	s_nop 0
	v_mul_f32_e32 v56, v56, v12
	ds_write_b32 v27, v56 offset:28672
	s_waitcnt vmcnt(4)
	v_mul_f32_e32 v12, 0xbfb8aa3b, v57
	v_exp_f32_e32 v12, v12
	s_nop 0
	v_add_f32_e32 v12, 1.0, v12
	v_rcp_f32_e32 v12, v12
	s_nop 0
	v_mul_f32_e32 v57, v57, v12
	ds_write_b32 v27, v57 offset:29696
	s_waitcnt vmcnt(3)
	v_mul_f32_e32 v12, 0xbfb8aa3b, v58
	v_exp_f32_e32 v12, v12
	s_nop 0
	v_add_f32_e32 v12, 1.0, v12
	v_rcp_f32_e32 v12, v12
	s_nop 0
	v_mul_f32_e32 v58, v58, v12
	ds_write_b32 v27, v58 offset:30720
	s_waitcnt vmcnt(2)
	v_mul_f32_e32 v12, 0xbfb8aa3b, v59
	v_exp_f32_e32 v12, v12
	s_nop 0
	v_add_f32_e32 v12, 1.0, v12
	v_rcp_f32_e32 v12, v12
	s_nop 0
	v_mul_f32_e32 v59, v59, v12
	ds_write_b32 v27, v59 offset:31744
	s_waitcnt vmcnt(1)
	v_mul_f32_e32 v12, 0xbfb8aa3b, v60
	v_exp_f32_e32 v12, v12
	s_nop 0
	v_add_f32_e32 v12, 1.0, v12
	v_rcp_f32_e32 v12, v12
	s_nop 0
	v_mul_f32_e32 v60, v60, v12
	ds_write_b32 v27, v60 offset:32768
	s_waitcnt vmcnt(0)
	v_mul_f32_e32 v12, 0xbfb8aa3b, v61
	v_exp_f32_e32 v12, v12
	s_nop 0
	v_add_f32_e32 v12, 1.0, v12
	v_rcp_f32_e32 v12, v12
	s_nop 0
	v_mul_f32_e32 v61, v61, v12
	ds_write_b32 v27, v61 offset:33792
	global_load_dword v28, v[10:11], off offset:2048
	global_load_dword v29, v[10:11], off offset:3072
	v_lshl_add_u64 v[10:11], v[10:11], 0, s[22:23]
	global_load_dword v30, v[10:11], off
	global_load_dword v31, v[10:11], off offset:1024
	global_load_dword v32, v[10:11], off offset:2048
	global_load_dword v33, v[10:11], off offset:3072
	v_lshl_add_u64 v[10:11], v[10:11], 0, s[22:23]
	global_load_dword v34, v[10:11], off
	global_load_dword v35, v[10:11], off offset:1024
	global_load_dword v36, v[10:11], off offset:2048
	global_load_dword v37, v[10:11], off offset:3072
	v_lshl_add_u64 v[10:11], v[10:11], 0, s[22:23]
	global_load_dword v38, v[10:11], off
	global_load_dword v39, v[10:11], off offset:1024
	global_load_dword v40, v[10:11], off offset:2048
	global_load_dword v41, v[10:11], off offset:3072
	v_lshl_add_u64 v[10:11], v[10:11], 0, s[22:23]
	global_load_dword v42, v[10:11], off
	global_load_dword v43, v[10:11], off offset:1024
	global_load_dword v44, v[10:11], off offset:2048
	global_load_dword v45, v[10:11], off offset:3072
	v_lshl_add_u64 v[10:11], v[10:11], 0, s[22:23]
	global_load_dword v46, v[10:11], off
	global_load_dword v47, v[10:11], off offset:1024
	global_load_dword v48, v[10:11], off offset:2048
	global_load_dword v49, v[10:11], off offset:3072
	v_lshl_add_u64 v[10:11], v[10:11], 0, s[22:23]
	global_load_dword v50, v[10:11], off
	global_load_dword v51, v[10:11], off offset:1024
	global_load_dword v52, v[10:11], off offset:2048
	global_load_dword v53, v[10:11], off offset:3072
	v_lshl_add_u64 v[10:11], v[10:11], 0, s[22:23]
	global_load_dword v54, v[10:11], off
	global_load_dword v55, v[10:11], off offset:1024
	global_load_dword v56, v[10:11], off offset:2048
	global_load_dword v57, v[10:11], off offset:3072
	v_lshl_add_u64 v[10:11], v[10:11], 0, s[22:23]
	global_load_dword v58, v[8:9], off
	global_load_dword v59, v[8:9], off offset:1024
	global_load_dword v60, v[8:9], off offset:2048
	global_load_dword v61, v[8:9], off offset:3072
	s_waitcnt vmcnt(33)
; __device__ __forceinline__ float siluf_(float x) { return x * __builtin_amdgcn_rcpf(1.f + __expf(-x)); }
; __device__ void ph_mod(const Params& p, char* smem) {
;     ...
;     for (int i = tid; i < 17 * D; i += 256) sl[0][i] = siluf_(i < 16 * D ? p.c[i] : p.c_ctx[i - 16 * D]);
	v_mul_f32_e32 v12, 0xbfb8aa3b, v28
	v_exp_f32_e32 v12, v12
	s_nop 0
	v_add_f32_e32 v12, 1.0, v12
	v_rcp_f32_e32 v12, v12
	s_nop 0
	v_mul_f32_e32 v28, v28, v12
	ds_write_b32 v27, v28 offset:34816
	s_waitcnt vmcnt(32)
	v_mul_f32_e32 v12, 0xbfb8aa3b, v29
	v_exp_f32_e32 v12, v12
	s_nop 0
	v_add_f32_e32 v12, 1.0, v12
	v_rcp_f32_e32 v12, v12
	s_nop 0
	v_mul_f32_e32 v29, v29, v12
	ds_write_b32 v27, v29 offset:35840
	s_waitcnt vmcnt(31)
	v_mul_f32_e32 v12, 0xbfb8aa3b, v30
	v_exp_f32_e32 v12, v12
	s_nop 0
	v_add_f32_e32 v12, 1.0, v12
	v_rcp_f32_e32 v12, v12
	s_nop 0
	v_mul_f32_e32 v30, v30, v12
	ds_write_b32 v27, v30 offset:36864
	s_waitcnt vmcnt(30)
	v_mul_f32_e32 v12, 0xbfb8aa3b, v31
	v_exp_f32_e32 v12, v12
	s_nop 0
	v_add_f32_e32 v12, 1.0, v12
	v_rcp_f32_e32 v12, v12
	s_nop 0
	v_mul_f32_e32 v31, v31, v12
	ds_write_b32 v27, v31 offset:37888
	s_waitcnt vmcnt(29)
	v_mul_f32_e32 v12, 0xbfb8aa3b, v32
	v_exp_f32_e32 v12, v12
	s_nop 0
	v_add_f32_e32 v12, 1.0, v12
	v_rcp_f32_e32 v12, v12
	s_nop 0
	v_mul_f32_e32 v32, v32, v12
	ds_write_b32 v27, v32 offset:38912
	s_waitcnt vmcnt(28)
	v_mul_f32_e32 v12, 0xbfb8aa3b, v33
	v_exp_f32_e32 v12, v12
	s_nop 0
	v_add_f32_e32 v12, 1.0, v12
	v_rcp_f32_e32 v12, v12
	s_nop 0
	v_mul_f32_e32 v33, v33, v12
	ds_write_b32 v27, v33 offset:39936
	s_waitcnt vmcnt(27)
	v_mul_f32_e32 v12, 0xbfb8aa3b, v34
	v_exp_f32_e32 v12, v12
	s_nop 0
	v_add_f32_e32 v12, 1.0, v12
	v_rcp_f32_e32 v12, v12
	s_nop 0
	v_mul_f32_e32 v34, v34, v12
	ds_write_b32 v27, v34 offset:40960
	s_waitcnt vmcnt(26)
	v_mul_f32_e32 v12, 0xbfb8aa3b, v35
	v_exp_f32_e32 v12, v12
	s_nop 0
	v_add_f32_e32 v12, 1.0, v12
	v_rcp_f32_e32 v12, v12
	s_nop 0
	v_mul_f32_e32 v35, v35, v12
	ds_write_b32 v27, v35 offset:41984
	s_waitcnt vmcnt(25)
	v_mul_f32_e32 v12, 0xbfb8aa3b, v36
	v_exp_f32_e32 v12, v12
	s_nop 0
	v_add_f32_e32 v12, 1.0, v12
	v_rcp_f32_e32 v12, v12
	s_nop 0
	v_mul_f32_e32 v36, v36, v12
	ds_write_b32 v27, v36 offset:43008
	s_waitcnt vmcnt(24)
	v_mul_f32_e32 v12, 0xbfb8aa3b, v37
	v_exp_f32_e32 v12, v12
	s_nop 0
	v_add_f32_e32 v12, 1.0, v12
	v_rcp_f32_e32 v12, v12
	s_nop 0
	v_mul_f32_e32 v37, v37, v12
	ds_write_b32 v27, v37 offset:44032
	s_waitcnt vmcnt(23)
	v_mul_f32_e32 v12, 0xbfb8aa3b, v38
	v_exp_f32_e32 v12, v12
	s_nop 0
	v_add_f32_e32 v12, 1.0, v12
	v_rcp_f32_e32 v12, v12
	s_nop 0
	v_mul_f32_e32 v38, v38, v12
	ds_write_b32 v27, v38 offset:45056
	s_waitcnt vmcnt(22)
	v_mul_f32_e32 v12, 0xbfb8aa3b, v39
	v_exp_f32_e32 v12, v12
	s_nop 0
	v_add_f32_e32 v12, 1.0, v12
	v_rcp_f32_e32 v12, v12
	s_nop 0
	v_mul_f32_e32 v39, v39, v12
	ds_write_b32 v27, v39 offset:46080
	s_waitcnt vmcnt(21)
	v_mul_f32_e32 v12, 0xbfb8aa3b, v40
	v_exp_f32_e32 v12, v12
	s_nop 0
	v_add_f32_e32 v12, 1.0, v12
	v_rcp_f32_e32 v12, v12
	s_nop 0
	v_mul_f32_e32 v40, v40, v12
	ds_write_b32 v27, v40 offset:47104
	s_waitcnt vmcnt(20)
	v_mul_f32_e32 v12, 0xbfb8aa3b, v41
	v_exp_f32_e32 v12, v12
	s_nop 0
	v_add_f32_e32 v12, 1.0, v12
	v_rcp_f32_e32 v12, v12
	s_nop 0
	v_mul_f32_e32 v41, v41, v12
	ds_write_b32 v27, v41 offset:48128
	s_waitcnt vmcnt(19)
	v_mul_f32_e32 v12, 0xbfb8aa3b, v42
	v_exp_f32_e32 v12, v12
	s_nop 0
	v_add_f32_e32 v12, 1.0, v12
	v_rcp_f32_e32 v12, v12
	s_nop 0
	v_mul_f32_e32 v42, v42, v12
	ds_write_b32 v27, v42 offset:49152
	s_waitcnt vmcnt(18)
	v_mul_f32_e32 v12, 0xbfb8aa3b, v43
	v_exp_f32_e32 v12, v12
	s_nop 0
	v_add_f32_e32 v12, 1.0, v12
	v_rcp_f32_e32 v12, v12
	s_nop 0
	v_mul_f32_e32 v43, v43, v12
	ds_write_b32 v27, v43 offset:50176
	s_waitcnt vmcnt(17)
	v_mul_f32_e32 v12, 0xbfb8aa3b, v44
	v_exp_f32_e32 v12, v12
	s_nop 0
	v_add_f32_e32 v12, 1.0, v12
	v_rcp_f32_e32 v12, v12
	s_nop 0
	v_mul_f32_e32 v44, v44, v12
	ds_write_b32 v27, v44 offset:51200
	s_waitcnt vmcnt(16)
	v_mul_f32_e32 v12, 0xbfb8aa3b, v45
	v_exp_f32_e32 v12, v12
	s_nop 0
	v_add_f32_e32 v12, 1.0, v12
	v_rcp_f32_e32 v12, v12
	s_nop 0
	v_mul_f32_e32 v45, v45, v12
	ds_write_b32 v27, v45 offset:52224
	s_waitcnt vmcnt(15)
	v_mul_f32_e32 v12, 0xbfb8aa3b, v46
	v_exp_f32_e32 v12, v12
	s_nop 0
	v_add_f32_e32 v12, 1.0, v12
	v_rcp_f32_e32 v12, v12
	s_nop 0
	v_mul_f32_e32 v46, v46, v12
	ds_write_b32 v27, v46 offset:53248
	s_waitcnt vmcnt(14)
	v_mul_f32_e32 v12, 0xbfb8aa3b, v47
	v_exp_f32_e32 v12, v12
	s_nop 0
	v_add_f32_e32 v12, 1.0, v12
	v_rcp_f32_e32 v12, v12
	s_nop 0
	v_mul_f32_e32 v47, v47, v12
	ds_write_b32 v27, v47 offset:54272
	s_waitcnt vmcnt(13)
	v_mul_f32_e32 v12, 0xbfb8aa3b, v48
	v_exp_f32_e32 v12, v12
	s_nop 0
	v_add_f32_e32 v12, 1.0, v12
	v_rcp_f32_e32 v12, v12
	s_nop 0
	v_mul_f32_e32 v48, v48, v12
	ds_write_b32 v27, v48 offset:55296
	s_waitcnt vmcnt(12)
	v_mul_f32_e32 v12, 0xbfb8aa3b, v49
	v_exp_f32_e32 v12, v12
	s_nop 0
	v_add_f32_e32 v12, 1.0, v12
	v_rcp_f32_e32 v12, v12
	s_nop 0
	v_mul_f32_e32 v49, v49, v12
	ds_write_b32 v27, v49 offset:56320
	s_waitcnt vmcnt(11)
	v_mul_f32_e32 v12, 0xbfb8aa3b, v50
	v_exp_f32_e32 v12, v12
	s_nop 0
	v_add_f32_e32 v12, 1.0, v12
	v_rcp_f32_e32 v12, v12
	s_nop 0
	v_mul_f32_e32 v50, v50, v12
	ds_write_b32 v27, v50 offset:57344
	s_waitcnt vmcnt(10)
	v_mul_f32_e32 v12, 0xbfb8aa3b, v51
	v_exp_f32_e32 v12, v12
	s_nop 0
	v_add_f32_e32 v12, 1.0, v12
	v_rcp_f32_e32 v12, v12
	s_nop 0
	v_mul_f32_e32 v51, v51, v12
	ds_write_b32 v27, v51 offset:58368
	s_waitcnt vmcnt(9)
	v_mul_f32_e32 v12, 0xbfb8aa3b, v52
	v_exp_f32_e32 v12, v12
	s_nop 0
	v_add_f32_e32 v12, 1.0, v12
	v_rcp_f32_e32 v12, v12
	s_nop 0
	v_mul_f32_e32 v52, v52, v12
	ds_write_b32 v27, v52 offset:59392
	s_waitcnt vmcnt(8)
	v_mul_f32_e32 v12, 0xbfb8aa3b, v53
	v_exp_f32_e32 v12, v12
	s_nop 0
	v_add_f32_e32 v12, 1.0, v12
	v_rcp_f32_e32 v12, v12
	s_nop 0
	v_mul_f32_e32 v53, v53, v12
	ds_write_b32 v27, v53 offset:60416
	s_waitcnt vmcnt(7)
; __device__ __forceinline__ float siluf_(float x) { return x * __builtin_amdgcn_rcpf(1.f + __expf(-x)); }
; __device__ void ph_mod(const Params& p, char* smem) {
;     ...
;     for (int i = tid; i < 17 * D; i += 256) sl[0][i] = siluf_(i < 16 * D ? p.c[i] : p.c_ctx[i - 16 * D]);
;     __syncthreads();
;     int l = u / 48, col = (u % 48) * 64 + cc;
;     float acc[17];
; #pragma unroll
;     for (int r = 0; r < 17; ++r) acc[r] = 0.f;
;     const float* w = p.ada_w + (long)l * D * 3072 + col;
; #pragma unroll 4
;     for (int k = kq * 256; k < kq * 256 + 256; ++k) {
;       float wv = w[(long)k * 3072];
; #pragma unroll
;       for (int r = 0; r < 17; ++r) acc[r] += sl[r][k] * wv;
	v_mul_f32_e32 v12, 0xbfb8aa3b, v54
	v_exp_f32_e32 v12, v12
	s_nop 0
	v_add_f32_e32 v12, 1.0, v12
	v_rcp_f32_e32 v12, v12
	s_nop 0
	v_mul_f32_e32 v54, v54, v12
	ds_write_b32 v27, v54 offset:61440
	s_waitcnt vmcnt(6)
	v_mul_f32_e32 v12, 0xbfb8aa3b, v55
	v_exp_f32_e32 v12, v12
	s_nop 0
	v_add_f32_e32 v12, 1.0, v12
	v_rcp_f32_e32 v12, v12
	s_nop 0
	v_mul_f32_e32 v55, v55, v12
	ds_write_b32 v27, v55 offset:62464
	s_waitcnt vmcnt(5)
	v_mul_f32_e32 v12, 0xbfb8aa3b, v56
	v_exp_f32_e32 v12, v12
	s_nop 0
	v_add_f32_e32 v12, 1.0, v12
	v_rcp_f32_e32 v12, v12
	s_nop 0
	v_mul_f32_e32 v56, v56, v12
	ds_write_b32 v27, v56 offset:63488
	s_waitcnt vmcnt(4)
	v_mul_f32_e32 v12, 0xbfb8aa3b, v57
	v_exp_f32_e32 v12, v12
	s_nop 0
	v_add_f32_e32 v12, 1.0, v12
	v_rcp_f32_e32 v12, v12
	s_nop 0
	v_mul_f32_e32 v57, v57, v12
	ds_write_b32 v27, v57 offset:64512
	s_waitcnt vmcnt(3)
	v_mul_f32_e32 v12, 0xbfb8aa3b, v58
	v_exp_f32_e32 v12, v12
	s_nop 0
	v_add_f32_e32 v12, 1.0, v12
	v_rcp_f32_e32 v12, v12
	s_nop 0
	v_mul_f32_e32 v58, v58, v12
	ds_write_b32 v6, v58
	s_waitcnt vmcnt(2)
	v_mul_f32_e32 v12, 0xbfb8aa3b, v59
	v_exp_f32_e32 v12, v12
	s_nop 0
	v_add_f32_e32 v12, 1.0, v12
	v_rcp_f32_e32 v12, v12
	s_nop 0
	v_mul_f32_e32 v59, v59, v12
	ds_write_b32 v6, v59 offset:1024
	s_waitcnt vmcnt(1)
	v_mul_f32_e32 v12, 0xbfb8aa3b, v60
	v_exp_f32_e32 v12, v12
	s_nop 0
	v_add_f32_e32 v12, 1.0, v12
	v_rcp_f32_e32 v12, v12
	s_nop 0
	v_mul_f32_e32 v60, v60, v12
	ds_write_b32 v6, v60 offset:2048
	s_waitcnt vmcnt(0)
	v_mul_f32_e32 v12, 0xbfb8aa3b, v61
	v_exp_f32_e32 v12, v12
	s_nop 0
	v_add_f32_e32 v12, 1.0, v12
	v_rcp_f32_e32 v12, v12
	s_nop 0
	v_mul_f32_e32 v61, v61, v12
	ds_write_b32 v6, v61 offset:3072
.LBB0_16:
	s_or_b64 exec, exec, s[20:21]
	s_mul_hi_i32 s6, s38, 0x2aaaaaab
	s_lshr_b32 s7, s6, 31
	s_ashr_i32 s6, s6, 3
	s_add_i32 s22, s6, s7
	s_mul_i32 s6, s22, 48
	s_sub_i32 s6, s38, s6
	s_lshl_b32 s39, s6, 6
	s_mul_i32 s6, s22, 0xc00000
	v_or_b32_e32 v8, s39, v1
	s_mul_hi_i32 s7, s22, 0xc00000
	s_add_u32 s6, s28, s6
	v_ashrrev_i32_e32 v9, 31, v8
	s_addc_u32 s7, s29, s7
	v_mov_b32_e32 v3, 0
	v_lshl_add_u64 v[8:9], v[8:9], 2, s[6:7]
	s_mov_b32 s20, 0
	v_mov_b32_e32 v10, 0
	v_mov_b32_e32 v11, v3
	v_mov_b32_e32 v12, 0
	v_mov_b32_e32 v13, v3
	v_mov_b32_e32 v14, 0
	v_mov_b32_e32 v15, v3
	v_mov_b32_e32 v16, 0
	v_mov_b32_e32 v17, v3
	v_mov_b32_e32 v18, 0
	v_mov_b32_e32 v19, v3
	v_mov_b32_e32 v20, 0
	v_mov_b32_e32 v21, v3
	v_mov_b32_e32 v22, 0
	v_mov_b32_e32 v23, v3
	v_mov_b32_e32 v24, 0
	v_mov_b32_e32 v25, v3
	global_load_dword v6, v[8:9], off
	v_lshl_add_u64 v[8:9], v[8:9], 0, s[18:19]
	global_load_dword v96, v[8:9], off
	v_lshl_add_u64 v[8:9], v[8:9], 0, s[18:19]
	global_load_dword v98, v[8:9], off
	v_lshl_add_u64 v[8:9], v[8:9], 0, s[18:19]
	global_load_dword v100, v[8:9], off
	v_lshl_add_u64 v[8:9], v[8:9], 0, s[18:19]
	global_load_dword v120, v[8:9], off
	v_lshl_add_u64 v[8:9], v[8:9], 0, s[18:19]
	global_load_dword v122, v[8:9], off
	v_lshl_add_u64 v[8:9], v[8:9], 0, s[18:19]
	global_load_dword v124, v[8:9], off
	v_lshl_add_u64 v[8:9], v[8:9], 0, s[18:19]
	global_load_dword v126, v[8:9], off
	v_lshl_add_u64 v[8:9], v[8:9], 0, s[18:19]
	global_load_dword v128, v[8:9], off
	v_lshl_add_u64 v[8:9], v[8:9], 0, s[18:19]
	global_load_dword v130, v[8:9], off
	v_lshl_add_u64 v[8:9], v[8:9], 0, s[18:19]
	global_load_dword v132, v[8:9], off
	v_lshl_add_u64 v[8:9], v[8:9], 0, s[18:19]
	global_load_dword v134, v[8:9], off
	v_lshl_add_u64 v[8:9], v[8:9], 0, s[18:19]
	global_load_dword v136, v[8:9], off
	v_lshl_add_u64 v[8:9], v[8:9], 0, s[18:19]
	global_load_dword v138, v[8:9], off
	v_lshl_add_u64 v[8:9], v[8:9], 0, s[18:19]
	global_load_dword v140, v[8:9], off
	v_lshl_add_u64 v[8:9], v[8:9], 0, s[18:19]
	global_load_dword v142, v[8:9], off
	v_lshl_add_u64 v[8:9], v[8:9], 0, s[18:19]
	s_waitcnt lgkmcnt(0)
	s_barrier
.LBB0_17:
	s_cmpk_eq_i32 s20, 0x3c0
	s_cselect_b32 s18, 0, 0x3000
	s_cselect_b32 s24, 0xffffd000, 0
	s_cselect_b32 s25, -1, 0
	s_nop 0
	v_lshl_add_u64 v[8:9], v[8:9], 0, s[24:25]
	s_add_i32 s21, s30, s20
	v_mov_b32_e32 v88, s21
	s_add_i32 s6, s21, 0x10000
	v_mov_b32_e32 v92, s6
	ds_read_b128 v[28:31], v88
	ds_read_b128 v[32:35], v88 offset:4096
	ds_read_b128 v[36:39], v88 offset:8192
	ds_read_b128 v[40:43], v88 offset:12288
	ds_read_b128 v[44:47], v88 offset:16384
	ds_read_b128 v[48:51], v88 offset:20480
	ds_read_b128 v[52:55], v88 offset:24576
	ds_read_b128 v[56:59], v88 offset:28672
	ds_read_b128 v[60:63], v88 offset:32768
	ds_read_b128 v[64:67], v88 offset:36864
	ds_read_b128 v[68:71], v88 offset:40960
	ds_read_b128 v[72:75], v88 offset:45056
	ds_read_b128 v[76:79], v88 offset:49152
	ds_read_b128 v[80:83], v88 offset:53248
	ds_read_b128 v[84:87], v88 offset:57344
	ds_read_b128 v[88:91], v88 offset:61440
	ds_read_b128 v[92:95], v92
	s_waitcnt lgkmcnt(14)
	v_mov_b32_e32 v102, v36
	v_mov_b32_e32 v103, v32
	s_waitcnt lgkmcnt(12)
	v_mov_b32_e32 v104, v44
	v_mov_b32_e32 v105, v40
	s_waitcnt lgkmcnt(10)
	v_mov_b32_e32 v106, v52
	v_mov_b32_e32 v107, v48
	s_waitcnt lgkmcnt(8)
	v_mov_b32_e32 v108, v60
	v_mov_b32_e32 v109, v56
	s_waitcnt lgkmcnt(6)
	v_mov_b32_e32 v110, v68
	v_mov_b32_e32 v111, v64
	s_waitcnt lgkmcnt(4)
	v_mov_b32_e32 v112, v76
	v_mov_b32_e32 v113, v72
	s_waitcnt lgkmcnt(2)
	v_mov_b32_e32 v114, v84
	v_mov_b32_e32 v115, v80
	s_waitcnt lgkmcnt(1)
	v_mov_b32_e32 v117, v88
	s_waitcnt lgkmcnt(0)
; __device__ void ph_mod(const Params& p, char* smem) {
;     ...
;     for (int k = kq * 256; k < kq * 256 + 256; ++k) {
;       float wv = w[(long)k * 3072];
; #pragma unroll
;       for (int r = 0; r < 17; ++r) acc[r] += sl[r][k] * wv;
	v_mov_b32_e32 v116, v92
	v_mov_b32_e32 v32, v37
	v_mov_b32_e32 v40, v45
	v_mov_b32_e32 v48, v53
	v_mov_b32_e32 v56, v61
	v_mov_b32_e32 v64, v69
	v_mov_b32_e32 v72, v77
	v_mov_b32_e32 v80, v85
	v_mov_b32_e32 v88, v93
	v_mov_b32_e32 v36, v38
	v_mov_b32_e32 v37, v34
	v_mov_b32_e32 v44, v46
	v_mov_b32_e32 v45, v42
	v_mov_b32_e32 v52, v54
	v_mov_b32_e32 v53, v50
	v_mov_b32_e32 v60, v62
	v_mov_b32_e32 v61, v58
	v_mov_b32_e32 v68, v70
	v_mov_b32_e32 v69, v66
	v_mov_b32_e32 v76, v78
	v_mov_b32_e32 v77, v74
	v_mov_b32_e32 v84, v86
	v_mov_b32_e32 v85, v82
	v_mov_b32_e32 v119, v90
	v_mov_b32_e32 v118, v94
	s_add_i32 s20, s20, 16
	v_mov_b32_e32 v34, v39
	v_mov_b32_e32 v42, v47
	v_mov_b32_e32 v50, v55
	v_mov_b32_e32 v58, v63
	v_mov_b32_e32 v66, v71
	v_mov_b32_e32 v74, v79
	v_mov_b32_e32 v82, v87
	v_mov_b32_e32 v90, v95
	s_waitcnt vmcnt(15)
	v_fmac_f32_e32 v3, v6, v28
	v_pk_fma_f32 v[24:25], v[6:7], v[102:103], v[24:25] op_sel_hi:[0,1,1]
	v_pk_fma_f32 v[22:23], v[6:7], v[104:105], v[22:23] op_sel_hi:[0,1,1]
	v_pk_fma_f32 v[20:21], v[6:7], v[106:107], v[20:21] op_sel_hi:[0,1,1]
	v_pk_fma_f32 v[18:19], v[6:7], v[108:109], v[18:19] op_sel_hi:[0,1,1]
	v_pk_fma_f32 v[16:17], v[6:7], v[110:111], v[16:17] op_sel_hi:[0,1,1]
	v_pk_fma_f32 v[14:15], v[6:7], v[112:113], v[14:15] op_sel_hi:[0,1,1]
	v_pk_fma_f32 v[12:13], v[6:7], v[114:115], v[12:13] op_sel_hi:[0,1,1]
	v_pk_fma_f32 v[10:11], v[6:7], v[116:117], v[10:11] op_sel_hi:[0,1,1]
	s_waitcnt vmcnt(14)
	v_fmac_f32_e32 v3, v96, v29
	v_pk_fma_f32 v[24:25], v[96:97], v[32:33], v[24:25] op_sel_hi:[0,1,1]
	v_pk_fma_f32 v[22:23], v[96:97], v[40:41], v[22:23] op_sel_hi:[0,1,1]
	v_pk_fma_f32 v[20:21], v[96:97], v[48:49], v[20:21] op_sel_hi:[0,1,1]
	v_pk_fma_f32 v[18:19], v[96:97], v[56:57], v[18:19] op_sel_hi:[0,1,1]
	v_pk_fma_f32 v[16:17], v[96:97], v[64:65], v[16:17] op_sel_hi:[0,1,1]
	v_pk_fma_f32 v[14:15], v[96:97], v[72:73], v[14:15] op_sel_hi:[0,1,1]
	v_pk_fma_f32 v[12:13], v[96:97], v[80:81], v[12:13] op_sel_hi:[0,1,1]
	v_pk_fma_f32 v[10:11], v[96:97], v[88:89], v[10:11] op_sel_hi:[0,1,1]
	s_waitcnt vmcnt(13)
	v_fmac_f32_e32 v3, v98, v30
	v_pk_fma_f32 v[24:25], v[98:99], v[36:37], v[24:25] op_sel_hi:[0,1,1]
	v_pk_fma_f32 v[22:23], v[98:99], v[44:45], v[22:23] op_sel_hi:[0,1,1]
	v_pk_fma_f32 v[20:21], v[98:99], v[52:53], v[20:21] op_sel_hi:[0,1,1]
	v_pk_fma_f32 v[18:19], v[98:99], v[60:61], v[18:19] op_sel_hi:[0,1,1]
	v_pk_fma_f32 v[16:17], v[98:99], v[68:69], v[16:17] op_sel_hi:[0,1,1]
	v_pk_fma_f32 v[14:15], v[98:99], v[76:77], v[14:15] op_sel_hi:[0,1,1]
	v_pk_fma_f32 v[12:13], v[98:99], v[84:85], v[12:13] op_sel_hi:[0,1,1]
	v_pk_fma_f32 v[10:11], v[98:99], v[118:119], v[10:11] op_sel_hi:[0,1,1]
	s_waitcnt vmcnt(12)
	v_fmac_f32_e32 v3, v100, v31
	v_pk_fma_f32 v[24:25], v[100:101], v[34:35], v[24:25] op_sel_hi:[0,1,1]
	v_pk_fma_f32 v[22:23], v[100:101], v[42:43], v[22:23] op_sel_hi:[0,1,1]
	v_pk_fma_f32 v[20:21], v[100:101], v[50:51], v[20:21] op_sel_hi:[0,1,1]
	v_pk_fma_f32 v[18:19], v[100:101], v[58:59], v[18:19] op_sel_hi:[0,1,1]
	v_pk_fma_f32 v[16:17], v[100:101], v[66:67], v[16:17] op_sel_hi:[0,1,1]
	v_pk_fma_f32 v[14:15], v[100:101], v[74:75], v[14:15] op_sel_hi:[0,1,1]
	v_pk_fma_f32 v[12:13], v[100:101], v[82:83], v[12:13] op_sel_hi:[0,1,1]
	v_pk_fma_f32 v[10:11], v[100:101], v[90:91], v[10:11] op_sel_hi:[0,1,1]
	global_load_dword v6, v[8:9], off
	v_lshl_add_u64 v[8:9], v[8:9], 0, s[18:19]
	global_load_dword v96, v[8:9], off
	v_lshl_add_u64 v[8:9], v[8:9], 0, s[18:19]
	global_load_dword v98, v[8:9], off
	v_lshl_add_u64 v[8:9], v[8:9], 0, s[18:19]
	global_load_dword v100, v[8:9], off
	v_lshl_add_u64 v[8:9], v[8:9], 0, s[18:19]
	s_add_i32 s21, s30, s20
	v_mov_b32_e32 v88, s21
	s_add_i32 s6, s21, 0x10000
	v_mov_b32_e32 v92, s6
	ds_read_b128 v[28:31], v88
	ds_read_b128 v[32:35], v88 offset:4096
	ds_read_b128 v[36:39], v88 offset:8192
	ds_read_b128 v[40:43], v88 offset:12288
	ds_read_b128 v[44:47], v88 offset:16384
	ds_read_b128 v[48:51], v88 offset:20480
	ds_read_b128 v[52:55], v88 offset:24576
	ds_read_b128 v[56:59], v88 offset:28672
	ds_read_b128 v[60:63], v88 offset:32768
	ds_read_b128 v[64:67], v88 offset:36864
	ds_read_b128 v[68:71], v88 offset:40960
	ds_read_b128 v[72:75], v88 offset:45056
	ds_read_b128 v[76:79], v88 offset:49152
	ds_read_b128 v[80:83], v88 offset:53248
	ds_read_b128 v[84:87], v88 offset:57344
	ds_read_b128 v[88:91], v88 offset:61440
	ds_read_b128 v[92:95], v92
	s_waitcnt lgkmcnt(14)
	v_mov_b32_e32 v102, v36
	v_mov_b32_e32 v103, v32
	s_waitcnt lgkmcnt(12)
	v_mov_b32_e32 v104, v44
	v_mov_b32_e32 v105, v40
	s_waitcnt lgkmcnt(10)
	v_mov_b32_e32 v106, v52
	v_mov_b32_e32 v107, v48
	s_waitcnt lgkmcnt(8)
	v_mov_b32_e32 v108, v60
	v_mov_b32_e32 v109, v56
	s_waitcnt lgkmcnt(6)
	v_mov_b32_e32 v110, v68
	v_mov_b32_e32 v111, v64
	s_waitcnt lgkmcnt(4)
	v_mov_b32_e32 v112, v76
	v_mov_b32_e32 v113, v72
	s_waitcnt lgkmcnt(2)
	v_mov_b32_e32 v114, v84
	v_mov_b32_e32 v115, v80
	s_waitcnt lgkmcnt(1)
	v_mov_b32_e32 v117, v88
	s_waitcnt lgkmcnt(0)
	v_mov_b32_e32 v116, v92
	v_mov_b32_e32 v32, v37
	v_mov_b32_e32 v40, v45
	v_mov_b32_e32 v48, v53
	v_mov_b32_e32 v56, v61
	v_mov_b32_e32 v64, v69
	v_mov_b32_e32 v72, v77
	v_mov_b32_e32 v80, v85
	v_mov_b32_e32 v88, v93
	v_mov_b32_e32 v36, v38
	v_mov_b32_e32 v37, v34
	v_mov_b32_e32 v44, v46
	v_mov_b32_e32 v45, v42
	v_mov_b32_e32 v52, v54
	v_mov_b32_e32 v53, v50
	v_mov_b32_e32 v60, v62
	v_mov_b32_e32 v61, v58
	v_mov_b32_e32 v68, v70
	v_mov_b32_e32 v69, v66
	v_mov_b32_e32 v76, v78
	v_mov_b32_e32 v77, v74
	v_mov_b32_e32 v84, v86
	v_mov_b32_e32 v85, v82
	v_mov_b32_e32 v119, v90
	v_mov_b32_e32 v118, v94
	s_add_i32 s20, s20, 16
	v_mov_b32_e32 v34, v39
	v_mov_b32_e32 v42, v47
	v_mov_b32_e32 v50, v55
	v_mov_b32_e32 v58, v63
	v_mov_b32_e32 v66, v71
	v_mov_b32_e32 v74, v79
	v_mov_b32_e32 v82, v87
	v_mov_b32_e32 v90, v95
	s_waitcnt vmcnt(15)
; __device__ void ph_mod(const Params& p, char* smem) {
;     ...
;     for (int k = kq * 256; k < kq * 256 + 256; ++k) {
;       float wv = w[(long)k * 3072];
; #pragma unroll
;       for (int r = 0; r < 17; ++r) acc[r] += sl[r][k] * wv;
	v_fmac_f32_e32 v3, v120, v28
	v_pk_fma_f32 v[24:25], v[120:121], v[102:103], v[24:25] op_sel_hi:[0,1,1]
	v_pk_fma_f32 v[22:23], v[120:121], v[104:105], v[22:23] op_sel_hi:[0,1,1]
	v_pk_fma_f32 v[20:21], v[120:121], v[106:107], v[20:21] op_sel_hi:[0,1,1]
	v_pk_fma_f32 v[18:19], v[120:121], v[108:109], v[18:19] op_sel_hi:[0,1,1]
	v_pk_fma_f32 v[16:17], v[120:121], v[110:111], v[16:17] op_sel_hi:[0,1,1]
	v_pk_fma_f32 v[14:15], v[120:121], v[112:113], v[14:15] op_sel_hi:[0,1,1]
	v_pk_fma_f32 v[12:13], v[120:121], v[114:115], v[12:13] op_sel_hi:[0,1,1]
	v_pk_fma_f32 v[10:11], v[120:121], v[116:117], v[10:11] op_sel_hi:[0,1,1]
	s_waitcnt vmcnt(14)
	v_fmac_f32_e32 v3, v122, v29
	v_pk_fma_f32 v[24:25], v[122:123], v[32:33], v[24:25] op_sel_hi:[0,1,1]
	v_pk_fma_f32 v[22:23], v[122:123], v[40:41], v[22:23] op_sel_hi:[0,1,1]
	v_pk_fma_f32 v[20:21], v[122:123], v[48:49], v[20:21] op_sel_hi:[0,1,1]
	v_pk_fma_f32 v[18:19], v[122:123], v[56:57], v[18:19] op_sel_hi:[0,1,1]
	v_pk_fma_f32 v[16:17], v[122:123], v[64:65], v[16:17] op_sel_hi:[0,1,1]
	v_pk_fma_f32 v[14:15], v[122:123], v[72:73], v[14:15] op_sel_hi:[0,1,1]
	v_pk_fma_f32 v[12:13], v[122:123], v[80:81], v[12:13] op_sel_hi:[0,1,1]
	v_pk_fma_f32 v[10:11], v[122:123], v[88:89], v[10:11] op_sel_hi:[0,1,1]
	s_waitcnt vmcnt(13)
	v_fmac_f32_e32 v3, v124, v30
	v_pk_fma_f32 v[24:25], v[124:125], v[36:37], v[24:25] op_sel_hi:[0,1,1]
	v_pk_fma_f32 v[22:23], v[124:125], v[44:45], v[22:23] op_sel_hi:[0,1,1]
	v_pk_fma_f32 v[20:21], v[124:125], v[52:53], v[20:21] op_sel_hi:[0,1,1]
	v_pk_fma_f32 v[18:19], v[124:125], v[60:61], v[18:19] op_sel_hi:[0,1,1]
	v_pk_fma_f32 v[16:17], v[124:125], v[68:69], v[16:17] op_sel_hi:[0,1,1]
	v_pk_fma_f32 v[14:15], v[124:125], v[76:77], v[14:15] op_sel_hi:[0,1,1]
	v_pk_fma_f32 v[12:13], v[124:125], v[84:85], v[12:13] op_sel_hi:[0,1,1]
	v_pk_fma_f32 v[10:11], v[124:125], v[118:119], v[10:11] op_sel_hi:[0,1,1]
	s_waitcnt vmcnt(12)
	v_fmac_f32_e32 v3, v126, v31
	v_pk_fma_f32 v[24:25], v[126:127], v[34:35], v[24:25] op_sel_hi:[0,1,1]
	v_pk_fma_f32 v[22:23], v[126:127], v[42:43], v[22:23] op_sel_hi:[0,1,1]
	v_pk_fma_f32 v[20:21], v[126:127], v[50:51], v[20:21] op_sel_hi:[0,1,1]
	v_pk_fma_f32 v[18:19], v[126:127], v[58:59], v[18:19] op_sel_hi:[0,1,1]
	v_pk_fma_f32 v[16:17], v[126:127], v[66:67], v[16:17] op_sel_hi:[0,1,1]
	v_pk_fma_f32 v[14:15], v[126:127], v[74:75], v[14:15] op_sel_hi:[0,1,1]
	v_pk_fma_f32 v[12:13], v[126:127], v[82:83], v[12:13] op_sel_hi:[0,1,1]
	v_pk_fma_f32 v[10:11], v[126:127], v[90:91], v[10:11] op_sel_hi:[0,1,1]
	global_load_dword v120, v[8:9], off
	v_lshl_add_u64 v[8:9], v[8:9], 0, s[18:19]
	global_load_dword v122, v[8:9], off
	v_lshl_add_u64 v[8:9], v[8:9], 0, s[18:19]
	global_load_dword v124, v[8:9], off
	v_lshl_add_u64 v[8:9], v[8:9], 0, s[18:19]
	global_load_dword v126, v[8:9], off
	v_lshl_add_u64 v[8:9], v[8:9], 0, s[18:19]
	s_add_i32 s21, s30, s20
	v_mov_b32_e32 v88, s21
	s_add_i32 s6, s21, 0x10000
	v_mov_b32_e32 v92, s6
	ds_read_b128 v[28:31], v88
	ds_read_b128 v[32:35], v88 offset:4096
	ds_read_b128 v[36:39], v88 offset:8192
	ds_read_b128 v[40:43], v88 offset:12288
	ds_read_b128 v[44:47], v88 offset:16384
	ds_read_b128 v[48:51], v88 offset:20480
	ds_read_b128 v[52:55], v88 offset:24576
	ds_read_b128 v[56:59], v88 offset:28672
	ds_read_b128 v[60:63], v88 offset:32768
	ds_read_b128 v[64:67], v88 offset:36864
	ds_read_b128 v[68:71], v88 offset:40960
	ds_read_b128 v[72:75], v88 offset:45056
	ds_read_b128 v[76:79], v88 offset:49152
	ds_read_b128 v[80:83], v88 offset:53248
	ds_read_b128 v[84:87], v88 offset:57344
	ds_read_b128 v[88:91], v88 offset:61440
	ds_read_b128 v[92:95], v92
	s_waitcnt lgkmcnt(14)
	v_mov_b32_e32 v102, v36
	v_mov_b32_e32 v103, v32
	s_waitcnt lgkmcnt(12)
	v_mov_b32_e32 v104, v44
	v_mov_b32_e32 v105, v40
	s_waitcnt lgkmcnt(10)
	v_mov_b32_e32 v106, v52
	v_mov_b32_e32 v107, v48
	s_waitcnt lgkmcnt(8)
	v_mov_b32_e32 v108, v60
	v_mov_b32_e32 v109, v56
	s_waitcnt lgkmcnt(6)
	v_mov_b32_e32 v110, v68
	v_mov_b32_e32 v111, v64
	s_waitcnt lgkmcnt(4)
	v_mov_b32_e32 v112, v76
	v_mov_b32_e32 v113, v72
	s_waitcnt lgkmcnt(2)
	v_mov_b32_e32 v114, v84
	v_mov_b32_e32 v115, v80
	s_waitcnt lgkmcnt(1)
	v_mov_b32_e32 v117, v88
	s_waitcnt lgkmcnt(0)
	v_mov_b32_e32 v116, v92
	v_mov_b32_e32 v32, v37
	v_mov_b32_e32 v40, v45
	v_mov_b32_e32 v48, v53
	v_mov_b32_e32 v56, v61
	v_mov_b32_e32 v64, v69
	v_mov_b32_e32 v72, v77
	v_mov_b32_e32 v80, v85
	v_mov_b32_e32 v88, v93
	v_mov_b32_e32 v36, v38
	v_mov_b32_e32 v37, v34
	v_mov_b32_e32 v44, v46
	v_mov_b32_e32 v45, v42
	v_mov_b32_e32 v52, v54
	v_mov_b32_e32 v53, v50
	v_mov_b32_e32 v60, v62
	v_mov_b32_e32 v61, v58
	v_mov_b32_e32 v68, v70
	v_mov_b32_e32 v69, v66
	v_mov_b32_e32 v76, v78
	v_mov_b32_e32 v77, v74
	v_mov_b32_e32 v84, v86
	v_mov_b32_e32 v85, v82
	v_mov_b32_e32 v119, v90
	v_mov_b32_e32 v118, v94
	s_add_i32 s20, s20, 16
	v_mov_b32_e32 v34, v39
	v_mov_b32_e32 v42, v47
	v_mov_b32_e32 v50, v55
	v_mov_b32_e32 v58, v63
	v_mov_b32_e32 v66, v71
	v_mov_b32_e32 v74, v79
	v_mov_b32_e32 v82, v87
	v_mov_b32_e32 v90, v95
	s_waitcnt vmcnt(15)
	v_fmac_f32_e32 v3, v128, v28
	v_pk_fma_f32 v[24:25], v[128:129], v[102:103], v[24:25] op_sel_hi:[0,1,1]
	v_pk_fma_f32 v[22:23], v[128:129], v[104:105], v[22:23] op_sel_hi:[0,1,1]
	v_pk_fma_f32 v[20:21], v[128:129], v[106:107], v[20:21] op_sel_hi:[0,1,1]
	v_pk_fma_f32 v[18:19], v[128:129], v[108:109], v[18:19] op_sel_hi:[0,1,1]
	v_pk_fma_f32 v[16:17], v[128:129], v[110:111], v[16:17] op_sel_hi:[0,1,1]
	v_pk_fma_f32 v[14:15], v[128:129], v[112:113], v[14:15] op_sel_hi:[0,1,1]
	v_pk_fma_f32 v[12:13], v[128:129], v[114:115], v[12:13] op_sel_hi:[0,1,1]
	v_pk_fma_f32 v[10:11], v[128:129], v[116:117], v[10:11] op_sel_hi:[0,1,1]
	s_waitcnt vmcnt(14)
; __device__ void ph_mod(const Params& p, char* smem) {
;     ...
;     for (int k = kq * 256; k < kq * 256 + 256; ++k) {
;       float wv = w[(long)k * 3072];
; #pragma unroll
;       for (int r = 0; r < 17; ++r) acc[r] += sl[r][k] * wv;
	v_fmac_f32_e32 v3, v130, v29
	v_pk_fma_f32 v[24:25], v[130:131], v[32:33], v[24:25] op_sel_hi:[0,1,1]
	v_pk_fma_f32 v[22:23], v[130:131], v[40:41], v[22:23] op_sel_hi:[0,1,1]
	v_pk_fma_f32 v[20:21], v[130:131], v[48:49], v[20:21] op_sel_hi:[0,1,1]
	v_pk_fma_f32 v[18:19], v[130:131], v[56:57], v[18:19] op_sel_hi:[0,1,1]
	v_pk_fma_f32 v[16:17], v[130:131], v[64:65], v[16:17] op_sel_hi:[0,1,1]
	v_pk_fma_f32 v[14:15], v[130:131], v[72:73], v[14:15] op_sel_hi:[0,1,1]
	v_pk_fma_f32 v[12:13], v[130:131], v[80:81], v[12:13] op_sel_hi:[0,1,1]
	v_pk_fma_f32 v[10:11], v[130:131], v[88:89], v[10:11] op_sel_hi:[0,1,1]
	s_waitcnt vmcnt(13)
	v_fmac_f32_e32 v3, v132, v30
	v_pk_fma_f32 v[24:25], v[132:133], v[36:37], v[24:25] op_sel_hi:[0,1,1]
	v_pk_fma_f32 v[22:23], v[132:133], v[44:45], v[22:23] op_sel_hi:[0,1,1]
	v_pk_fma_f32 v[20:21], v[132:133], v[52:53], v[20:21] op_sel_hi:[0,1,1]
	v_pk_fma_f32 v[18:19], v[132:133], v[60:61], v[18:19] op_sel_hi:[0,1,1]
	v_pk_fma_f32 v[16:17], v[132:133], v[68:69], v[16:17] op_sel_hi:[0,1,1]
	v_pk_fma_f32 v[14:15], v[132:133], v[76:77], v[14:15] op_sel_hi:[0,1,1]
	v_pk_fma_f32 v[12:13], v[132:133], v[84:85], v[12:13] op_sel_hi:[0,1,1]
	v_pk_fma_f32 v[10:11], v[132:133], v[118:119], v[10:11] op_sel_hi:[0,1,1]
	s_waitcnt vmcnt(12)
	v_fmac_f32_e32 v3, v134, v31
	v_pk_fma_f32 v[24:25], v[134:135], v[34:35], v[24:25] op_sel_hi:[0,1,1]
	v_pk_fma_f32 v[22:23], v[134:135], v[42:43], v[22:23] op_sel_hi:[0,1,1]
	v_pk_fma_f32 v[20:21], v[134:135], v[50:51], v[20:21] op_sel_hi:[0,1,1]
	v_pk_fma_f32 v[18:19], v[134:135], v[58:59], v[18:19] op_sel_hi:[0,1,1]
	v_pk_fma_f32 v[16:17], v[134:135], v[66:67], v[16:17] op_sel_hi:[0,1,1]
	v_pk_fma_f32 v[14:15], v[134:135], v[74:75], v[14:15] op_sel_hi:[0,1,1]
	v_pk_fma_f32 v[12:13], v[134:135], v[82:83], v[12:13] op_sel_hi:[0,1,1]
	v_pk_fma_f32 v[10:11], v[134:135], v[90:91], v[10:11] op_sel_hi:[0,1,1]
	global_load_dword v128, v[8:9], off
	v_lshl_add_u64 v[8:9], v[8:9], 0, s[18:19]
	global_load_dword v130, v[8:9], off
	v_lshl_add_u64 v[8:9], v[8:9], 0, s[18:19]
	global_load_dword v132, v[8:9], off
	v_lshl_add_u64 v[8:9], v[8:9], 0, s[18:19]
	global_load_dword v134, v[8:9], off
	v_lshl_add_u64 v[8:9], v[8:9], 0, s[18:19]
	s_add_i32 s21, s30, s20
	v_mov_b32_e32 v88, s21
	s_add_i32 s6, s21, 0x10000
	v_mov_b32_e32 v92, s6
	ds_read_b128 v[28:31], v88
	ds_read_b128 v[32:35], v88 offset:4096
	ds_read_b128 v[36:39], v88 offset:8192
	ds_read_b128 v[40:43], v88 offset:12288
	ds_read_b128 v[44:47], v88 offset:16384
	ds_read_b128 v[48:51], v88 offset:20480
	ds_read_b128 v[52:55], v88 offset:24576
	ds_read_b128 v[56:59], v88 offset:28672
	ds_read_b128 v[60:63], v88 offset:32768
	ds_read_b128 v[64:67], v88 offset:36864
	ds_read_b128 v[68:71], v88 offset:40960
	ds_read_b128 v[72:75], v88 offset:45056
	ds_read_b128 v[76:79], v88 offset:49152
	ds_read_b128 v[80:83], v88 offset:53248
	ds_read_b128 v[84:87], v88 offset:57344
	ds_read_b128 v[88:91], v88 offset:61440
	ds_read_b128 v[92:95], v92
	s_waitcnt lgkmcnt(14)
	v_mov_b32_e32 v102, v36
	v_mov_b32_e32 v103, v32
	s_waitcnt lgkmcnt(12)
	v_mov_b32_e32 v104, v44
	v_mov_b32_e32 v105, v40
	s_waitcnt lgkmcnt(10)
	v_mov_b32_e32 v106, v52
	v_mov_b32_e32 v107, v48
	s_waitcnt lgkmcnt(8)
	v_mov_b32_e32 v108, v60
	v_mov_b32_e32 v109, v56
	s_waitcnt lgkmcnt(6)
	v_mov_b32_e32 v110, v68
	v_mov_b32_e32 v111, v64
	s_waitcnt lgkmcnt(4)
	v_mov_b32_e32 v112, v76
	v_mov_b32_e32 v113, v72
	s_waitcnt lgkmcnt(2)
	v_mov_b32_e32 v114, v84
	v_mov_b32_e32 v115, v80
	s_waitcnt lgkmcnt(1)
	v_mov_b32_e32 v117, v88
	s_waitcnt lgkmcnt(0)
	v_mov_b32_e32 v116, v92
	v_mov_b32_e32 v32, v37
	v_mov_b32_e32 v40, v45
	v_mov_b32_e32 v48, v53
	v_mov_b32_e32 v56, v61
	v_mov_b32_e32 v64, v69
	v_mov_b32_e32 v72, v77
	v_mov_b32_e32 v80, v85
	v_mov_b32_e32 v88, v93
	v_mov_b32_e32 v36, v38
	v_mov_b32_e32 v37, v34
	v_mov_b32_e32 v44, v46
	v_mov_b32_e32 v45, v42
	v_mov_b32_e32 v52, v54
	v_mov_b32_e32 v53, v50
	v_mov_b32_e32 v60, v62
	v_mov_b32_e32 v61, v58
	v_mov_b32_e32 v68, v70
	v_mov_b32_e32 v69, v66
	v_mov_b32_e32 v76, v78
	v_mov_b32_e32 v77, v74
	v_mov_b32_e32 v84, v86
	v_mov_b32_e32 v85, v82
	v_mov_b32_e32 v119, v90
	v_mov_b32_e32 v118, v94
	s_add_i32 s20, s20, 16
	v_mov_b32_e32 v34, v39
	v_mov_b32_e32 v42, v47
	v_mov_b32_e32 v50, v55
	v_mov_b32_e32 v58, v63
	v_mov_b32_e32 v66, v71
	v_mov_b32_e32 v74, v79
	v_mov_b32_e32 v82, v87
	v_mov_b32_e32 v90, v95
	s_waitcnt vmcnt(15)
; __device__ void ph_mod(const Params& p, char* smem) {
;     ...
;     for (int k = kq * 256; k < kq * 256 + 256; ++k) {
;       float wv = w[(long)k * 3072];
; #pragma unroll
;       for (int r = 0; r < 17; ++r) acc[r] += sl[r][k] * wv;
;     }
;     __syncthreads();
; #pragma unroll
;     for (int r = 0; r < 17; ++r) red[kq][r][cc] = acc[r];
;     __syncthreads();
;     for (int i = tid; i < 17 * 64; i += 256) {
	v_fmac_f32_e32 v3, v136, v28
	v_pk_fma_f32 v[24:25], v[136:137], v[102:103], v[24:25] op_sel_hi:[0,1,1]
	v_pk_fma_f32 v[22:23], v[136:137], v[104:105], v[22:23] op_sel_hi:[0,1,1]
	v_pk_fma_f32 v[20:21], v[136:137], v[106:107], v[20:21] op_sel_hi:[0,1,1]
	v_pk_fma_f32 v[18:19], v[136:137], v[108:109], v[18:19] op_sel_hi:[0,1,1]
	v_pk_fma_f32 v[16:17], v[136:137], v[110:111], v[16:17] op_sel_hi:[0,1,1]
	v_pk_fma_f32 v[14:15], v[136:137], v[112:113], v[14:15] op_sel_hi:[0,1,1]
	v_pk_fma_f32 v[12:13], v[136:137], v[114:115], v[12:13] op_sel_hi:[0,1,1]
	v_pk_fma_f32 v[10:11], v[136:137], v[116:117], v[10:11] op_sel_hi:[0,1,1]
	s_waitcnt vmcnt(14)
	v_fmac_f32_e32 v3, v138, v29
	v_pk_fma_f32 v[24:25], v[138:139], v[32:33], v[24:25] op_sel_hi:[0,1,1]
	v_pk_fma_f32 v[22:23], v[138:139], v[40:41], v[22:23] op_sel_hi:[0,1,1]
	v_pk_fma_f32 v[20:21], v[138:139], v[48:49], v[20:21] op_sel_hi:[0,1,1]
	v_pk_fma_f32 v[18:19], v[138:139], v[56:57], v[18:19] op_sel_hi:[0,1,1]
	v_pk_fma_f32 v[16:17], v[138:139], v[64:65], v[16:17] op_sel_hi:[0,1,1]
	v_pk_fma_f32 v[14:15], v[138:139], v[72:73], v[14:15] op_sel_hi:[0,1,1]
	v_pk_fma_f32 v[12:13], v[138:139], v[80:81], v[12:13] op_sel_hi:[0,1,1]
	v_pk_fma_f32 v[10:11], v[138:139], v[88:89], v[10:11] op_sel_hi:[0,1,1]
	s_waitcnt vmcnt(13)
	v_fmac_f32_e32 v3, v140, v30
	v_pk_fma_f32 v[24:25], v[140:141], v[36:37], v[24:25] op_sel_hi:[0,1,1]
	v_pk_fma_f32 v[22:23], v[140:141], v[44:45], v[22:23] op_sel_hi:[0,1,1]
	v_pk_fma_f32 v[20:21], v[140:141], v[52:53], v[20:21] op_sel_hi:[0,1,1]
	v_pk_fma_f32 v[18:19], v[140:141], v[60:61], v[18:19] op_sel_hi:[0,1,1]
	v_pk_fma_f32 v[16:17], v[140:141], v[68:69], v[16:17] op_sel_hi:[0,1,1]
	v_pk_fma_f32 v[14:15], v[140:141], v[76:77], v[14:15] op_sel_hi:[0,1,1]
	v_pk_fma_f32 v[12:13], v[140:141], v[84:85], v[12:13] op_sel_hi:[0,1,1]
	v_pk_fma_f32 v[10:11], v[140:141], v[118:119], v[10:11] op_sel_hi:[0,1,1]
	s_waitcnt vmcnt(12)
	v_fmac_f32_e32 v3, v142, v31
	v_pk_fma_f32 v[24:25], v[142:143], v[34:35], v[24:25] op_sel_hi:[0,1,1]
	v_pk_fma_f32 v[22:23], v[142:143], v[42:43], v[22:23] op_sel_hi:[0,1,1]
	v_pk_fma_f32 v[20:21], v[142:143], v[50:51], v[20:21] op_sel_hi:[0,1,1]
	v_pk_fma_f32 v[18:19], v[142:143], v[58:59], v[18:19] op_sel_hi:[0,1,1]
	v_pk_fma_f32 v[16:17], v[142:143], v[66:67], v[16:17] op_sel_hi:[0,1,1]
	v_pk_fma_f32 v[14:15], v[142:143], v[74:75], v[14:15] op_sel_hi:[0,1,1]
	v_pk_fma_f32 v[12:13], v[142:143], v[82:83], v[12:13] op_sel_hi:[0,1,1]
	v_pk_fma_f32 v[10:11], v[142:143], v[90:91], v[10:11] op_sel_hi:[0,1,1]
	global_load_dword v136, v[8:9], off
	v_lshl_add_u64 v[8:9], v[8:9], 0, s[18:19]
	global_load_dword v138, v[8:9], off
	v_lshl_add_u64 v[8:9], v[8:9], 0, s[18:19]
	global_load_dword v140, v[8:9], off
	v_lshl_add_u64 v[8:9], v[8:9], 0, s[18:19]
	global_load_dword v142, v[8:9], off
	v_lshl_add_u64 v[8:9], v[8:9], 0, s[18:19]
	s_cmpk_eq_i32 s20, 0x400
	s_cbranch_scc0 .LBB0_17
	s_waitcnt vmcnt(0)
	s_movk_i32 s18, 0x3000
	s_barrier
	ds_write2st64_b32 v26, v3, v25 offset1:1
	ds_write2st64_b32 v26, v24, v23 offset0:2 offset1:3
	ds_write2st64_b32 v26, v22, v21 offset0:4 offset1:5
	ds_write2st64_b32 v26, v20, v19 offset0:6 offset1:7
	ds_write2st64_b32 v26, v18, v17 offset0:8 offset1:9
	ds_write2st64_b32 v26, v16, v15 offset0:10 offset1:11
	ds_write2st64_b32 v26, v14, v13 offset0:12 offset1:13
	ds_write2st64_b32 v26, v12, v11 offset0:14 offset1:15
	ds_write_b32 v26, v10 offset:4096
	s_waitcnt lgkmcnt(0)
	s_barrier
	s_and_saveexec_b64 s[20:21], s[4:5]
	s_cbranch_execz .LBB0_12
	s_mul_hi_i32 s23, s22, 17
	s_mul_i32 s22, s22, 17
	s_lshl_b32 s40, s38, 6
	s_mov_b64 s[24:25], 0
	v_mov_b32_e32 v3, v27
	v_mov_b32_e32 v6, v2

; __device__ __forceinline__ float sigmoidf_(float x) { return __builtin_amdgcn_rcpf(1.f + __expf(-x)); }
; template <int MF>
; __device__ __forceinline__ void gemm_in_tile(const Params& p, int l, char* smem, int mt, int nt) {
;     ...
;         if (nt >= 16 && nt < 32) {
;           float4 lb4 = *(const float4*)(p.lb + l * D + ((col - C_HGF) & 1023));
;           acc[m][n][0] = __logf(lb4.x + (1.f - lb4.x) * sigmoidf_(acc[m][n][0]));
;           acc[m][n][1] = __logf(lb4.y + (1.f - lb4.y) * sigmoidf_(acc[m][n][1]));
;           acc[m][n][2] = __logf(lb4.z + (1.f - lb4.z) * sigmoidf_(acc[m][n][2]));
;           acc[m][n][3] = __logf(lb4.w + (1.f - lb4.w) * sigmoidf_(acc[m][n][3]));
;         }
;         uint2 o; o.x = pack2(acc[m][n][0], acc[m][n][1]); o.y = pack2(acc[m][n][2], acc[m][n][3]);
;         *(uint2*)(dbase + (long)row * dld + col) = o;
.LBB0_194:
	v_lshlrev_b32_e32 v0, 6, v130
	v_lshlrev_b32_e32 v130, 2, v131
	v_or3_b32 v134, v0, s41, v130
	v_and_b32_e32 v0, 0x3cc, v134
	s_andn2_b64 vcc, exec, s[38:39]
	v_lshlrev_b32_e32 v0, 2, v0
	s_cbranch_vccnz .LBB0_196
	v_readlane_b32 s12, v240, 26
	v_readlane_b32 s13, v240, 27
	v_mul_f32_e32 v126, 0xbfb8aa3b, v126
	v_exp_f32_e32 v126, v126
	v_mul_f32_e32 v127, 0xbfb8aa3b, v127
	v_exp_f32_e32 v127, v127
	s_mov_b32 s10, 0x3f317217
	v_or_b32_e32 v236, 16, v134
	v_and_b32_e32 v236, 0x3ff, v236
	v_lshlrev_b32_e32 v236, 2, v236
	v_or_b32_e32 v237, 32, v134
	v_and_b32_e32 v237, 0x3ff, v237
	v_lshlrev_b32_e32 v237, 2, v237
	v_or_b32_e32 v238, 48, v134
	v_and_b32_e32 v238, 0x3ff, v238
	v_lshlrev_b32_e32 v238, 2, v238
	global_load_dwordx4 v[220:223], v0, s[12:13]
	global_load_dwordx4 v[224:227], v236, s[12:13]
	global_load_dwordx4 v[228:231], v237, s[12:13]
	global_load_dwordx4 v[232:235], v238, s[12:13]
	v_add_f32_e32 v126, 1.0, v126
	v_rcp_f32_e32 v126, v126
	v_add_f32_e32 v127, 1.0, v127
	v_rcp_f32_e32 v127, v127
	v_mul_f32_e32 v128, 0xbfb8aa3b, v128
	v_exp_f32_e32 v128, v128
	v_mul_f32_e32 v129, 0xbfb8aa3b, v129
	v_exp_f32_e32 v129, v129
	v_add_f32_e32 v128, 1.0, v128
	v_rcp_f32_e32 v128, v128
	v_add_f32_e32 v129, 1.0, v129
	v_rcp_f32_e32 v129, v129
	s_waitcnt vmcnt(0)
	v_mov_b32_e32 v130, v220
	v_mov_b32_e32 v131, v221
	v_mov_b32_e32 v132, v222
	v_mov_b32_e32 v133, v223
	v_sub_f32_e32 v137, 1.0, v130
	v_fma_f32 v126, v126, v137, v130
	v_cmp_gt_f32_e32 vcc, s25, v126
	s_nop 1
	v_cndmask_b32_e64 v130, 0, 32, vcc
	v_ldexp_f32 v126, v126, v130
	v_log_f32_e32 v126, v126
	s_nop 0
	v_mul_f32_e32 v130, 0x3f317217, v126
	v_fma_f32 v130, v126, s10, -v130
	v_fmac_f32_e32 v130, 0x3377d1cf, v126
	v_fmac_f32_e32 v130, 0x3f317217, v126
	v_cmp_lt_f32_e64 s[38:39], |v126|, s11
	s_nop 1
	v_cndmask_b32_e64 v126, v126, v130, s[38:39]
	v_cndmask_b32_e32 v130, 0, v171, vcc
	v_sub_f32_e32 v126, v126, v130
	v_sub_f32_e32 v130, 1.0, v131
	v_fma_f32 v127, v127, v130, v131
	v_cmp_gt_f32_e32 vcc, s25, v127
	s_nop 1
	v_cndmask_b32_e64 v130, 0, 32, vcc
	v_ldexp_f32 v127, v127, v130
	v_log_f32_e32 v127, v127
	s_nop 0
	v_mul_f32_e32 v130, 0x3f317217, v127
	v_fma_f32 v130, v127, s10, -v130
	v_fmac_f32_e32 v130, 0x3377d1cf, v127
	v_fmac_f32_e32 v130, 0x3f317217, v127
	v_cmp_lt_f32_e64 s[38:39], |v127|, s11
	s_nop 1
	v_cndmask_b32_e64 v127, v127, v130, s[38:39]
	v_cndmask_b32_e32 v130, 0, v171, vcc
	v_sub_f32_e32 v127, v127, v130
	v_sub_f32_e32 v130, 1.0, v132
	v_fma_f32 v128, v128, v130, v132
	v_cmp_gt_f32_e32 vcc, s25, v128
	s_nop 1
	v_cndmask_b32_e64 v130, 0, 32, vcc
	v_ldexp_f32 v128, v128, v130
	v_log_f32_e32 v128, v128
	s_nop 0
	v_mul_f32_e32 v130, 0x3f317217, v128
	v_fma_f32 v130, v128, s10, -v130
	v_fmac_f32_e32 v130, 0x3377d1cf, v128
	v_fmac_f32_e32 v130, 0x3f317217, v128
	v_cmp_lt_f32_e64 s[38:39], |v128|, s11
	s_nop 1
	v_cndmask_b32_e64 v128, v128, v130, s[38:39]
	v_cndmask_b32_e32 v130, 0, v171, vcc
	v_sub_f32_e32 v128, v128, v130
	v_sub_f32_e32 v130, 1.0, v133
	v_fmac_f32_e32 v133, v129, v130
	v_cmp_gt_f32_e32 vcc, s25, v133
	s_nop 1
	v_cndmask_b32_e64 v129, 0, 32, vcc
	v_ldexp_f32 v129, v133, v129
	v_log_f32_e32 v129, v129
	s_nop 0
	v_mul_f32_e32 v130, 0x3f317217, v129
	v_fma_f32 v130, v129, s10, -v130
	v_fmac_f32_e32 v130, 0x3377d1cf, v129
	v_fmac_f32_e32 v130, 0x3f317217, v129
	v_cmp_lt_f32_e64 s[38:39], |v129|, s11
	s_nop 1
	v_cndmask_b32_e64 v129, v129, v130, s[38:39]
	v_cndmask_b32_e32 v130, 0, v171, vcc
	v_sub_f32_e32 v129, v129, v130

; __device__ __forceinline__ float sigmoidf_(float x) { return __builtin_amdgcn_rcpf(1.f + __expf(-x)); }
; template <int MF>
; __device__ __forceinline__ void gemm_in_tile(const Params& p, int l, char* smem, int mt, int nt) {
;     ...
;         if (nt >= 16 && nt < 32) {
;           float4 lb4 = *(const float4*)(p.lb + l * D + ((col - C_HGF) & 1023));
;           acc[m][n][0] = __logf(lb4.x + (1.f - lb4.x) * sigmoidf_(acc[m][n][0]));
;           acc[m][n][1] = __logf(lb4.y + (1.f - lb4.y) * sigmoidf_(acc[m][n][1]));
;           acc[m][n][2] = __logf(lb4.z + (1.f - lb4.z) * sigmoidf_(acc[m][n][2]));
;           acc[m][n][3] = __logf(lb4.w + (1.f - lb4.w) * sigmoidf_(acc[m][n][3]));
;         }
;         uint2 o; o.x = pack2(acc[m][n][0], acc[m][n][1]); o.y = pack2(acc[m][n][2], acc[m][n][3]);
;         *(uint2*)(dbase + (long)row * dld + col) = o;
.LBB0_198:
	v_or_b32_e32 v126, 16, v134
	v_and_b32_e32 v126, 0x3ff, v126
	s_andn2_b64 vcc, exec, s[40:41]
	v_lshlrev_b32_e32 v132, 2, v126
	s_cbranch_vccnz .LBB0_200
	v_readlane_b32 s12, v240, 26
	v_readlane_b32 s13, v240, 27
	v_mul_f32_e32 v122, 0xbfb8aa3b, v122
	v_exp_f32_e32 v122, v122
	v_mul_f32_e32 v123, 0xbfb8aa3b, v123
	v_exp_f32_e32 v123, v123
	s_mov_b32 s10, 0x3f317217
	v_add_f32_e32 v122, 1.0, v122
	v_rcp_f32_e32 v122, v122
	v_add_f32_e32 v123, 1.0, v123
	v_rcp_f32_e32 v123, v123
	v_mul_f32_e32 v124, 0xbfb8aa3b, v124
	v_exp_f32_e32 v124, v124
	v_mul_f32_e32 v125, 0xbfb8aa3b, v125
	v_exp_f32_e32 v125, v125
	v_add_f32_e32 v124, 1.0, v124
	v_rcp_f32_e32 v124, v124
	v_add_f32_e32 v125, 1.0, v125
	v_rcp_f32_e32 v125, v125
	v_mov_b32_e32 v126, v224
	v_mov_b32_e32 v127, v225
	v_mov_b32_e32 v128, v226
	v_mov_b32_e32 v129, v227
	v_sub_f32_e32 v136, 1.0, v126
	v_fma_f32 v122, v122, v136, v126
	v_cmp_gt_f32_e32 vcc, s25, v122
	s_nop 1
	v_cndmask_b32_e64 v126, 0, 32, vcc
	v_ldexp_f32 v122, v122, v126
	v_log_f32_e32 v122, v122
	s_nop 0
	v_mul_f32_e32 v126, 0x3f317217, v122
	v_fma_f32 v126, v122, s10, -v126
	v_fmac_f32_e32 v126, 0x3377d1cf, v122
	v_fmac_f32_e32 v126, 0x3f317217, v122
	v_cmp_lt_f32_e64 s[40:41], |v122|, s11
	s_nop 1
	v_cndmask_b32_e64 v122, v122, v126, s[40:41]
	v_cndmask_b32_e32 v126, 0, v171, vcc
	v_sub_f32_e32 v122, v122, v126
	v_sub_f32_e32 v126, 1.0, v127
	v_fma_f32 v123, v123, v126, v127
	v_cmp_gt_f32_e32 vcc, s25, v123
	s_nop 1
	v_cndmask_b32_e64 v126, 0, 32, vcc
	v_ldexp_f32 v123, v123, v126
	v_log_f32_e32 v123, v123
	s_nop 0
	v_mul_f32_e32 v126, 0x3f317217, v123
	v_fma_f32 v126, v123, s10, -v126
	v_fmac_f32_e32 v126, 0x3377d1cf, v123
	v_fmac_f32_e32 v126, 0x3f317217, v123
	v_cmp_lt_f32_e64 s[40:41], |v123|, s11
	s_nop 1
	v_cndmask_b32_e64 v123, v123, v126, s[40:41]
	v_cndmask_b32_e32 v126, 0, v171, vcc
	v_sub_f32_e32 v123, v123, v126
	v_sub_f32_e32 v126, 1.0, v128
	v_fma_f32 v124, v124, v126, v128
	v_cmp_gt_f32_e32 vcc, s25, v124
	s_nop 1
	v_cndmask_b32_e64 v126, 0, 32, vcc
	v_ldexp_f32 v124, v124, v126
	v_log_f32_e32 v124, v124
	s_nop 0
	v_mul_f32_e32 v126, 0x3f317217, v124
	v_fma_f32 v126, v124, s10, -v126
	v_fmac_f32_e32 v126, 0x3377d1cf, v124
	v_fmac_f32_e32 v126, 0x3f317217, v124
	v_cmp_lt_f32_e64 s[40:41], |v124|, s11
	s_nop 1
	v_cndmask_b32_e64 v124, v124, v126, s[40:41]
	v_cndmask_b32_e32 v126, 0, v171, vcc
	v_sub_f32_e32 v124, v124, v126
	v_sub_f32_e32 v126, 1.0, v129
	v_fmac_f32_e32 v129, v125, v126
	v_cmp_gt_f32_e32 vcc, s25, v129
	s_nop 1
	v_cndmask_b32_e64 v125, 0, 32, vcc
	v_ldexp_f32 v125, v129, v125
	v_log_f32_e32 v125, v125
	s_nop 0
	v_mul_f32_e32 v126, 0x3f317217, v125
	v_fma_f32 v126, v125, s10, -v126
	v_fmac_f32_e32 v126, 0x3377d1cf, v125
	v_fmac_f32_e32 v126, 0x3f317217, v125
	v_cmp_lt_f32_e64 s[40:41], |v125|, s11
	s_nop 1
	v_cndmask_b32_e64 v125, v125, v126, s[40:41]
	v_cndmask_b32_e32 v126, 0, v171, vcc
	v_sub_f32_e32 v125, v125, v126

; __device__ __forceinline__ float sigmoidf_(float x) { return __builtin_amdgcn_rcpf(1.f + __expf(-x)); }
; template <int MF>
; __device__ __forceinline__ void gemm_in_tile(const Params& p, int l, char* smem, int mt, int nt) {
;     ...
;         if (nt >= 16 && nt < 32) {
;           float4 lb4 = *(const float4*)(p.lb + l * D + ((col - C_HGF) & 1023));
;           acc[m][n][0] = __logf(lb4.x + (1.f - lb4.x) * sigmoidf_(acc[m][n][0]));
;           acc[m][n][1] = __logf(lb4.y + (1.f - lb4.y) * sigmoidf_(acc[m][n][1]));
;           acc[m][n][2] = __logf(lb4.z + (1.f - lb4.z) * sigmoidf_(acc[m][n][2]));
;           acc[m][n][3] = __logf(lb4.w + (1.f - lb4.w) * sigmoidf_(acc[m][n][3]));
;         }
;         uint2 o; o.x = pack2(acc[m][n][0], acc[m][n][1]); o.y = pack2(acc[m][n][2], acc[m][n][3]);
;         *(uint2*)(dbase + (long)row * dld + col) = o;
.LBB0_202:
	v_or_b32_e32 v122, 32, v134
	v_and_b32_e32 v122, 0x3ff, v122
	s_andn2_b64 vcc, exec, s[40:41]
	v_lshlrev_b32_e32 v126, 2, v122
	s_cbranch_vccnz .LBB0_204
	v_readlane_b32 s12, v240, 26
	v_readlane_b32 s13, v240, 27
	v_mul_f32_e32 v118, 0xbfb8aa3b, v118
	v_exp_f32_e32 v118, v118
	v_mul_f32_e32 v119, 0xbfb8aa3b, v119
	v_exp_f32_e32 v119, v119
	s_mov_b32 s10, 0x3f317217
	v_add_f32_e32 v118, 1.0, v118
	v_rcp_f32_e32 v118, v118
	v_add_f32_e32 v119, 1.0, v119
	v_rcp_f32_e32 v119, v119
	v_mul_f32_e32 v120, 0xbfb8aa3b, v120
	v_exp_f32_e32 v120, v120
	v_mul_f32_e32 v121, 0xbfb8aa3b, v121
	v_exp_f32_e32 v121, v121
	v_add_f32_e32 v120, 1.0, v120
	v_rcp_f32_e32 v120, v120
	v_add_f32_e32 v121, 1.0, v121
	v_rcp_f32_e32 v121, v121
	v_mov_b32_e32 v122, v228
	v_mov_b32_e32 v123, v229
	v_mov_b32_e32 v124, v230
	v_mov_b32_e32 v125, v231
	v_sub_f32_e32 v127, 1.0, v122
	v_fma_f32 v118, v118, v127, v122
	v_cmp_gt_f32_e32 vcc, s25, v118
	s_nop 1
	v_cndmask_b32_e64 v122, 0, 32, vcc
	v_ldexp_f32 v118, v118, v122
	v_log_f32_e32 v118, v118
	s_nop 0
	v_mul_f32_e32 v122, 0x3f317217, v118
	v_fma_f32 v122, v118, s10, -v122
	v_fmac_f32_e32 v122, 0x3377d1cf, v118
	v_fmac_f32_e32 v122, 0x3f317217, v118
	v_cmp_lt_f32_e64 s[40:41], |v118|, s11
	s_nop 1
	v_cndmask_b32_e64 v118, v118, v122, s[40:41]
	v_cndmask_b32_e32 v122, 0, v171, vcc
	v_sub_f32_e32 v118, v118, v122
	v_sub_f32_e32 v122, 1.0, v123
	v_fma_f32 v119, v119, v122, v123
	v_cmp_gt_f32_e32 vcc, s25, v119
	s_nop 1
	v_cndmask_b32_e64 v122, 0, 32, vcc
	v_ldexp_f32 v119, v119, v122
	v_log_f32_e32 v119, v119
	s_nop 0
	v_mul_f32_e32 v122, 0x3f317217, v119
	v_fma_f32 v122, v119, s10, -v122
	v_fmac_f32_e32 v122, 0x3377d1cf, v119
	v_fmac_f32_e32 v122, 0x3f317217, v119
	v_cmp_lt_f32_e64 s[40:41], |v119|, s11
	s_nop 1
	v_cndmask_b32_e64 v119, v119, v122, s[40:41]
	v_cndmask_b32_e32 v122, 0, v171, vcc
	v_sub_f32_e32 v119, v119, v122
	v_sub_f32_e32 v122, 1.0, v124
	v_fma_f32 v120, v120, v122, v124
	v_cmp_gt_f32_e32 vcc, s25, v120
	s_nop 1
	v_cndmask_b32_e64 v122, 0, 32, vcc
	v_ldexp_f32 v120, v120, v122
	v_log_f32_e32 v120, v120
	s_nop 0
	v_mul_f32_e32 v122, 0x3f317217, v120
	v_fma_f32 v122, v120, s10, -v122
	v_fmac_f32_e32 v122, 0x3377d1cf, v120
	v_fmac_f32_e32 v122, 0x3f317217, v120
	v_cmp_lt_f32_e64 s[40:41], |v120|, s11
	s_nop 1
	v_cndmask_b32_e64 v120, v120, v122, s[40:41]
	v_cndmask_b32_e32 v122, 0, v171, vcc
	v_sub_f32_e32 v120, v120, v122
	v_sub_f32_e32 v122, 1.0, v125
	v_fmac_f32_e32 v125, v121, v122
	v_cmp_gt_f32_e32 vcc, s25, v125
	s_nop 1
	v_cndmask_b32_e64 v121, 0, 32, vcc
	v_ldexp_f32 v121, v125, v121
	v_log_f32_e32 v121, v121
	s_nop 0
	v_mul_f32_e32 v122, 0x3f317217, v121
	v_fma_f32 v122, v121, s10, -v122
	v_fmac_f32_e32 v122, 0x3377d1cf, v121
	v_fmac_f32_e32 v122, 0x3f317217, v121
	v_cmp_lt_f32_e64 s[40:41], |v121|, s11
	s_nop 1
	v_cndmask_b32_e64 v121, v121, v122, s[40:41]
	v_cndmask_b32_e32 v122, 0, v171, vcc
	v_sub_f32_e32 v121, v121, v122

; __device__ __forceinline__ float sigmoidf_(float x) { return __builtin_amdgcn_rcpf(1.f + __expf(-x)); }
; template <int MF>
; __device__ __forceinline__ void gemm_in_tile(const Params& p, int l, char* smem, int mt, int nt) {
;     ...
;         if (nt >= 16 && nt < 32) {
;           float4 lb4 = *(const float4*)(p.lb + l * D + ((col - C_HGF) & 1023));
;           acc[m][n][0] = __logf(lb4.x + (1.f - lb4.x) * sigmoidf_(acc[m][n][0]));
;           acc[m][n][1] = __logf(lb4.y + (1.f - lb4.y) * sigmoidf_(acc[m][n][1]));
;           acc[m][n][2] = __logf(lb4.z + (1.f - lb4.z) * sigmoidf_(acc[m][n][2]));
;           acc[m][n][3] = __logf(lb4.w + (1.f - lb4.w) * sigmoidf_(acc[m][n][3]));
;         }
;         uint2 o; o.x = pack2(acc[m][n][0], acc[m][n][1]); o.y = pack2(acc[m][n][2], acc[m][n][3]);
;         *(uint2*)(dbase + (long)row * dld + col) = o;
.LBB0_206:
	v_or_b32_e32 v118, 48, v134
	v_and_b32_e32 v118, 0x3ff, v118
	s_andn2_b64 vcc, exec, s[38:39]
	v_lshlrev_b32_e32 v122, 2, v118
	s_cbranch_vccnz .LBB0_208
	v_mul_f32_e32 v114, 0xbfb8aa3b, v114
	v_exp_f32_e32 v114, v114
	v_mul_f32_e32 v115, 0xbfb8aa3b, v115
	v_exp_f32_e32 v115, v115
	s_mov_b32 s10, 0x3f317217
	v_add_f32_e32 v114, 1.0, v114
	v_rcp_f32_e32 v114, v114
	v_add_f32_e32 v115, 1.0, v115
	v_rcp_f32_e32 v115, v115
	v_mul_f32_e32 v116, 0xbfb8aa3b, v116
	v_exp_f32_e32 v116, v116
	v_mul_f32_e32 v117, 0xbfb8aa3b, v117
	v_exp_f32_e32 v117, v117
	v_add_f32_e32 v116, 1.0, v116
	v_rcp_f32_e32 v116, v116
	v_add_f32_e32 v117, 1.0, v117
	v_rcp_f32_e32 v117, v117
	v_mov_b32_e32 v118, v232
	v_mov_b32_e32 v119, v233
	v_mov_b32_e32 v120, v234
	v_mov_b32_e32 v121, v235
	v_sub_f32_e32 v123, 1.0, v118
	v_fma_f32 v114, v114, v123, v118
	v_cmp_gt_f32_e32 vcc, s25, v114
	s_nop 1
	v_cndmask_b32_e64 v118, 0, 32, vcc
	v_ldexp_f32 v114, v114, v118
	v_log_f32_e32 v114, v114
	s_nop 0
	v_mul_f32_e32 v118, 0x3f317217, v114
	v_fma_f32 v118, v114, s10, -v118
	v_fmac_f32_e32 v118, 0x3377d1cf, v114
	v_fmac_f32_e32 v118, 0x3f317217, v114
	v_cmp_lt_f32_e64 s[38:39], |v114|, s11
	s_nop 1
	v_cndmask_b32_e64 v114, v114, v118, s[38:39]
	v_cndmask_b32_e32 v118, 0, v171, vcc
	v_sub_f32_e32 v114, v114, v118
	v_sub_f32_e32 v118, 1.0, v119
	v_fma_f32 v115, v115, v118, v119
	v_cmp_gt_f32_e32 vcc, s25, v115
	s_nop 1
	v_cndmask_b32_e64 v118, 0, 32, vcc
	v_ldexp_f32 v115, v115, v118
	v_log_f32_e32 v115, v115
	s_nop 0
	v_mul_f32_e32 v118, 0x3f317217, v115
	v_fma_f32 v118, v115, s10, -v118
	v_fmac_f32_e32 v118, 0x3377d1cf, v115
	v_fmac_f32_e32 v118, 0x3f317217, v115
	v_cmp_lt_f32_e64 s[38:39], |v115|, s11
	s_nop 1
	v_cndmask_b32_e64 v115, v115, v118, s[38:39]
	v_cndmask_b32_e32 v118, 0, v171, vcc
	v_sub_f32_e32 v115, v115, v118
	v_sub_f32_e32 v118, 1.0, v120
	v_fma_f32 v116, v116, v118, v120
	v_cmp_gt_f32_e32 vcc, s25, v116
	s_nop 1
	v_cndmask_b32_e64 v118, 0, 32, vcc
	v_ldexp_f32 v116, v116, v118
	v_log_f32_e32 v116, v116
	s_nop 0
	v_mul_f32_e32 v118, 0x3f317217, v116
	v_fma_f32 v118, v116, s10, -v118
	v_fmac_f32_e32 v118, 0x3377d1cf, v116
	v_fmac_f32_e32 v118, 0x3f317217, v116
	v_cmp_lt_f32_e64 s[38:39], |v116|, s11
	s_nop 1
	v_cndmask_b32_e64 v116, v116, v118, s[38:39]
	v_cndmask_b32_e32 v118, 0, v171, vcc
	v_sub_f32_e32 v116, v116, v118
	v_sub_f32_e32 v118, 1.0, v121
	v_fmac_f32_e32 v121, v117, v118
	v_cmp_gt_f32_e32 vcc, s25, v121
	s_nop 1
	v_cndmask_b32_e64 v117, 0, 32, vcc
	v_ldexp_f32 v117, v121, v117
	v_log_f32_e32 v117, v117
	s_nop 0
	v_mul_f32_e32 v118, 0x3f317217, v117
	v_fma_f32 v118, v117, s10, -v118
	v_fmac_f32_e32 v118, 0x3377d1cf, v117
	v_fmac_f32_e32 v118, 0x3f317217, v117
	v_cmp_lt_f32_e64 s[38:39], |v117|, s11
	s_nop 1
	v_cndmask_b32_e64 v117, v117, v118, s[38:39]
	v_cndmask_b32_e32 v118, 0, v171, vcc
	v_sub_f32_e32 v117, v117, v118

; __device__ __forceinline__ float sigmoidf_(float x) { return __builtin_amdgcn_rcpf(1.f + __expf(-x)); }
; template <int MF>
; __device__ __forceinline__ void gemm_in_tile(const Params& p, int l, char* smem, int mt, int nt) {
;     ...
;         if (nt >= 16 && nt < 32) {
;           float4 lb4 = *(const float4*)(p.lb + l * D + ((col - C_HGF) & 1023));
;           acc[m][n][0] = __logf(lb4.x + (1.f - lb4.x) * sigmoidf_(acc[m][n][0]));
;           acc[m][n][1] = __logf(lb4.y + (1.f - lb4.y) * sigmoidf_(acc[m][n][1]));
;           acc[m][n][2] = __logf(lb4.z + (1.f - lb4.z) * sigmoidf_(acc[m][n][2]));
;           acc[m][n][3] = __logf(lb4.w + (1.f - lb4.w) * sigmoidf_(acc[m][n][3]));
;         }
;         uint2 o; o.x = pack2(acc[m][n][0], acc[m][n][1]); o.y = pack2(acc[m][n][2], acc[m][n][3]);
;         *(uint2*)(dbase + (long)row * dld + col) = o;
.LBB0_210:
	s_andn2_b64 vcc, exec, s[38:39]
	s_cbranch_vccnz .LBB0_212
	v_mul_f32_e32 v110, 0xbfb8aa3b, v110
	v_exp_f32_e32 v110, v110
	v_mul_f32_e32 v111, 0xbfb8aa3b, v111
	v_exp_f32_e32 v111, v111
	s_mov_b32 s10, 0x3f317217
	v_add_f32_e32 v110, 1.0, v110
	v_rcp_f32_e32 v110, v110
	v_add_f32_e32 v111, 1.0, v111
	v_rcp_f32_e32 v111, v111
	v_mul_f32_e32 v112, 0xbfb8aa3b, v112
	v_exp_f32_e32 v112, v112
	v_mul_f32_e32 v113, 0xbfb8aa3b, v113
	v_exp_f32_e32 v113, v113
	v_mul_f32_e32 v106, 0xbfb8aa3b, v106
	v_add_f32_e32 v112, 1.0, v112
	v_rcp_f32_e32 v112, v112
	v_add_f32_e32 v113, 1.0, v113
	v_rcp_f32_e32 v113, v113
	v_exp_f32_e32 v106, v106
	v_mul_f32_e32 v107, 0xbfb8aa3b, v107
	v_exp_f32_e32 v107, v107
	v_mul_f32_e32 v108, 0xbfb8aa3b, v108
	v_add_f32_e32 v106, 1.0, v106
	v_rcp_f32_e32 v106, v106
	v_add_f32_e32 v107, 1.0, v107
	v_rcp_f32_e32 v107, v107
	v_exp_f32_e32 v108, v108
	v_mul_f32_e32 v109, 0xbfb8aa3b, v109
	v_exp_f32_e32 v109, v109
	v_add_f32_e32 v108, 1.0, v108
	v_rcp_f32_e32 v108, v108
	v_add_f32_e32 v109, 1.0, v109
	v_rcp_f32_e32 v109, v109
	v_mov_b32_e32 v114, v220
	v_mov_b32_e32 v115, v221
	v_mov_b32_e32 v116, v222
	v_mov_b32_e32 v117, v223
	v_sub_f32_e32 v120, 1.0, v114
	v_fma_f32 v110, v110, v120, v114
	v_cmp_gt_f32_e32 vcc, s25, v110
	s_nop 1
	v_cndmask_b32_e64 v114, 0, 32, vcc
	v_ldexp_f32 v110, v110, v114
	v_log_f32_e32 v110, v110
	s_nop 0
	v_mul_f32_e32 v114, 0x3f317217, v110
	v_fma_f32 v114, v110, s10, -v114
	v_fmac_f32_e32 v114, 0x3377d1cf, v110
	v_fmac_f32_e32 v114, 0x3f317217, v110
	v_cmp_lt_f32_e64 s[38:39], |v110|, s11
	s_nop 1
	v_cndmask_b32_e64 v110, v110, v114, s[38:39]
	v_cndmask_b32_e32 v114, 0, v171, vcc
	v_sub_f32_e32 v110, v110, v114
	v_sub_f32_e32 v114, 1.0, v115
	v_fma_f32 v111, v111, v114, v115
	v_cmp_gt_f32_e32 vcc, s25, v111
	s_nop 1
	v_cndmask_b32_e64 v114, 0, 32, vcc
	v_ldexp_f32 v111, v111, v114
	v_log_f32_e32 v111, v111
	s_nop 0
	v_mul_f32_e32 v114, 0x3f317217, v111
	v_fma_f32 v114, v111, s10, -v114
	v_fmac_f32_e32 v114, 0x3377d1cf, v111
	v_fmac_f32_e32 v114, 0x3f317217, v111
	v_cmp_lt_f32_e64 s[38:39], |v111|, s11
	s_nop 1
	v_cndmask_b32_e64 v111, v111, v114, s[38:39]
	v_cndmask_b32_e32 v114, 0, v171, vcc
	v_sub_f32_e32 v111, v111, v114
	v_sub_f32_e32 v114, 1.0, v116
	v_fma_f32 v112, v112, v114, v116
	v_cmp_gt_f32_e32 vcc, s25, v112
	v_cvt_pk_bf16_f32 v110, v110, v111
	s_nop 0
	v_cndmask_b32_e64 v114, 0, 32, vcc
	v_ldexp_f32 v112, v112, v114
	v_log_f32_e32 v112, v112
	s_nop 0
	v_mul_f32_e32 v114, 0x3f317217, v112
	v_fma_f32 v114, v112, s10, -v114
	v_fmac_f32_e32 v114, 0x3377d1cf, v112
	v_fmac_f32_e32 v114, 0x3f317217, v112
	v_cmp_lt_f32_e64 s[38:39], |v112|, s11
	s_nop 1
	v_cndmask_b32_e64 v112, v112, v114, s[38:39]
	v_cndmask_b32_e32 v114, 0, v171, vcc
	v_sub_f32_e32 v112, v112, v114
	v_sub_f32_e32 v114, 1.0, v117
	v_fmac_f32_e32 v117, v113, v114
	v_cmp_gt_f32_e32 vcc, s25, v117
	s_nop 1
	v_cndmask_b32_e64 v113, 0, 32, vcc
	v_ldexp_f32 v113, v117, v113
	v_log_f32_e32 v113, v113
	s_nop 0
	v_mul_f32_e32 v114, 0x3f317217, v113
	v_fma_f32 v114, v113, s10, -v114
	v_fmac_f32_e32 v114, 0x3377d1cf, v113
	v_fmac_f32_e32 v114, 0x3f317217, v113
	v_cmp_lt_f32_e64 s[38:39], |v113|, s11
	s_nop 1
	v_cndmask_b32_e64 v113, v113, v114, s[38:39]
	v_cndmask_b32_e32 v114, 0, v171, vcc
	v_sub_f32_e32 v113, v113, v114
	v_cvt_pk_bf16_f32 v111, v112, v113
	global_store_dwordx2 v[118:119], v[110:111], off
	v_mov_b32_e32 v110, v224
	v_mov_b32_e32 v111, v225
	v_mov_b32_e32 v112, v226
	v_mov_b32_e32 v113, v227
	v_sub_f32_e32 v114, 1.0, v110
	v_fma_f32 v106, v106, v114, v110
	v_cmp_gt_f32_e32 vcc, s25, v106
	s_nop 1
	v_cndmask_b32_e64 v110, 0, 32, vcc
	v_ldexp_f32 v106, v106, v110
	v_log_f32_e32 v106, v106
	s_nop 0
	v_mul_f32_e32 v110, 0x3f317217, v106
	v_fma_f32 v110, v106, s10, -v110
	v_fmac_f32_e32 v110, 0x3377d1cf, v106
	v_fmac_f32_e32 v110, 0x3f317217, v106
	v_cmp_lt_f32_e64 s[38:39], |v106|, s11
	s_nop 1
	v_cndmask_b32_e64 v106, v106, v110, s[38:39]
	v_cndmask_b32_e32 v110, 0, v171, vcc
	v_sub_f32_e32 v106, v106, v110
	v_sub_f32_e32 v110, 1.0, v111
	v_fma_f32 v107, v107, v110, v111
	v_cmp_gt_f32_e32 vcc, s25, v107
	s_nop 1
	v_cndmask_b32_e64 v110, 0, 32, vcc
	v_ldexp_f32 v107, v107, v110
	v_log_f32_e32 v107, v107
	s_nop 0
	v_mul_f32_e32 v110, 0x3f317217, v107
	v_fma_f32 v110, v107, s10, -v110
	v_fmac_f32_e32 v110, 0x3377d1cf, v107
	v_fmac_f32_e32 v110, 0x3f317217, v107
	v_cmp_lt_f32_e64 s[38:39], |v107|, s11
	s_nop 1
	v_cndmask_b32_e64 v107, v107, v110, s[38:39]
	v_cndmask_b32_e32 v110, 0, v171, vcc
	v_sub_f32_e32 v107, v107, v110
	v_sub_f32_e32 v110, 1.0, v112
	v_fma_f32 v108, v108, v110, v112
	v_cmp_gt_f32_e32 vcc, s25, v108
	s_nop 1
	v_cndmask_b32_e64 v110, 0, 32, vcc
	v_ldexp_f32 v108, v108, v110
	v_log_f32_e32 v108, v108
	s_nop 0
	v_mul_f32_e32 v110, 0x3f317217, v108
	v_fma_f32 v110, v108, s10, -v110
	v_fmac_f32_e32 v110, 0x3377d1cf, v108
	v_fmac_f32_e32 v110, 0x3f317217, v108
	v_cmp_lt_f32_e64 s[38:39], |v108|, s11
	s_nop 1
	v_cndmask_b32_e64 v108, v108, v110, s[38:39]
	v_cndmask_b32_e32 v110, 0, v171, vcc
	v_sub_f32_e32 v108, v108, v110
	v_sub_f32_e32 v110, 1.0, v113
	v_fmac_f32_e32 v113, v109, v110
	v_cmp_gt_f32_e32 vcc, s25, v113
	s_nop 1
	v_cndmask_b32_e64 v109, 0, 32, vcc
	v_ldexp_f32 v109, v113, v109
	v_log_f32_e32 v109, v109
	s_nop 0
	v_mul_f32_e32 v110, 0x3f317217, v109
	v_fma_f32 v110, v109, s10, -v110
	v_fmac_f32_e32 v110, 0x3377d1cf, v109
	v_fmac_f32_e32 v110, 0x3f317217, v109
	v_cmp_lt_f32_e64 s[38:39], |v109|, s11
	s_nop 1
	v_cndmask_b32_e64 v109, v109, v110, s[38:39]
	v_cndmask_b32_e32 v110, 0, v171, vcc
	v_sub_f32_e32 v109, v109, v110

; __device__ __forceinline__ float sigmoidf_(float x) { return __builtin_amdgcn_rcpf(1.f + __expf(-x)); }
; template <int MF>
; __device__ __forceinline__ void gemm_in_tile(const Params& p, int l, char* smem, int mt, int nt) {
;     ...
;         if (nt >= 16 && nt < 32) {
;           float4 lb4 = *(const float4*)(p.lb + l * D + ((col - C_HGF) & 1023));
;           acc[m][n][0] = __logf(lb4.x + (1.f - lb4.x) * sigmoidf_(acc[m][n][0]));
;           acc[m][n][1] = __logf(lb4.y + (1.f - lb4.y) * sigmoidf_(acc[m][n][1]));
;           acc[m][n][2] = __logf(lb4.z + (1.f - lb4.z) * sigmoidf_(acc[m][n][2]));
;           acc[m][n][3] = __logf(lb4.w + (1.f - lb4.w) * sigmoidf_(acc[m][n][3]));
;         }
;         uint2 o; o.x = pack2(acc[m][n][0], acc[m][n][1]); o.y = pack2(acc[m][n][2], acc[m][n][3]);
;         *(uint2*)(dbase + (long)row * dld + col) = o;
.LBB0_214:
	s_andn2_b64 vcc, exec, s[38:39]
	s_cbranch_vccnz .LBB0_216
	v_mul_f32_e32 v102, 0xbfb8aa3b, v102
	v_exp_f32_e32 v102, v102
	v_mul_f32_e32 v103, 0xbfb8aa3b, v103
	v_exp_f32_e32 v103, v103
	s_mov_b32 s10, 0x3f317217
	v_add_f32_e32 v102, 1.0, v102
	v_rcp_f32_e32 v102, v102
	v_add_f32_e32 v103, 1.0, v103
	v_rcp_f32_e32 v103, v103
	v_mul_f32_e32 v104, 0xbfb8aa3b, v104
	v_exp_f32_e32 v104, v104
	v_mul_f32_e32 v105, 0xbfb8aa3b, v105
	v_exp_f32_e32 v105, v105
	v_mul_f32_e32 v98, 0xbfb8aa3b, v98
	v_add_f32_e32 v104, 1.0, v104
	v_rcp_f32_e32 v104, v104
	v_add_f32_e32 v105, 1.0, v105
	v_rcp_f32_e32 v105, v105
	v_exp_f32_e32 v98, v98
	v_mul_f32_e32 v99, 0xbfb8aa3b, v99
	v_exp_f32_e32 v99, v99
	v_mul_f32_e32 v100, 0xbfb8aa3b, v100
	v_add_f32_e32 v98, 1.0, v98
	v_rcp_f32_e32 v98, v98
	v_add_f32_e32 v99, 1.0, v99
	v_rcp_f32_e32 v99, v99
	v_exp_f32_e32 v100, v100
	v_mul_f32_e32 v101, 0xbfb8aa3b, v101
	v_exp_f32_e32 v101, v101
	v_add_f32_e32 v100, 1.0, v100
	v_rcp_f32_e32 v100, v100
	v_add_f32_e32 v101, 1.0, v101
	v_rcp_f32_e32 v101, v101
	v_mov_b32_e32 v106, v228
	v_mov_b32_e32 v107, v229
	v_mov_b32_e32 v108, v230
	v_mov_b32_e32 v109, v231
	v_sub_f32_e32 v110, 1.0, v106
	v_fma_f32 v102, v102, v110, v106
	v_cmp_gt_f32_e32 vcc, s25, v102
	s_nop 1
	v_cndmask_b32_e64 v106, 0, 32, vcc
	v_ldexp_f32 v102, v102, v106
	v_log_f32_e32 v102, v102
	s_nop 0
	v_mul_f32_e32 v106, 0x3f317217, v102
	v_fma_f32 v106, v102, s10, -v106
	v_fmac_f32_e32 v106, 0x3377d1cf, v102
	v_fmac_f32_e32 v106, 0x3f317217, v102
	v_cmp_lt_f32_e64 s[38:39], |v102|, s11
	s_nop 1
	v_cndmask_b32_e64 v102, v102, v106, s[38:39]
	v_cndmask_b32_e32 v106, 0, v171, vcc
	v_sub_f32_e32 v102, v102, v106
	v_sub_f32_e32 v106, 1.0, v107
	v_fma_f32 v103, v103, v106, v107
	v_cmp_gt_f32_e32 vcc, s25, v103
	s_nop 1
	v_cndmask_b32_e64 v106, 0, 32, vcc
	v_ldexp_f32 v103, v103, v106
	v_log_f32_e32 v103, v103
	s_nop 0
	v_mul_f32_e32 v106, 0x3f317217, v103
	v_fma_f32 v106, v103, s10, -v106
	v_fmac_f32_e32 v106, 0x3377d1cf, v103
	v_fmac_f32_e32 v106, 0x3f317217, v103
	v_cmp_lt_f32_e64 s[38:39], |v103|, s11
	s_nop 1
	v_cndmask_b32_e64 v103, v103, v106, s[38:39]
	v_cndmask_b32_e32 v106, 0, v171, vcc
	v_sub_f32_e32 v103, v103, v106
	v_sub_f32_e32 v106, 1.0, v108
	v_fma_f32 v104, v104, v106, v108
	v_cmp_gt_f32_e32 vcc, s25, v104
	v_cvt_pk_bf16_f32 v102, v102, v103
	s_nop 0
	v_cndmask_b32_e64 v106, 0, 32, vcc
	v_ldexp_f32 v104, v104, v106
	v_log_f32_e32 v104, v104
	s_nop 0
	v_mul_f32_e32 v106, 0x3f317217, v104
	v_fma_f32 v106, v104, s10, -v106
	v_fmac_f32_e32 v106, 0x3377d1cf, v104
	v_fmac_f32_e32 v106, 0x3f317217, v104
	v_cmp_lt_f32_e64 s[38:39], |v104|, s11
	s_nop 1
	v_cndmask_b32_e64 v104, v104, v106, s[38:39]
	v_cndmask_b32_e32 v106, 0, v171, vcc
	v_sub_f32_e32 v104, v104, v106
	v_sub_f32_e32 v106, 1.0, v109
	v_fmac_f32_e32 v109, v105, v106
	v_cmp_gt_f32_e32 vcc, s25, v109
	s_nop 1
	v_cndmask_b32_e64 v105, 0, 32, vcc
	v_ldexp_f32 v105, v109, v105
	v_log_f32_e32 v105, v105
	s_nop 0
	v_mul_f32_e32 v106, 0x3f317217, v105
	v_fma_f32 v106, v105, s10, -v106
	v_fmac_f32_e32 v106, 0x3377d1cf, v105
	v_fmac_f32_e32 v106, 0x3f317217, v105
	v_cmp_lt_f32_e64 s[38:39], |v105|, s11
	s_nop 1
	v_cndmask_b32_e64 v105, v105, v106, s[38:39]
	v_cndmask_b32_e32 v106, 0, v171, vcc
	v_sub_f32_e32 v105, v105, v106
	v_cvt_pk_bf16_f32 v103, v104, v105
	global_store_dwordx2 v[118:119], v[102:103], off offset:64
	v_mov_b32_e32 v102, v232
	v_mov_b32_e32 v103, v233
	v_mov_b32_e32 v104, v234
	v_mov_b32_e32 v105, v235
	v_sub_f32_e32 v106, 1.0, v102
	v_fma_f32 v98, v98, v106, v102
	v_cmp_gt_f32_e32 vcc, s25, v98
	s_nop 1
	v_cndmask_b32_e64 v102, 0, 32, vcc
	v_ldexp_f32 v98, v98, v102
	v_log_f32_e32 v98, v98
	s_nop 0
	v_mul_f32_e32 v102, 0x3f317217, v98
	v_fma_f32 v102, v98, s10, -v102
	v_fmac_f32_e32 v102, 0x3377d1cf, v98
	v_fmac_f32_e32 v102, 0x3f317217, v98
	v_cmp_lt_f32_e64 s[38:39], |v98|, s11
	s_nop 1
	v_cndmask_b32_e64 v98, v98, v102, s[38:39]
	v_cndmask_b32_e32 v102, 0, v171, vcc
	v_sub_f32_e32 v98, v98, v102
	v_sub_f32_e32 v102, 1.0, v103
	v_fma_f32 v99, v99, v102, v103
	v_cmp_gt_f32_e32 vcc, s25, v99
	s_nop 1
	v_cndmask_b32_e64 v102, 0, 32, vcc
	v_ldexp_f32 v99, v99, v102
	v_log_f32_e32 v99, v99
	s_nop 0
	v_mul_f32_e32 v102, 0x3f317217, v99
	v_fma_f32 v102, v99, s10, -v102
	v_fmac_f32_e32 v102, 0x3377d1cf, v99
	v_fmac_f32_e32 v102, 0x3f317217, v99
	v_cmp_lt_f32_e64 s[38:39], |v99|, s11
	s_nop 1
	v_cndmask_b32_e64 v99, v99, v102, s[38:39]
	v_cndmask_b32_e32 v102, 0, v171, vcc
	v_sub_f32_e32 v99, v99, v102
	v_sub_f32_e32 v102, 1.0, v104
	v_fma_f32 v100, v100, v102, v104
	v_cmp_gt_f32_e32 vcc, s25, v100
	s_nop 1
	v_cndmask_b32_e64 v102, 0, 32, vcc
	v_ldexp_f32 v100, v100, v102
	v_log_f32_e32 v100, v100
	s_nop 0
	v_mul_f32_e32 v102, 0x3f317217, v100
	v_fma_f32 v102, v100, s10, -v102
	v_fmac_f32_e32 v102, 0x3377d1cf, v100
	v_fmac_f32_e32 v102, 0x3f317217, v100
	v_cmp_lt_f32_e64 s[38:39], |v100|, s11
	s_nop 1
	v_cndmask_b32_e64 v100, v100, v102, s[38:39]
	v_cndmask_b32_e32 v102, 0, v171, vcc
	v_sub_f32_e32 v100, v100, v102
	v_sub_f32_e32 v102, 1.0, v105
	v_fmac_f32_e32 v105, v101, v102
	v_cmp_gt_f32_e32 vcc, s25, v105
	s_nop 1
	v_cndmask_b32_e64 v101, 0, 32, vcc
	v_ldexp_f32 v101, v105, v101
	v_log_f32_e32 v101, v101
	s_nop 0
	v_mul_f32_e32 v102, 0x3f317217, v101
	v_fma_f32 v102, v101, s10, -v102
	v_fmac_f32_e32 v102, 0x3377d1cf, v101
	v_fmac_f32_e32 v102, 0x3f317217, v101
	v_cmp_lt_f32_e64 s[38:39], |v101|, s11
	s_nop 1
	v_cndmask_b32_e64 v101, v101, v102, s[38:39]
	v_cndmask_b32_e32 v102, 0, v171, vcc
	v_sub_f32_e32 v101, v101, v102

; __device__ __forceinline__ float sigmoidf_(float x) { return __builtin_amdgcn_rcpf(1.f + __expf(-x)); }
; template <int MF>
; __device__ __forceinline__ void gemm_in_tile(const Params& p, int l, char* smem, int mt, int nt) {
;     ...
;         if (nt >= 16 && nt < 32) {
;           float4 lb4 = *(const float4*)(p.lb + l * D + ((col - C_HGF) & 1023));
;           acc[m][n][0] = __logf(lb4.x + (1.f - lb4.x) * sigmoidf_(acc[m][n][0]));
;           acc[m][n][1] = __logf(lb4.y + (1.f - lb4.y) * sigmoidf_(acc[m][n][1]));
;           acc[m][n][2] = __logf(lb4.z + (1.f - lb4.z) * sigmoidf_(acc[m][n][2]));
;           acc[m][n][3] = __logf(lb4.w + (1.f - lb4.w) * sigmoidf_(acc[m][n][3]));
;         }
;         uint2 o; o.x = pack2(acc[m][n][0], acc[m][n][1]); o.y = pack2(acc[m][n][2], acc[m][n][3]);
;         *(uint2*)(dbase + (long)row * dld + col) = o;
.LBB0_218:
	s_andn2_b64 vcc, exec, s[38:39]
	s_cbranch_vccnz .LBB0_220
	v_mul_f32_e32 v94, 0xbfb8aa3b, v94
	v_exp_f32_e32 v94, v94
	v_mul_f32_e32 v95, 0xbfb8aa3b, v95
	v_exp_f32_e32 v95, v95
	s_mov_b32 s10, 0x3f317217
	v_add_f32_e32 v94, 1.0, v94
	v_rcp_f32_e32 v94, v94
	v_add_f32_e32 v95, 1.0, v95
	v_rcp_f32_e32 v95, v95
	v_mul_f32_e32 v96, 0xbfb8aa3b, v96
	v_exp_f32_e32 v96, v96
	v_mul_f32_e32 v97, 0xbfb8aa3b, v97
	v_exp_f32_e32 v97, v97
	v_mul_f32_e32 v90, 0xbfb8aa3b, v90
	v_add_f32_e32 v96, 1.0, v96
	v_rcp_f32_e32 v96, v96
	v_add_f32_e32 v97, 1.0, v97
	v_rcp_f32_e32 v97, v97
	v_exp_f32_e32 v90, v90
	v_mul_f32_e32 v91, 0xbfb8aa3b, v91
	v_exp_f32_e32 v91, v91
	v_mul_f32_e32 v92, 0xbfb8aa3b, v92
	v_add_f32_e32 v90, 1.0, v90
	v_rcp_f32_e32 v90, v90
	v_add_f32_e32 v91, 1.0, v91
	v_rcp_f32_e32 v91, v91
	v_exp_f32_e32 v92, v92
	v_mul_f32_e32 v93, 0xbfb8aa3b, v93
	v_exp_f32_e32 v93, v93
	v_add_f32_e32 v92, 1.0, v92
	v_rcp_f32_e32 v92, v92
	v_add_f32_e32 v93, 1.0, v93
	v_rcp_f32_e32 v93, v93
	v_mov_b32_e32 v98, v220
	v_mov_b32_e32 v99, v221
	v_mov_b32_e32 v100, v222
	v_mov_b32_e32 v101, v223
	v_sub_f32_e32 v104, 1.0, v98
	v_fma_f32 v94, v94, v104, v98
	v_cmp_gt_f32_e32 vcc, s25, v94
	s_nop 1
	v_cndmask_b32_e64 v98, 0, 32, vcc
	v_ldexp_f32 v94, v94, v98
	v_log_f32_e32 v94, v94
	s_nop 0
	v_mul_f32_e32 v98, 0x3f317217, v94
	v_fma_f32 v98, v94, s10, -v98
	v_fmac_f32_e32 v98, 0x3377d1cf, v94
	v_fmac_f32_e32 v98, 0x3f317217, v94
	v_cmp_lt_f32_e64 s[38:39], |v94|, s11
	s_nop 1
	v_cndmask_b32_e64 v94, v94, v98, s[38:39]
	v_cndmask_b32_e32 v98, 0, v171, vcc
	v_sub_f32_e32 v94, v94, v98
	v_sub_f32_e32 v98, 1.0, v99
	v_fma_f32 v95, v95, v98, v99
	v_cmp_gt_f32_e32 vcc, s25, v95
	s_nop 1
	v_cndmask_b32_e64 v98, 0, 32, vcc
	v_ldexp_f32 v95, v95, v98
	v_log_f32_e32 v95, v95
	s_nop 0
	v_mul_f32_e32 v98, 0x3f317217, v95
	v_fma_f32 v98, v95, s10, -v98
	v_fmac_f32_e32 v98, 0x3377d1cf, v95
	v_fmac_f32_e32 v98, 0x3f317217, v95
	v_cmp_lt_f32_e64 s[38:39], |v95|, s11
	s_nop 1
	v_cndmask_b32_e64 v95, v95, v98, s[38:39]
	v_cndmask_b32_e32 v98, 0, v171, vcc
	v_sub_f32_e32 v95, v95, v98
	v_sub_f32_e32 v98, 1.0, v100
	v_fma_f32 v96, v96, v98, v100
	v_cmp_gt_f32_e32 vcc, s25, v96
	v_cvt_pk_bf16_f32 v94, v94, v95
	s_nop 0
	v_cndmask_b32_e64 v98, 0, 32, vcc
	v_ldexp_f32 v96, v96, v98
	v_log_f32_e32 v96, v96
	s_nop 0
	v_mul_f32_e32 v98, 0x3f317217, v96
	v_fma_f32 v98, v96, s10, -v98
	v_fmac_f32_e32 v98, 0x3377d1cf, v96
	v_fmac_f32_e32 v98, 0x3f317217, v96
	v_cmp_lt_f32_e64 s[38:39], |v96|, s11
	s_nop 1
	v_cndmask_b32_e64 v96, v96, v98, s[38:39]
	v_cndmask_b32_e32 v98, 0, v171, vcc
	v_sub_f32_e32 v96, v96, v98
	v_sub_f32_e32 v98, 1.0, v101
	v_fmac_f32_e32 v101, v97, v98
	v_cmp_gt_f32_e32 vcc, s25, v101
	s_nop 1
	v_cndmask_b32_e64 v97, 0, 32, vcc
	v_ldexp_f32 v97, v101, v97
	v_log_f32_e32 v97, v97
	s_nop 0
	v_mul_f32_e32 v98, 0x3f317217, v97
	v_fma_f32 v98, v97, s10, -v98
	v_fmac_f32_e32 v98, 0x3377d1cf, v97
	v_fmac_f32_e32 v98, 0x3f317217, v97
	v_cmp_lt_f32_e64 s[38:39], |v97|, s11
	s_nop 1
	v_cndmask_b32_e64 v97, v97, v98, s[38:39]
	v_cndmask_b32_e32 v98, 0, v171, vcc
	v_sub_f32_e32 v97, v97, v98
	v_cvt_pk_bf16_f32 v95, v96, v97
	global_store_dwordx2 v[102:103], v[94:95], off
	v_mov_b32_e32 v94, v224
	v_mov_b32_e32 v95, v225
	v_mov_b32_e32 v96, v226
	v_mov_b32_e32 v97, v227
	v_sub_f32_e32 v98, 1.0, v94
	v_fma_f32 v90, v90, v98, v94
	v_cmp_gt_f32_e32 vcc, s25, v90
	s_nop 1
	v_cndmask_b32_e64 v94, 0, 32, vcc
	v_ldexp_f32 v90, v90, v94
	v_log_f32_e32 v90, v90
	s_nop 0
	v_mul_f32_e32 v94, 0x3f317217, v90
	v_fma_f32 v94, v90, s10, -v94
	v_fmac_f32_e32 v94, 0x3377d1cf, v90
	v_fmac_f32_e32 v94, 0x3f317217, v90
	v_cmp_lt_f32_e64 s[38:39], |v90|, s11
	s_nop 1
	v_cndmask_b32_e64 v90, v90, v94, s[38:39]
	v_cndmask_b32_e32 v94, 0, v171, vcc
	v_sub_f32_e32 v90, v90, v94
	v_sub_f32_e32 v94, 1.0, v95
	v_fma_f32 v91, v91, v94, v95
	v_cmp_gt_f32_e32 vcc, s25, v91
	s_nop 1
	v_cndmask_b32_e64 v94, 0, 32, vcc
	v_ldexp_f32 v91, v91, v94
	v_log_f32_e32 v91, v91
	s_nop 0
	v_mul_f32_e32 v94, 0x3f317217, v91
	v_fma_f32 v94, v91, s10, -v94
	v_fmac_f32_e32 v94, 0x3377d1cf, v91
	v_fmac_f32_e32 v94, 0x3f317217, v91
	v_cmp_lt_f32_e64 s[38:39], |v91|, s11
	s_nop 1
	v_cndmask_b32_e64 v91, v91, v94, s[38:39]
	v_cndmask_b32_e32 v94, 0, v171, vcc
	v_sub_f32_e32 v91, v91, v94
	v_sub_f32_e32 v94, 1.0, v96
	v_fma_f32 v92, v92, v94, v96
	v_cmp_gt_f32_e32 vcc, s25, v92
	s_nop 1
	v_cndmask_b32_e64 v94, 0, 32, vcc
	v_ldexp_f32 v92, v92, v94
	v_log_f32_e32 v92, v92
	s_nop 0
	v_mul_f32_e32 v94, 0x3f317217, v92
	v_fma_f32 v94, v92, s10, -v94
	v_fmac_f32_e32 v94, 0x3377d1cf, v92
	v_fmac_f32_e32 v94, 0x3f317217, v92
	v_cmp_lt_f32_e64 s[38:39], |v92|, s11
	s_nop 1
	v_cndmask_b32_e64 v92, v92, v94, s[38:39]
	v_cndmask_b32_e32 v94, 0, v171, vcc
	v_sub_f32_e32 v92, v92, v94
	v_sub_f32_e32 v94, 1.0, v97
	v_fmac_f32_e32 v97, v93, v94
	v_cmp_gt_f32_e32 vcc, s25, v97
	s_nop 1
	v_cndmask_b32_e64 v93, 0, 32, vcc
	v_ldexp_f32 v93, v97, v93
	v_log_f32_e32 v93, v93
	s_nop 0
	v_mul_f32_e32 v94, 0x3f317217, v93
	v_fma_f32 v94, v93, s10, -v94
	v_fmac_f32_e32 v94, 0x3377d1cf, v93
	v_fmac_f32_e32 v94, 0x3f317217, v93
	v_cmp_lt_f32_e64 s[38:39], |v93|, s11
	s_nop 1
	v_cndmask_b32_e64 v93, v93, v94, s[38:39]
	v_cndmask_b32_e32 v94, 0, v171, vcc
	v_sub_f32_e32 v93, v93, v94

; __device__ __forceinline__ float sigmoidf_(float x) { return __builtin_amdgcn_rcpf(1.f + __expf(-x)); }
; template <int MF>
; __device__ __forceinline__ void gemm_in_tile(const Params& p, int l, char* smem, int mt, int nt) {
;     ...
;         if (nt >= 16 && nt < 32) {
;           float4 lb4 = *(const float4*)(p.lb + l * D + ((col - C_HGF) & 1023));
;           acc[m][n][0] = __logf(lb4.x + (1.f - lb4.x) * sigmoidf_(acc[m][n][0]));
;           acc[m][n][1] = __logf(lb4.y + (1.f - lb4.y) * sigmoidf_(acc[m][n][1]));
;           acc[m][n][2] = __logf(lb4.z + (1.f - lb4.z) * sigmoidf_(acc[m][n][2]));
;           acc[m][n][3] = __logf(lb4.w + (1.f - lb4.w) * sigmoidf_(acc[m][n][3]));
;         }
;         uint2 o; o.x = pack2(acc[m][n][0], acc[m][n][1]); o.y = pack2(acc[m][n][2], acc[m][n][3]);
;         *(uint2*)(dbase + (long)row * dld + col) = o;
.LBB0_222:
	s_andn2_b64 vcc, exec, s[38:39]
	s_cbranch_vccnz .LBB0_224
	v_mul_f32_e32 v86, 0xbfb8aa3b, v86
	v_exp_f32_e32 v86, v86
	v_mul_f32_e32 v87, 0xbfb8aa3b, v87
	v_exp_f32_e32 v87, v87
	s_mov_b32 s10, 0x3f317217
	v_add_f32_e32 v86, 1.0, v86
	v_rcp_f32_e32 v86, v86
	v_add_f32_e32 v87, 1.0, v87
	v_rcp_f32_e32 v87, v87
	v_mul_f32_e32 v88, 0xbfb8aa3b, v88
	v_exp_f32_e32 v88, v88
	v_mul_f32_e32 v89, 0xbfb8aa3b, v89
	v_exp_f32_e32 v89, v89
	v_mul_f32_e32 v82, 0xbfb8aa3b, v82
	v_add_f32_e32 v88, 1.0, v88
	v_rcp_f32_e32 v88, v88
	v_add_f32_e32 v89, 1.0, v89
	v_rcp_f32_e32 v89, v89
	v_exp_f32_e32 v82, v82
	v_mul_f32_e32 v83, 0xbfb8aa3b, v83
	v_exp_f32_e32 v83, v83
	v_mul_f32_e32 v84, 0xbfb8aa3b, v84
	v_add_f32_e32 v82, 1.0, v82
	v_rcp_f32_e32 v82, v82
	v_add_f32_e32 v83, 1.0, v83
	v_rcp_f32_e32 v83, v83
	v_exp_f32_e32 v84, v84
	v_mul_f32_e32 v85, 0xbfb8aa3b, v85
	v_exp_f32_e32 v85, v85
	v_add_f32_e32 v84, 1.0, v84
	v_rcp_f32_e32 v84, v84
	v_add_f32_e32 v85, 1.0, v85
	v_rcp_f32_e32 v85, v85
	v_mov_b32_e32 v90, v228
	v_mov_b32_e32 v91, v229
	v_mov_b32_e32 v92, v230
	v_mov_b32_e32 v93, v231
	v_sub_f32_e32 v94, 1.0, v90
	v_fma_f32 v86, v86, v94, v90
	v_cmp_gt_f32_e32 vcc, s25, v86
	s_nop 1
	v_cndmask_b32_e64 v90, 0, 32, vcc
	v_ldexp_f32 v86, v86, v90
	v_log_f32_e32 v86, v86
	s_nop 0
	v_mul_f32_e32 v90, 0x3f317217, v86
	v_fma_f32 v90, v86, s10, -v90
	v_fmac_f32_e32 v90, 0x3377d1cf, v86
	v_fmac_f32_e32 v90, 0x3f317217, v86
	v_cmp_lt_f32_e64 s[38:39], |v86|, s11
	s_nop 1
	v_cndmask_b32_e64 v86, v86, v90, s[38:39]
	v_cndmask_b32_e32 v90, 0, v171, vcc
	v_sub_f32_e32 v86, v86, v90
	v_sub_f32_e32 v90, 1.0, v91
	v_fma_f32 v87, v87, v90, v91
	v_cmp_gt_f32_e32 vcc, s25, v87
	s_nop 1
	v_cndmask_b32_e64 v90, 0, 32, vcc
	v_ldexp_f32 v87, v87, v90
	v_log_f32_e32 v87, v87
	s_nop 0
	v_mul_f32_e32 v90, 0x3f317217, v87
	v_fma_f32 v90, v87, s10, -v90
	v_fmac_f32_e32 v90, 0x3377d1cf, v87
	v_fmac_f32_e32 v90, 0x3f317217, v87
	v_cmp_lt_f32_e64 s[38:39], |v87|, s11
	s_nop 1
	v_cndmask_b32_e64 v87, v87, v90, s[38:39]
	v_cndmask_b32_e32 v90, 0, v171, vcc
	v_sub_f32_e32 v87, v87, v90
	v_sub_f32_e32 v90, 1.0, v92
	v_fma_f32 v88, v88, v90, v92
	v_cmp_gt_f32_e32 vcc, s25, v88
	v_cvt_pk_bf16_f32 v86, v86, v87
	s_nop 0
	v_cndmask_b32_e64 v90, 0, 32, vcc
	v_ldexp_f32 v88, v88, v90
	v_log_f32_e32 v88, v88
	s_nop 0
	v_mul_f32_e32 v90, 0x3f317217, v88
	v_fma_f32 v90, v88, s10, -v90
	v_fmac_f32_e32 v90, 0x3377d1cf, v88
	v_fmac_f32_e32 v90, 0x3f317217, v88
	v_cmp_lt_f32_e64 s[38:39], |v88|, s11
	s_nop 1
	v_cndmask_b32_e64 v88, v88, v90, s[38:39]
	v_cndmask_b32_e32 v90, 0, v171, vcc
	v_sub_f32_e32 v88, v88, v90
	v_sub_f32_e32 v90, 1.0, v93
	v_fmac_f32_e32 v93, v89, v90
	v_cmp_gt_f32_e32 vcc, s25, v93
	s_nop 1
	v_cndmask_b32_e64 v89, 0, 32, vcc
	v_ldexp_f32 v89, v93, v89
	v_log_f32_e32 v89, v89
	s_nop 0
	v_mul_f32_e32 v90, 0x3f317217, v89
	v_fma_f32 v90, v89, s10, -v90
	v_fmac_f32_e32 v90, 0x3377d1cf, v89
	v_fmac_f32_e32 v90, 0x3f317217, v89
	v_cmp_lt_f32_e64 s[38:39], |v89|, s11
	s_nop 1
	v_cndmask_b32_e64 v89, v89, v90, s[38:39]
	v_cndmask_b32_e32 v90, 0, v171, vcc
	v_sub_f32_e32 v89, v89, v90
	v_cvt_pk_bf16_f32 v87, v88, v89
	global_store_dwordx2 v[102:103], v[86:87], off offset:64
	v_mov_b32_e32 v86, v232
	v_mov_b32_e32 v87, v233
	v_mov_b32_e32 v88, v234
	v_mov_b32_e32 v89, v235
	v_sub_f32_e32 v90, 1.0, v86
	v_fma_f32 v82, v82, v90, v86
	v_cmp_gt_f32_e32 vcc, s25, v82
	s_nop 1
	v_cndmask_b32_e64 v86, 0, 32, vcc
	v_ldexp_f32 v82, v82, v86
	v_log_f32_e32 v82, v82
	s_nop 0
	v_mul_f32_e32 v86, 0x3f317217, v82
	v_fma_f32 v86, v82, s10, -v86
	v_fmac_f32_e32 v86, 0x3377d1cf, v82
	v_fmac_f32_e32 v86, 0x3f317217, v82
	v_cmp_lt_f32_e64 s[38:39], |v82|, s11
	s_nop 1
	v_cndmask_b32_e64 v82, v82, v86, s[38:39]
	v_cndmask_b32_e32 v86, 0, v171, vcc
	v_sub_f32_e32 v82, v82, v86
	v_sub_f32_e32 v86, 1.0, v87
	v_fma_f32 v83, v83, v86, v87
	v_cmp_gt_f32_e32 vcc, s25, v83
	s_nop 1
	v_cndmask_b32_e64 v86, 0, 32, vcc
	v_ldexp_f32 v83, v83, v86
	v_log_f32_e32 v83, v83
	s_nop 0
	v_mul_f32_e32 v86, 0x3f317217, v83
	v_fma_f32 v86, v83, s10, -v86
	v_fmac_f32_e32 v86, 0x3377d1cf, v83
	v_fmac_f32_e32 v86, 0x3f317217, v83
	v_cmp_lt_f32_e64 s[38:39], |v83|, s11
	s_nop 1
	v_cndmask_b32_e64 v83, v83, v86, s[38:39]
	v_cndmask_b32_e32 v86, 0, v171, vcc
	v_sub_f32_e32 v83, v83, v86
	v_sub_f32_e32 v86, 1.0, v88
	v_fma_f32 v84, v84, v86, v88
	v_cmp_gt_f32_e32 vcc, s25, v84
	s_nop 1
	v_cndmask_b32_e64 v86, 0, 32, vcc
	v_ldexp_f32 v84, v84, v86
	v_log_f32_e32 v84, v84
	s_nop 0
	v_mul_f32_e32 v86, 0x3f317217, v84
	v_fma_f32 v86, v84, s10, -v86
	v_fmac_f32_e32 v86, 0x3377d1cf, v84
	v_fmac_f32_e32 v86, 0x3f317217, v84
	v_cmp_lt_f32_e64 s[38:39], |v84|, s11
	s_nop 1
	v_cndmask_b32_e64 v84, v84, v86, s[38:39]
	v_cndmask_b32_e32 v86, 0, v171, vcc
	v_sub_f32_e32 v84, v84, v86
	v_sub_f32_e32 v86, 1.0, v89
	v_fmac_f32_e32 v89, v85, v86
	v_cmp_gt_f32_e32 vcc, s25, v89
	s_nop 1
	v_cndmask_b32_e64 v85, 0, 32, vcc
	v_ldexp_f32 v85, v89, v85
	v_log_f32_e32 v85, v85
	s_nop 0
	v_mul_f32_e32 v86, 0x3f317217, v85
	v_fma_f32 v86, v85, s10, -v86
	v_fmac_f32_e32 v86, 0x3377d1cf, v85
	v_fmac_f32_e32 v86, 0x3f317217, v85
	v_cmp_lt_f32_e64 s[38:39], |v85|, s11
	s_nop 1
	v_cndmask_b32_e64 v85, v85, v86, s[38:39]
	v_cndmask_b32_e32 v86, 0, v171, vcc
	v_sub_f32_e32 v85, v85, v86

; __device__ __forceinline__ float sigmoidf_(float x) { return __builtin_amdgcn_rcpf(1.f + __expf(-x)); }
; template <int MF>
; __device__ __forceinline__ void gemm_in_tile(const Params& p, int l, char* smem, int mt, int nt) {
;     ...
;         if (nt >= 16 && nt < 32) {
;           float4 lb4 = *(const float4*)(p.lb + l * D + ((col - C_HGF) & 1023));
;           acc[m][n][0] = __logf(lb4.x + (1.f - lb4.x) * sigmoidf_(acc[m][n][0]));
;           acc[m][n][1] = __logf(lb4.y + (1.f - lb4.y) * sigmoidf_(acc[m][n][1]));
;           acc[m][n][2] = __logf(lb4.z + (1.f - lb4.z) * sigmoidf_(acc[m][n][2]));
;           acc[m][n][3] = __logf(lb4.w + (1.f - lb4.w) * sigmoidf_(acc[m][n][3]));
;         }
;         uint2 o; o.x = pack2(acc[m][n][0], acc[m][n][1]); o.y = pack2(acc[m][n][2], acc[m][n][3]);
;         *(uint2*)(dbase + (long)row * dld + col) = o;
.LBB0_226:
	s_andn2_b64 vcc, exec, s[38:39]
	s_cbranch_vccnz .LBB0_228
	v_mul_f32_e32 v78, 0xbfb8aa3b, v78
	v_exp_f32_e32 v78, v78
	v_mul_f32_e32 v79, 0xbfb8aa3b, v79
	v_exp_f32_e32 v79, v79
	s_mov_b32 s10, 0x3f317217
	v_add_f32_e32 v78, 1.0, v78
	v_rcp_f32_e32 v78, v78
	v_add_f32_e32 v79, 1.0, v79
	v_rcp_f32_e32 v79, v79
	v_mul_f32_e32 v80, 0xbfb8aa3b, v80
	v_exp_f32_e32 v80, v80
	v_mul_f32_e32 v81, 0xbfb8aa3b, v81
	v_exp_f32_e32 v81, v81
	v_mul_f32_e32 v74, 0xbfb8aa3b, v74
	v_add_f32_e32 v80, 1.0, v80
	v_rcp_f32_e32 v80, v80
	v_add_f32_e32 v81, 1.0, v81
	v_rcp_f32_e32 v81, v81
	v_exp_f32_e32 v74, v74
	v_mul_f32_e32 v75, 0xbfb8aa3b, v75
	v_exp_f32_e32 v75, v75
	v_mul_f32_e32 v76, 0xbfb8aa3b, v76
	v_add_f32_e32 v74, 1.0, v74
	v_rcp_f32_e32 v74, v74
	v_add_f32_e32 v75, 1.0, v75
	v_rcp_f32_e32 v75, v75
	v_exp_f32_e32 v76, v76
	v_mul_f32_e32 v77, 0xbfb8aa3b, v77
	v_exp_f32_e32 v77, v77
	v_add_f32_e32 v76, 1.0, v76
	v_rcp_f32_e32 v76, v76
	v_add_f32_e32 v77, 1.0, v77
	v_rcp_f32_e32 v77, v77
	v_mov_b32_e32 v82, v220
	v_mov_b32_e32 v83, v221
	v_mov_b32_e32 v84, v222
	v_mov_b32_e32 v85, v223
	v_sub_f32_e32 v88, 1.0, v82
	v_fma_f32 v78, v78, v88, v82
	v_cmp_gt_f32_e32 vcc, s25, v78
	s_nop 1
	v_cndmask_b32_e64 v82, 0, 32, vcc
	v_ldexp_f32 v78, v78, v82
	v_log_f32_e32 v78, v78
	s_nop 0
	v_mul_f32_e32 v82, 0x3f317217, v78
	v_fma_f32 v82, v78, s10, -v82
	v_fmac_f32_e32 v82, 0x3377d1cf, v78
	v_fmac_f32_e32 v82, 0x3f317217, v78
	v_cmp_lt_f32_e64 s[38:39], |v78|, s11
	s_nop 1
	v_cndmask_b32_e64 v78, v78, v82, s[38:39]
	v_cndmask_b32_e32 v82, 0, v171, vcc
	v_sub_f32_e32 v78, v78, v82
	v_sub_f32_e32 v82, 1.0, v83
	v_fma_f32 v79, v79, v82, v83
	v_cmp_gt_f32_e32 vcc, s25, v79
	s_nop 1
	v_cndmask_b32_e64 v82, 0, 32, vcc
	v_ldexp_f32 v79, v79, v82
	v_log_f32_e32 v79, v79
	s_nop 0
	v_mul_f32_e32 v82, 0x3f317217, v79
	v_fma_f32 v82, v79, s10, -v82
	v_fmac_f32_e32 v82, 0x3377d1cf, v79
	v_fmac_f32_e32 v82, 0x3f317217, v79
	v_cmp_lt_f32_e64 s[38:39], |v79|, s11
	s_nop 1
	v_cndmask_b32_e64 v79, v79, v82, s[38:39]
	v_cndmask_b32_e32 v82, 0, v171, vcc
	v_sub_f32_e32 v79, v79, v82
	v_sub_f32_e32 v82, 1.0, v84
	v_fma_f32 v80, v80, v82, v84
	v_cmp_gt_f32_e32 vcc, s25, v80
	v_cvt_pk_bf16_f32 v78, v78, v79
	s_nop 0
	v_cndmask_b32_e64 v82, 0, 32, vcc
	v_ldexp_f32 v80, v80, v82
	v_log_f32_e32 v80, v80
	s_nop 0
	v_mul_f32_e32 v82, 0x3f317217, v80
	v_fma_f32 v82, v80, s10, -v82
	v_fmac_f32_e32 v82, 0x3377d1cf, v80
	v_fmac_f32_e32 v82, 0x3f317217, v80
	v_cmp_lt_f32_e64 s[38:39], |v80|, s11
	s_nop 1
	v_cndmask_b32_e64 v80, v80, v82, s[38:39]
	v_cndmask_b32_e32 v82, 0, v171, vcc
	v_sub_f32_e32 v80, v80, v82
	v_sub_f32_e32 v82, 1.0, v85
	v_fmac_f32_e32 v85, v81, v82
	v_cmp_gt_f32_e32 vcc, s25, v85
	s_nop 1
	v_cndmask_b32_e64 v81, 0, 32, vcc
	v_ldexp_f32 v81, v85, v81
	v_log_f32_e32 v81, v81
	s_nop 0
	v_mul_f32_e32 v82, 0x3f317217, v81
	v_fma_f32 v82, v81, s10, -v82
	v_fmac_f32_e32 v82, 0x3377d1cf, v81
	v_fmac_f32_e32 v82, 0x3f317217, v81
	v_cmp_lt_f32_e64 s[38:39], |v81|, s11
	s_nop 1
	v_cndmask_b32_e64 v81, v81, v82, s[38:39]
	v_cndmask_b32_e32 v82, 0, v171, vcc
	v_sub_f32_e32 v81, v81, v82
	v_cvt_pk_bf16_f32 v79, v80, v81
	global_store_dwordx2 v[86:87], v[78:79], off
	v_mov_b32_e32 v78, v224
	v_mov_b32_e32 v79, v225
	v_mov_b32_e32 v80, v226
	v_mov_b32_e32 v81, v227
	v_sub_f32_e32 v82, 1.0, v78
	v_fma_f32 v74, v74, v82, v78
	v_cmp_gt_f32_e32 vcc, s25, v74
	s_nop 1
	v_cndmask_b32_e64 v78, 0, 32, vcc
	v_ldexp_f32 v74, v74, v78
	v_log_f32_e32 v74, v74
	s_nop 0
	v_mul_f32_e32 v78, 0x3f317217, v74
	v_fma_f32 v78, v74, s10, -v78
	v_fmac_f32_e32 v78, 0x3377d1cf, v74
	v_fmac_f32_e32 v78, 0x3f317217, v74
	v_cmp_lt_f32_e64 s[38:39], |v74|, s11
	s_nop 1
	v_cndmask_b32_e64 v74, v74, v78, s[38:39]
	v_cndmask_b32_e32 v78, 0, v171, vcc
	v_sub_f32_e32 v74, v74, v78
	v_sub_f32_e32 v78, 1.0, v79
	v_fma_f32 v75, v75, v78, v79
	v_cmp_gt_f32_e32 vcc, s25, v75
	s_nop 1
	v_cndmask_b32_e64 v78, 0, 32, vcc
	v_ldexp_f32 v75, v75, v78
	v_log_f32_e32 v75, v75
	s_nop 0
	v_mul_f32_e32 v78, 0x3f317217, v75
	v_fma_f32 v78, v75, s10, -v78
	v_fmac_f32_e32 v78, 0x3377d1cf, v75
	v_fmac_f32_e32 v78, 0x3f317217, v75
	v_cmp_lt_f32_e64 s[38:39], |v75|, s11
	s_nop 1
	v_cndmask_b32_e64 v75, v75, v78, s[38:39]
	v_cndmask_b32_e32 v78, 0, v171, vcc
	v_sub_f32_e32 v75, v75, v78
	v_sub_f32_e32 v78, 1.0, v80
	v_fma_f32 v76, v76, v78, v80
	v_cmp_gt_f32_e32 vcc, s25, v76
	s_nop 1
	v_cndmask_b32_e64 v78, 0, 32, vcc
	v_ldexp_f32 v76, v76, v78
	v_log_f32_e32 v76, v76
	s_nop 0
	v_mul_f32_e32 v78, 0x3f317217, v76
	v_fma_f32 v78, v76, s10, -v78
	v_fmac_f32_e32 v78, 0x3377d1cf, v76
	v_fmac_f32_e32 v78, 0x3f317217, v76
	v_cmp_lt_f32_e64 s[38:39], |v76|, s11
	s_nop 1
	v_cndmask_b32_e64 v76, v76, v78, s[38:39]
	v_cndmask_b32_e32 v78, 0, v171, vcc
	v_sub_f32_e32 v76, v76, v78
	v_sub_f32_e32 v78, 1.0, v81
	v_fmac_f32_e32 v81, v77, v78
	v_cmp_gt_f32_e32 vcc, s25, v81
	s_nop 1
	v_cndmask_b32_e64 v77, 0, 32, vcc
	v_ldexp_f32 v77, v81, v77
	v_log_f32_e32 v77, v77
	s_nop 0
	v_mul_f32_e32 v78, 0x3f317217, v77
	v_fma_f32 v78, v77, s10, -v78
	v_fmac_f32_e32 v78, 0x3377d1cf, v77
	v_fmac_f32_e32 v78, 0x3f317217, v77
	v_cmp_lt_f32_e64 s[38:39], |v77|, s11
	s_nop 1
	v_cndmask_b32_e64 v77, v77, v78, s[38:39]
	v_cndmask_b32_e32 v78, 0, v171, vcc
	v_sub_f32_e32 v77, v77, v78

; __device__ __forceinline__ float sigmoidf_(float x) { return __builtin_amdgcn_rcpf(1.f + __expf(-x)); }
; template <int MF>
; __device__ __forceinline__ void gemm_in_tile(const Params& p, int l, char* smem, int mt, int nt) {
;     ...
;         if (nt >= 16 && nt < 32) {
;           float4 lb4 = *(const float4*)(p.lb + l * D + ((col - C_HGF) & 1023));
;           acc[m][n][0] = __logf(lb4.x + (1.f - lb4.x) * sigmoidf_(acc[m][n][0]));
;           acc[m][n][1] = __logf(lb4.y + (1.f - lb4.y) * sigmoidf_(acc[m][n][1]));
;           acc[m][n][2] = __logf(lb4.z + (1.f - lb4.z) * sigmoidf_(acc[m][n][2]));
;           acc[m][n][3] = __logf(lb4.w + (1.f - lb4.w) * sigmoidf_(acc[m][n][3]));
;         }
;         uint2 o; o.x = pack2(acc[m][n][0], acc[m][n][1]); o.y = pack2(acc[m][n][2], acc[m][n][3]);
;         *(uint2*)(dbase + (long)row * dld + col) = o;
.LBB0_230:
	s_andn2_b64 vcc, exec, s[38:39]
	s_cbranch_vccnz .LBB0_232
	v_mul_f32_e32 v70, 0xbfb8aa3b, v70
	v_exp_f32_e32 v70, v70
	v_mul_f32_e32 v71, 0xbfb8aa3b, v71
	v_exp_f32_e32 v71, v71
	s_mov_b32 s10, 0x3f317217
	v_add_f32_e32 v70, 1.0, v70
	v_rcp_f32_e32 v70, v70
	v_add_f32_e32 v71, 1.0, v71
	v_rcp_f32_e32 v71, v71
	v_mul_f32_e32 v72, 0xbfb8aa3b, v72
	v_exp_f32_e32 v72, v72
	v_mul_f32_e32 v73, 0xbfb8aa3b, v73
	v_exp_f32_e32 v73, v73
	v_mul_f32_e32 v66, 0xbfb8aa3b, v66
	v_add_f32_e32 v72, 1.0, v72
	v_rcp_f32_e32 v72, v72
	v_add_f32_e32 v73, 1.0, v73
	v_rcp_f32_e32 v73, v73
	v_exp_f32_e32 v66, v66
	v_mul_f32_e32 v67, 0xbfb8aa3b, v67
	v_exp_f32_e32 v67, v67
	v_mul_f32_e32 v68, 0xbfb8aa3b, v68
	v_add_f32_e32 v66, 1.0, v66
	v_rcp_f32_e32 v66, v66
	v_add_f32_e32 v67, 1.0, v67
	v_rcp_f32_e32 v67, v67
	v_exp_f32_e32 v68, v68
	v_mul_f32_e32 v69, 0xbfb8aa3b, v69
	v_exp_f32_e32 v69, v69
	v_add_f32_e32 v68, 1.0, v68
	v_rcp_f32_e32 v68, v68
	v_add_f32_e32 v69, 1.0, v69
	v_rcp_f32_e32 v69, v69
	v_mov_b32_e32 v74, v228
	v_mov_b32_e32 v75, v229
	v_mov_b32_e32 v76, v230
	v_mov_b32_e32 v77, v231
	v_sub_f32_e32 v78, 1.0, v74
	v_fma_f32 v70, v70, v78, v74
	v_cmp_gt_f32_e32 vcc, s25, v70
	s_nop 1
	v_cndmask_b32_e64 v74, 0, 32, vcc
	v_ldexp_f32 v70, v70, v74
	v_log_f32_e32 v70, v70
	s_nop 0
	v_mul_f32_e32 v74, 0x3f317217, v70
	v_fma_f32 v74, v70, s10, -v74
	v_fmac_f32_e32 v74, 0x3377d1cf, v70
	v_fmac_f32_e32 v74, 0x3f317217, v70
	v_cmp_lt_f32_e64 s[38:39], |v70|, s11
	s_nop 1
	v_cndmask_b32_e64 v70, v70, v74, s[38:39]
	v_cndmask_b32_e32 v74, 0, v171, vcc
	v_sub_f32_e32 v70, v70, v74
	v_sub_f32_e32 v74, 1.0, v75
	v_fma_f32 v71, v71, v74, v75
	v_cmp_gt_f32_e32 vcc, s25, v71
	s_nop 1
	v_cndmask_b32_e64 v74, 0, 32, vcc
	v_ldexp_f32 v71, v71, v74
	v_log_f32_e32 v71, v71
	s_nop 0
	v_mul_f32_e32 v74, 0x3f317217, v71
	v_fma_f32 v74, v71, s10, -v74
	v_fmac_f32_e32 v74, 0x3377d1cf, v71
	v_fmac_f32_e32 v74, 0x3f317217, v71
	v_cmp_lt_f32_e64 s[38:39], |v71|, s11
	s_nop 1
	v_cndmask_b32_e64 v71, v71, v74, s[38:39]
	v_cndmask_b32_e32 v74, 0, v171, vcc
	v_sub_f32_e32 v71, v71, v74
	v_sub_f32_e32 v74, 1.0, v76
	v_fma_f32 v72, v72, v74, v76
	v_cmp_gt_f32_e32 vcc, s25, v72
	v_cvt_pk_bf16_f32 v70, v70, v71
	s_nop 0
	v_cndmask_b32_e64 v74, 0, 32, vcc
	v_ldexp_f32 v72, v72, v74
	v_log_f32_e32 v72, v72
	s_nop 0
	v_mul_f32_e32 v74, 0x3f317217, v72
	v_fma_f32 v74, v72, s10, -v74
	v_fmac_f32_e32 v74, 0x3377d1cf, v72
	v_fmac_f32_e32 v74, 0x3f317217, v72
	v_cmp_lt_f32_e64 s[38:39], |v72|, s11
	s_nop 1
	v_cndmask_b32_e64 v72, v72, v74, s[38:39]
	v_cndmask_b32_e32 v74, 0, v171, vcc
	v_sub_f32_e32 v72, v72, v74
	v_sub_f32_e32 v74, 1.0, v77
	v_fmac_f32_e32 v77, v73, v74
	v_cmp_gt_f32_e32 vcc, s25, v77
	s_nop 1
	v_cndmask_b32_e64 v73, 0, 32, vcc
	v_ldexp_f32 v73, v77, v73
	v_log_f32_e32 v73, v73
	s_nop 0
	v_mul_f32_e32 v74, 0x3f317217, v73
	v_fma_f32 v74, v73, s10, -v74
	v_fmac_f32_e32 v74, 0x3377d1cf, v73
	v_fmac_f32_e32 v74, 0x3f317217, v73
	v_cmp_lt_f32_e64 s[38:39], |v73|, s11
	s_nop 1
	v_cndmask_b32_e64 v73, v73, v74, s[38:39]
	v_cndmask_b32_e32 v74, 0, v171, vcc
	v_sub_f32_e32 v73, v73, v74
	v_cvt_pk_bf16_f32 v71, v72, v73
	global_store_dwordx2 v[86:87], v[70:71], off offset:64
	v_mov_b32_e32 v70, v232
	v_mov_b32_e32 v71, v233
	v_mov_b32_e32 v72, v234
	v_mov_b32_e32 v73, v235
	v_sub_f32_e32 v74, 1.0, v70
	v_fma_f32 v66, v66, v74, v70
	v_cmp_gt_f32_e32 vcc, s25, v66
	s_nop 1
	v_cndmask_b32_e64 v70, 0, 32, vcc
	v_ldexp_f32 v66, v66, v70
	v_log_f32_e32 v66, v66
	s_nop 0
	v_mul_f32_e32 v70, 0x3f317217, v66
	v_fma_f32 v70, v66, s10, -v70
	v_fmac_f32_e32 v70, 0x3377d1cf, v66
	v_fmac_f32_e32 v70, 0x3f317217, v66
	v_cmp_lt_f32_e64 s[38:39], |v66|, s11
	s_nop 1
	v_cndmask_b32_e64 v66, v66, v70, s[38:39]
	v_cndmask_b32_e32 v70, 0, v171, vcc
	v_sub_f32_e32 v66, v66, v70
	v_sub_f32_e32 v70, 1.0, v71
	v_fma_f32 v67, v67, v70, v71
	v_cmp_gt_f32_e32 vcc, s25, v67
	s_nop 1
	v_cndmask_b32_e64 v70, 0, 32, vcc
	v_ldexp_f32 v67, v67, v70
	v_log_f32_e32 v67, v67
	s_nop 0
	v_mul_f32_e32 v70, 0x3f317217, v67
	v_fma_f32 v70, v67, s10, -v70
	v_fmac_f32_e32 v70, 0x3377d1cf, v67
	v_fmac_f32_e32 v70, 0x3f317217, v67
	v_cmp_lt_f32_e64 s[38:39], |v67|, s11
	s_nop 1
	v_cndmask_b32_e64 v67, v67, v70, s[38:39]
	v_cndmask_b32_e32 v70, 0, v171, vcc
	v_sub_f32_e32 v67, v67, v70
	v_sub_f32_e32 v70, 1.0, v72
	v_fma_f32 v68, v68, v70, v72
	v_cmp_gt_f32_e32 vcc, s25, v68
	s_nop 1
	v_cndmask_b32_e64 v70, 0, 32, vcc
	v_ldexp_f32 v68, v68, v70
	v_log_f32_e32 v68, v68
	s_nop 0
	v_mul_f32_e32 v70, 0x3f317217, v68
	v_fma_f32 v70, v68, s10, -v70
	v_fmac_f32_e32 v70, 0x3377d1cf, v68
	v_fmac_f32_e32 v70, 0x3f317217, v68
	v_cmp_lt_f32_e64 s[38:39], |v68|, s11
	s_nop 1
	v_cndmask_b32_e64 v68, v68, v70, s[38:39]
	v_cndmask_b32_e32 v70, 0, v171, vcc
	v_sub_f32_e32 v68, v68, v70
	v_sub_f32_e32 v70, 1.0, v73
	v_fmac_f32_e32 v73, v69, v70
	v_cmp_gt_f32_e32 vcc, s25, v73
	s_nop 1
	v_cndmask_b32_e64 v69, 0, 32, vcc
	v_ldexp_f32 v69, v73, v69
	v_log_f32_e32 v69, v69
	s_nop 0
	v_mul_f32_e32 v70, 0x3f317217, v69
	v_fma_f32 v70, v69, s10, -v70
	v_fmac_f32_e32 v70, 0x3377d1cf, v69
	v_fmac_f32_e32 v70, 0x3f317217, v69
	v_cmp_lt_f32_e64 s[38:39], |v69|, s11
	s_nop 1
	v_cndmask_b32_e64 v69, v69, v70, s[38:39]
	v_cndmask_b32_e32 v70, 0, v171, vcc
	v_sub_f32_e32 v69, v69, v70

; __device__ __forceinline__ float sigmoidf_(float x) { return __builtin_amdgcn_rcpf(1.f + __expf(-x)); }
; template <int MF>
; __device__ __forceinline__ void gemm_in_tile(const Params& p, int l, char* smem, int mt, int nt) {
;     ...
;         if (nt >= 16 && nt < 32) {
;           float4 lb4 = *(const float4*)(p.lb + l * D + ((col - C_HGF) & 1023));
;           acc[m][n][0] = __logf(lb4.x + (1.f - lb4.x) * sigmoidf_(acc[m][n][0]));
;           acc[m][n][1] = __logf(lb4.y + (1.f - lb4.y) * sigmoidf_(acc[m][n][1]));
;           acc[m][n][2] = __logf(lb4.z + (1.f - lb4.z) * sigmoidf_(acc[m][n][2]));
;           acc[m][n][3] = __logf(lb4.w + (1.f - lb4.w) * sigmoidf_(acc[m][n][3]));
;         }
;         uint2 o; o.x = pack2(acc[m][n][0], acc[m][n][1]); o.y = pack2(acc[m][n][2], acc[m][n][3]);
;         *(uint2*)(dbase + (long)row * dld + col) = o;
.LBB0_234:
	s_andn2_b64 vcc, exec, s[38:39]
	s_cbranch_vccnz .LBB0_236
	v_mul_f32_e32 v62, 0xbfb8aa3b, v62
	v_exp_f32_e32 v62, v62
	v_mul_f32_e32 v63, 0xbfb8aa3b, v63
	v_exp_f32_e32 v63, v63
	s_mov_b32 s10, 0x3f317217
	v_add_f32_e32 v62, 1.0, v62
	v_rcp_f32_e32 v62, v62
	v_add_f32_e32 v63, 1.0, v63
	v_rcp_f32_e32 v63, v63
	v_mul_f32_e32 v64, 0xbfb8aa3b, v64
	v_exp_f32_e32 v64, v64
	v_mul_f32_e32 v65, 0xbfb8aa3b, v65
	v_exp_f32_e32 v65, v65
	v_mul_f32_e32 v58, 0xbfb8aa3b, v58
	v_add_f32_e32 v64, 1.0, v64
	v_rcp_f32_e32 v64, v64
	v_add_f32_e32 v65, 1.0, v65
	v_rcp_f32_e32 v65, v65
	v_exp_f32_e32 v58, v58
	v_mul_f32_e32 v59, 0xbfb8aa3b, v59
	v_exp_f32_e32 v59, v59
	v_mul_f32_e32 v60, 0xbfb8aa3b, v60
	v_add_f32_e32 v58, 1.0, v58
	v_rcp_f32_e32 v58, v58
	v_add_f32_e32 v59, 1.0, v59
	v_rcp_f32_e32 v59, v59
	v_exp_f32_e32 v60, v60
	v_mul_f32_e32 v61, 0xbfb8aa3b, v61
	v_exp_f32_e32 v61, v61
	v_add_f32_e32 v60, 1.0, v60
	v_rcp_f32_e32 v60, v60
	v_add_f32_e32 v61, 1.0, v61
	v_rcp_f32_e32 v61, v61
	v_mov_b32_e32 v66, v220
	v_mov_b32_e32 v67, v221
	v_mov_b32_e32 v68, v222
	v_mov_b32_e32 v69, v223
	v_sub_f32_e32 v72, 1.0, v66
	v_fma_f32 v62, v62, v72, v66
	v_cmp_gt_f32_e32 vcc, s25, v62
	s_nop 1
	v_cndmask_b32_e64 v66, 0, 32, vcc
	v_ldexp_f32 v62, v62, v66
	v_log_f32_e32 v62, v62
	s_nop 0
	v_mul_f32_e32 v66, 0x3f317217, v62
	v_fma_f32 v66, v62, s10, -v66
	v_fmac_f32_e32 v66, 0x3377d1cf, v62
	v_fmac_f32_e32 v66, 0x3f317217, v62
	v_cmp_lt_f32_e64 s[38:39], |v62|, s11
	s_nop 1
	v_cndmask_b32_e64 v62, v62, v66, s[38:39]
	v_cndmask_b32_e32 v66, 0, v171, vcc
	v_sub_f32_e32 v62, v62, v66
	v_sub_f32_e32 v66, 1.0, v67
	v_fma_f32 v63, v63, v66, v67
	v_cmp_gt_f32_e32 vcc, s25, v63
	s_nop 1
	v_cndmask_b32_e64 v66, 0, 32, vcc
	v_ldexp_f32 v63, v63, v66
	v_log_f32_e32 v63, v63
	s_nop 0
	v_mul_f32_e32 v66, 0x3f317217, v63
	v_fma_f32 v66, v63, s10, -v66
	v_fmac_f32_e32 v66, 0x3377d1cf, v63
	v_fmac_f32_e32 v66, 0x3f317217, v63
	v_cmp_lt_f32_e64 s[38:39], |v63|, s11
	s_nop 1
	v_cndmask_b32_e64 v63, v63, v66, s[38:39]
	v_cndmask_b32_e32 v66, 0, v171, vcc
	v_sub_f32_e32 v63, v63, v66
	v_sub_f32_e32 v66, 1.0, v68
	v_fma_f32 v64, v64, v66, v68
	v_cmp_gt_f32_e32 vcc, s25, v64
	v_cvt_pk_bf16_f32 v62, v62, v63
	s_nop 0
	v_cndmask_b32_e64 v66, 0, 32, vcc
	v_ldexp_f32 v64, v64, v66
	v_log_f32_e32 v64, v64
	s_nop 0
	v_mul_f32_e32 v66, 0x3f317217, v64
	v_fma_f32 v66, v64, s10, -v66
	v_fmac_f32_e32 v66, 0x3377d1cf, v64
	v_fmac_f32_e32 v66, 0x3f317217, v64
	v_cmp_lt_f32_e64 s[38:39], |v64|, s11
	s_nop 1
	v_cndmask_b32_e64 v64, v64, v66, s[38:39]
	v_cndmask_b32_e32 v66, 0, v171, vcc
	v_sub_f32_e32 v64, v64, v66
	v_sub_f32_e32 v66, 1.0, v69
	v_fmac_f32_e32 v69, v65, v66
	v_cmp_gt_f32_e32 vcc, s25, v69
	s_nop 1
	v_cndmask_b32_e64 v65, 0, 32, vcc
	v_ldexp_f32 v65, v69, v65
	v_log_f32_e32 v65, v65
	s_nop 0
	v_mul_f32_e32 v66, 0x3f317217, v65
	v_fma_f32 v66, v65, s10, -v66
	v_fmac_f32_e32 v66, 0x3377d1cf, v65
	v_fmac_f32_e32 v66, 0x3f317217, v65
	v_cmp_lt_f32_e64 s[38:39], |v65|, s11
	s_nop 1
	v_cndmask_b32_e64 v65, v65, v66, s[38:39]
	v_cndmask_b32_e32 v66, 0, v171, vcc
	v_sub_f32_e32 v65, v65, v66
	v_cvt_pk_bf16_f32 v63, v64, v65
	global_store_dwordx2 v[70:71], v[62:63], off
	v_mov_b32_e32 v62, v224
	v_mov_b32_e32 v63, v225
	v_mov_b32_e32 v64, v226
	v_mov_b32_e32 v65, v227
	v_sub_f32_e32 v66, 1.0, v62
	v_fma_f32 v58, v58, v66, v62
	v_cmp_gt_f32_e32 vcc, s25, v58
	s_nop 1
	v_cndmask_b32_e64 v62, 0, 32, vcc
	v_ldexp_f32 v58, v58, v62
	v_log_f32_e32 v58, v58
	s_nop 0
	v_mul_f32_e32 v62, 0x3f317217, v58
	v_fma_f32 v62, v58, s10, -v62
	v_fmac_f32_e32 v62, 0x3377d1cf, v58
	v_fmac_f32_e32 v62, 0x3f317217, v58
	v_cmp_lt_f32_e64 s[38:39], |v58|, s11
	s_nop 1
	v_cndmask_b32_e64 v58, v58, v62, s[38:39]
	v_cndmask_b32_e32 v62, 0, v171, vcc
	v_sub_f32_e32 v58, v58, v62
	v_sub_f32_e32 v62, 1.0, v63
	v_fma_f32 v59, v59, v62, v63
	v_cmp_gt_f32_e32 vcc, s25, v59
	s_nop 1
	v_cndmask_b32_e64 v62, 0, 32, vcc
	v_ldexp_f32 v59, v59, v62
	v_log_f32_e32 v59, v59
	s_nop 0
	v_mul_f32_e32 v62, 0x3f317217, v59
	v_fma_f32 v62, v59, s10, -v62
	v_fmac_f32_e32 v62, 0x3377d1cf, v59
	v_fmac_f32_e32 v62, 0x3f317217, v59
	v_cmp_lt_f32_e64 s[38:39], |v59|, s11
	s_nop 1
	v_cndmask_b32_e64 v59, v59, v62, s[38:39]
	v_cndmask_b32_e32 v62, 0, v171, vcc
	v_sub_f32_e32 v59, v59, v62
	v_sub_f32_e32 v62, 1.0, v64
	v_fma_f32 v60, v60, v62, v64
	v_cmp_gt_f32_e32 vcc, s25, v60
	s_nop 1
	v_cndmask_b32_e64 v62, 0, 32, vcc
	v_ldexp_f32 v60, v60, v62
	v_log_f32_e32 v60, v60
	s_nop 0
	v_mul_f32_e32 v62, 0x3f317217, v60
	v_fma_f32 v62, v60, s10, -v62
	v_fmac_f32_e32 v62, 0x3377d1cf, v60
	v_fmac_f32_e32 v62, 0x3f317217, v60
	v_cmp_lt_f32_e64 s[38:39], |v60|, s11
	s_nop 1
	v_cndmask_b32_e64 v60, v60, v62, s[38:39]
	v_cndmask_b32_e32 v62, 0, v171, vcc
	v_sub_f32_e32 v60, v60, v62
	v_sub_f32_e32 v62, 1.0, v65
	v_fmac_f32_e32 v65, v61, v62
	v_cmp_gt_f32_e32 vcc, s25, v65
	s_nop 1
	v_cndmask_b32_e64 v61, 0, 32, vcc
	v_ldexp_f32 v61, v65, v61
	v_log_f32_e32 v61, v61
	s_nop 0
	v_mul_f32_e32 v62, 0x3f317217, v61
	v_fma_f32 v62, v61, s10, -v62
	v_fmac_f32_e32 v62, 0x3377d1cf, v61
	v_fmac_f32_e32 v62, 0x3f317217, v61
	v_cmp_lt_f32_e64 s[38:39], |v61|, s11
	s_nop 1
	v_cndmask_b32_e64 v61, v61, v62, s[38:39]
	v_cndmask_b32_e32 v62, 0, v171, vcc
	v_sub_f32_e32 v61, v61, v62

; __device__ __forceinline__ float sigmoidf_(float x) { return __builtin_amdgcn_rcpf(1.f + __expf(-x)); }
; template <int MF>
; __device__ __forceinline__ void gemm_in_tile(const Params& p, int l, char* smem, int mt, int nt) {
;     ...
;         if (nt >= 16 && nt < 32) {
;           float4 lb4 = *(const float4*)(p.lb + l * D + ((col - C_HGF) & 1023));
;           acc[m][n][0] = __logf(lb4.x + (1.f - lb4.x) * sigmoidf_(acc[m][n][0]));
;           acc[m][n][1] = __logf(lb4.y + (1.f - lb4.y) * sigmoidf_(acc[m][n][1]));
;           acc[m][n][2] = __logf(lb4.z + (1.f - lb4.z) * sigmoidf_(acc[m][n][2]));
;           acc[m][n][3] = __logf(lb4.w + (1.f - lb4.w) * sigmoidf_(acc[m][n][3]));
;         }
;         uint2 o; o.x = pack2(acc[m][n][0], acc[m][n][1]); o.y = pack2(acc[m][n][2], acc[m][n][3]);
;         *(uint2*)(dbase + (long)row * dld + col) = o;
.LBB0_238:
	s_andn2_b64 vcc, exec, s[38:39]
	s_cbranch_vccnz .LBB0_240
	v_mul_f32_e32 v54, 0xbfb8aa3b, v54
	v_exp_f32_e32 v54, v54
	v_mul_f32_e32 v55, 0xbfb8aa3b, v55
	v_exp_f32_e32 v55, v55
	s_mov_b32 s10, 0x3f317217
	v_add_f32_e32 v54, 1.0, v54
	v_rcp_f32_e32 v54, v54
	v_add_f32_e32 v55, 1.0, v55
	v_rcp_f32_e32 v55, v55
	v_mul_f32_e32 v56, 0xbfb8aa3b, v56
	v_exp_f32_e32 v56, v56
	v_mul_f32_e32 v57, 0xbfb8aa3b, v57
	v_exp_f32_e32 v57, v57
	v_mul_f32_e32 v50, 0xbfb8aa3b, v50
	v_add_f32_e32 v56, 1.0, v56
	v_rcp_f32_e32 v56, v56
	v_add_f32_e32 v57, 1.0, v57
	v_rcp_f32_e32 v57, v57
	v_exp_f32_e32 v50, v50
	v_mul_f32_e32 v51, 0xbfb8aa3b, v51
	v_exp_f32_e32 v51, v51
	v_mul_f32_e32 v52, 0xbfb8aa3b, v52
	v_add_f32_e32 v50, 1.0, v50
	v_rcp_f32_e32 v50, v50
	v_add_f32_e32 v51, 1.0, v51
	v_rcp_f32_e32 v51, v51
	v_exp_f32_e32 v52, v52
	v_mul_f32_e32 v53, 0xbfb8aa3b, v53
	v_exp_f32_e32 v53, v53
	v_add_f32_e32 v52, 1.0, v52
	v_rcp_f32_e32 v52, v52
	v_add_f32_e32 v53, 1.0, v53
	v_rcp_f32_e32 v53, v53
	v_mov_b32_e32 v58, v228
	v_mov_b32_e32 v59, v229
	v_mov_b32_e32 v60, v230
	v_mov_b32_e32 v61, v231
	v_sub_f32_e32 v62, 1.0, v58
	v_fma_f32 v54, v54, v62, v58
	v_cmp_gt_f32_e32 vcc, s25, v54
	s_nop 1
	v_cndmask_b32_e64 v58, 0, 32, vcc
	v_ldexp_f32 v54, v54, v58
	v_log_f32_e32 v54, v54
	s_nop 0
	v_mul_f32_e32 v58, 0x3f317217, v54
	v_fma_f32 v58, v54, s10, -v58
	v_fmac_f32_e32 v58, 0x3377d1cf, v54
	v_fmac_f32_e32 v58, 0x3f317217, v54
	v_cmp_lt_f32_e64 s[38:39], |v54|, s11
	s_nop 1
	v_cndmask_b32_e64 v54, v54, v58, s[38:39]
	v_cndmask_b32_e32 v58, 0, v171, vcc
	v_sub_f32_e32 v54, v54, v58
	v_sub_f32_e32 v58, 1.0, v59
	v_fma_f32 v55, v55, v58, v59
	v_cmp_gt_f32_e32 vcc, s25, v55
	s_nop 1
	v_cndmask_b32_e64 v58, 0, 32, vcc
	v_ldexp_f32 v55, v55, v58
	v_log_f32_e32 v55, v55
	s_nop 0
	v_mul_f32_e32 v58, 0x3f317217, v55
	v_fma_f32 v58, v55, s10, -v58
	v_fmac_f32_e32 v58, 0x3377d1cf, v55
	v_fmac_f32_e32 v58, 0x3f317217, v55
	v_cmp_lt_f32_e64 s[38:39], |v55|, s11
	s_nop 1
	v_cndmask_b32_e64 v55, v55, v58, s[38:39]
	v_cndmask_b32_e32 v58, 0, v171, vcc
	v_sub_f32_e32 v55, v55, v58
	v_sub_f32_e32 v58, 1.0, v60
	v_fma_f32 v56, v56, v58, v60
	v_cmp_gt_f32_e32 vcc, s25, v56
	v_cvt_pk_bf16_f32 v54, v54, v55
	s_nop 0
	v_cndmask_b32_e64 v58, 0, 32, vcc
	v_ldexp_f32 v56, v56, v58
	v_log_f32_e32 v56, v56
	s_nop 0
	v_mul_f32_e32 v58, 0x3f317217, v56
	v_fma_f32 v58, v56, s10, -v58
	v_fmac_f32_e32 v58, 0x3377d1cf, v56
	v_fmac_f32_e32 v58, 0x3f317217, v56
	v_cmp_lt_f32_e64 s[38:39], |v56|, s11
	s_nop 1
	v_cndmask_b32_e64 v56, v56, v58, s[38:39]
	v_cndmask_b32_e32 v58, 0, v171, vcc
	v_sub_f32_e32 v56, v56, v58
	v_sub_f32_e32 v58, 1.0, v61
	v_fmac_f32_e32 v61, v57, v58
	v_cmp_gt_f32_e32 vcc, s25, v61
	s_nop 1
	v_cndmask_b32_e64 v57, 0, 32, vcc
	v_ldexp_f32 v57, v61, v57
	v_log_f32_e32 v57, v57
	s_nop 0
	v_mul_f32_e32 v58, 0x3f317217, v57
	v_fma_f32 v58, v57, s10, -v58
	v_fmac_f32_e32 v58, 0x3377d1cf, v57
	v_fmac_f32_e32 v58, 0x3f317217, v57
	v_cmp_lt_f32_e64 s[38:39], |v57|, s11
	s_nop 1
	v_cndmask_b32_e64 v57, v57, v58, s[38:39]
	v_cndmask_b32_e32 v58, 0, v171, vcc
	v_sub_f32_e32 v57, v57, v58
	v_cvt_pk_bf16_f32 v55, v56, v57
	global_store_dwordx2 v[70:71], v[54:55], off offset:64
	v_mov_b32_e32 v54, v232
	v_mov_b32_e32 v55, v233
	v_mov_b32_e32 v56, v234
	v_mov_b32_e32 v57, v235
	v_sub_f32_e32 v58, 1.0, v54
	v_fma_f32 v50, v50, v58, v54
	v_cmp_gt_f32_e32 vcc, s25, v50
	s_nop 1
	v_cndmask_b32_e64 v54, 0, 32, vcc
	v_ldexp_f32 v50, v50, v54
	v_log_f32_e32 v50, v50
	s_nop 0
	v_mul_f32_e32 v54, 0x3f317217, v50
	v_fma_f32 v54, v50, s10, -v54
	v_fmac_f32_e32 v54, 0x3377d1cf, v50
	v_fmac_f32_e32 v54, 0x3f317217, v50
	v_cmp_lt_f32_e64 s[38:39], |v50|, s11
	s_nop 1
	v_cndmask_b32_e64 v50, v50, v54, s[38:39]
	v_cndmask_b32_e32 v54, 0, v171, vcc
	v_sub_f32_e32 v50, v50, v54
	v_sub_f32_e32 v54, 1.0, v55
	v_fma_f32 v51, v51, v54, v55
	v_cmp_gt_f32_e32 vcc, s25, v51
	s_nop 1
	v_cndmask_b32_e64 v54, 0, 32, vcc
	v_ldexp_f32 v51, v51, v54
	v_log_f32_e32 v51, v51
	s_nop 0
	v_mul_f32_e32 v54, 0x3f317217, v51
	v_fma_f32 v54, v51, s10, -v54
	v_fmac_f32_e32 v54, 0x3377d1cf, v51
	v_fmac_f32_e32 v54, 0x3f317217, v51
	v_cmp_lt_f32_e64 s[38:39], |v51|, s11
	s_nop 1
	v_cndmask_b32_e64 v51, v51, v54, s[38:39]
	v_cndmask_b32_e32 v54, 0, v171, vcc
	v_sub_f32_e32 v51, v51, v54
	v_sub_f32_e32 v54, 1.0, v56
	v_fma_f32 v52, v52, v54, v56
	v_cmp_gt_f32_e32 vcc, s25, v52
	s_nop 1
	v_cndmask_b32_e64 v54, 0, 32, vcc
	v_ldexp_f32 v52, v52, v54
	v_log_f32_e32 v52, v52
	s_nop 0
	v_mul_f32_e32 v54, 0x3f317217, v52
	v_fma_f32 v54, v52, s10, -v54
	v_fmac_f32_e32 v54, 0x3377d1cf, v52
	v_fmac_f32_e32 v54, 0x3f317217, v52
	v_cmp_lt_f32_e64 s[38:39], |v52|, s11
	s_nop 1
	v_cndmask_b32_e64 v52, v52, v54, s[38:39]
	v_cndmask_b32_e32 v54, 0, v171, vcc
	v_sub_f32_e32 v52, v52, v54
	v_sub_f32_e32 v54, 1.0, v57
	v_fmac_f32_e32 v57, v53, v54
	v_cmp_gt_f32_e32 vcc, s25, v57
	s_nop 1
	v_cndmask_b32_e64 v53, 0, 32, vcc
	v_ldexp_f32 v53, v57, v53
	v_log_f32_e32 v53, v53
	s_nop 0
	v_mul_f32_e32 v54, 0x3f317217, v53
	v_fma_f32 v54, v53, s10, -v54
	v_fmac_f32_e32 v54, 0x3377d1cf, v53
	v_fmac_f32_e32 v54, 0x3f317217, v53
	v_cmp_lt_f32_e64 s[38:39], |v53|, s11
	s_nop 1
	v_cndmask_b32_e64 v53, v53, v54, s[38:39]
	v_cndmask_b32_e32 v54, 0, v171, vcc
	v_sub_f32_e32 v53, v53, v54

; __device__ __forceinline__ float sigmoidf_(float x) { return __builtin_amdgcn_rcpf(1.f + __expf(-x)); }
; template <int MF>
; __device__ __forceinline__ void gemm_in_tile(const Params& p, int l, char* smem, int mt, int nt) {
;     ...
;         if (nt >= 16 && nt < 32) {
;           float4 lb4 = *(const float4*)(p.lb + l * D + ((col - C_HGF) & 1023));
;           acc[m][n][0] = __logf(lb4.x + (1.f - lb4.x) * sigmoidf_(acc[m][n][0]));
;           acc[m][n][1] = __logf(lb4.y + (1.f - lb4.y) * sigmoidf_(acc[m][n][1]));
;           acc[m][n][2] = __logf(lb4.z + (1.f - lb4.z) * sigmoidf_(acc[m][n][2]));
;           acc[m][n][3] = __logf(lb4.w + (1.f - lb4.w) * sigmoidf_(acc[m][n][3]));
;         }
;         uint2 o; o.x = pack2(acc[m][n][0], acc[m][n][1]); o.y = pack2(acc[m][n][2], acc[m][n][3]);
;         *(uint2*)(dbase + (long)row * dld + col) = o;
.LBB0_242:
	s_andn2_b64 vcc, exec, s[38:39]
	s_cbranch_vccnz .LBB0_244
	v_mul_f32_e32 v46, 0xbfb8aa3b, v46
	v_exp_f32_e32 v46, v46
	v_mul_f32_e32 v47, 0xbfb8aa3b, v47
	v_exp_f32_e32 v47, v47
	s_mov_b32 s10, 0x3f317217
	v_add_f32_e32 v46, 1.0, v46
	v_rcp_f32_e32 v46, v46
	v_add_f32_e32 v47, 1.0, v47
	v_rcp_f32_e32 v47, v47
	v_mul_f32_e32 v48, 0xbfb8aa3b, v48
	v_exp_f32_e32 v48, v48
	v_mul_f32_e32 v49, 0xbfb8aa3b, v49
	v_exp_f32_e32 v49, v49
	v_mul_f32_e32 v42, 0xbfb8aa3b, v42
	v_add_f32_e32 v48, 1.0, v48
	v_rcp_f32_e32 v48, v48
	v_add_f32_e32 v49, 1.0, v49
	v_rcp_f32_e32 v49, v49
	v_exp_f32_e32 v42, v42
	v_mul_f32_e32 v43, 0xbfb8aa3b, v43
	v_exp_f32_e32 v43, v43
	v_mul_f32_e32 v44, 0xbfb8aa3b, v44
	v_add_f32_e32 v42, 1.0, v42
	v_rcp_f32_e32 v42, v42
	v_add_f32_e32 v43, 1.0, v43
	v_rcp_f32_e32 v43, v43
	v_exp_f32_e32 v44, v44
	v_mul_f32_e32 v45, 0xbfb8aa3b, v45
	v_exp_f32_e32 v45, v45
	v_add_f32_e32 v44, 1.0, v44
	v_rcp_f32_e32 v44, v44
	v_add_f32_e32 v45, 1.0, v45
	v_rcp_f32_e32 v45, v45
	v_mov_b32_e32 v50, v220
	v_mov_b32_e32 v51, v221
	v_mov_b32_e32 v52, v222
	v_mov_b32_e32 v53, v223
	v_sub_f32_e32 v56, 1.0, v50
	v_fma_f32 v46, v46, v56, v50
	v_cmp_gt_f32_e32 vcc, s25, v46
	s_nop 1
	v_cndmask_b32_e64 v50, 0, 32, vcc
	v_ldexp_f32 v46, v46, v50
	v_log_f32_e32 v46, v46
	s_nop 0
	v_mul_f32_e32 v50, 0x3f317217, v46
	v_fma_f32 v50, v46, s10, -v50
	v_fmac_f32_e32 v50, 0x3377d1cf, v46
	v_fmac_f32_e32 v50, 0x3f317217, v46
	v_cmp_lt_f32_e64 s[38:39], |v46|, s11
	s_nop 1
	v_cndmask_b32_e64 v46, v46, v50, s[38:39]
	v_cndmask_b32_e32 v50, 0, v171, vcc
	v_sub_f32_e32 v46, v46, v50
	v_sub_f32_e32 v50, 1.0, v51
	v_fma_f32 v47, v47, v50, v51
	v_cmp_gt_f32_e32 vcc, s25, v47
	s_nop 1
	v_cndmask_b32_e64 v50, 0, 32, vcc
	v_ldexp_f32 v47, v47, v50
	v_log_f32_e32 v47, v47
	s_nop 0
	v_mul_f32_e32 v50, 0x3f317217, v47
	v_fma_f32 v50, v47, s10, -v50
	v_fmac_f32_e32 v50, 0x3377d1cf, v47
	v_fmac_f32_e32 v50, 0x3f317217, v47
	v_cmp_lt_f32_e64 s[38:39], |v47|, s11
	s_nop 1
	v_cndmask_b32_e64 v47, v47, v50, s[38:39]
	v_cndmask_b32_e32 v50, 0, v171, vcc
	v_sub_f32_e32 v47, v47, v50
	v_sub_f32_e32 v50, 1.0, v52
	v_fma_f32 v48, v48, v50, v52
	v_cmp_gt_f32_e32 vcc, s25, v48
	v_cvt_pk_bf16_f32 v46, v46, v47
	s_nop 0
	v_cndmask_b32_e64 v50, 0, 32, vcc
	v_ldexp_f32 v48, v48, v50
	v_log_f32_e32 v48, v48
	s_nop 0
	v_mul_f32_e32 v50, 0x3f317217, v48
	v_fma_f32 v50, v48, s10, -v50
	v_fmac_f32_e32 v50, 0x3377d1cf, v48
	v_fmac_f32_e32 v50, 0x3f317217, v48
	v_cmp_lt_f32_e64 s[38:39], |v48|, s11
	s_nop 1
	v_cndmask_b32_e64 v48, v48, v50, s[38:39]
	v_cndmask_b32_e32 v50, 0, v171, vcc
	v_sub_f32_e32 v48, v48, v50
	v_sub_f32_e32 v50, 1.0, v53
	v_fmac_f32_e32 v53, v49, v50
	v_cmp_gt_f32_e32 vcc, s25, v53
	s_nop 1
	v_cndmask_b32_e64 v49, 0, 32, vcc
	v_ldexp_f32 v49, v53, v49
	v_log_f32_e32 v49, v49
	s_nop 0
	v_mul_f32_e32 v50, 0x3f317217, v49
	v_fma_f32 v50, v49, s10, -v50
	v_fmac_f32_e32 v50, 0x3377d1cf, v49
	v_fmac_f32_e32 v50, 0x3f317217, v49
	v_cmp_lt_f32_e64 s[38:39], |v49|, s11
	s_nop 1
	v_cndmask_b32_e64 v49, v49, v50, s[38:39]
	v_cndmask_b32_e32 v50, 0, v171, vcc
	v_sub_f32_e32 v49, v49, v50
	v_cvt_pk_bf16_f32 v47, v48, v49
	global_store_dwordx2 v[54:55], v[46:47], off
	v_mov_b32_e32 v46, v224
	v_mov_b32_e32 v47, v225
	v_mov_b32_e32 v48, v226
	v_mov_b32_e32 v49, v227
	v_sub_f32_e32 v50, 1.0, v46
	v_fma_f32 v42, v42, v50, v46
	v_cmp_gt_f32_e32 vcc, s25, v42
	s_nop 1
	v_cndmask_b32_e64 v46, 0, 32, vcc
	v_ldexp_f32 v42, v42, v46
	v_log_f32_e32 v42, v42
	s_nop 0
	v_mul_f32_e32 v46, 0x3f317217, v42
	v_fma_f32 v46, v42, s10, -v46
	v_fmac_f32_e32 v46, 0x3377d1cf, v42
	v_fmac_f32_e32 v46, 0x3f317217, v42
	v_cmp_lt_f32_e64 s[38:39], |v42|, s11
	s_nop 1
	v_cndmask_b32_e64 v42, v42, v46, s[38:39]
	v_cndmask_b32_e32 v46, 0, v171, vcc
	v_sub_f32_e32 v42, v42, v46
	v_sub_f32_e32 v46, 1.0, v47
	v_fma_f32 v43, v43, v46, v47
	v_cmp_gt_f32_e32 vcc, s25, v43
	s_nop 1
	v_cndmask_b32_e64 v46, 0, 32, vcc
	v_ldexp_f32 v43, v43, v46
	v_log_f32_e32 v43, v43
	s_nop 0
	v_mul_f32_e32 v46, 0x3f317217, v43
	v_fma_f32 v46, v43, s10, -v46
	v_fmac_f32_e32 v46, 0x3377d1cf, v43
	v_fmac_f32_e32 v46, 0x3f317217, v43
	v_cmp_lt_f32_e64 s[38:39], |v43|, s11
	s_nop 1
	v_cndmask_b32_e64 v43, v43, v46, s[38:39]
	v_cndmask_b32_e32 v46, 0, v171, vcc
	v_sub_f32_e32 v43, v43, v46
	v_sub_f32_e32 v46, 1.0, v48
	v_fma_f32 v44, v44, v46, v48
	v_cmp_gt_f32_e32 vcc, s25, v44
	s_nop 1
	v_cndmask_b32_e64 v46, 0, 32, vcc
	v_ldexp_f32 v44, v44, v46
	v_log_f32_e32 v44, v44
	s_nop 0
	v_mul_f32_e32 v46, 0x3f317217, v44
	v_fma_f32 v46, v44, s10, -v46
	v_fmac_f32_e32 v46, 0x3377d1cf, v44
	v_fmac_f32_e32 v46, 0x3f317217, v44
	v_cmp_lt_f32_e64 s[38:39], |v44|, s11
	s_nop 1
	v_cndmask_b32_e64 v44, v44, v46, s[38:39]
	v_cndmask_b32_e32 v46, 0, v171, vcc
	v_sub_f32_e32 v44, v44, v46
	v_sub_f32_e32 v46, 1.0, v49
	v_fmac_f32_e32 v49, v45, v46
	v_cmp_gt_f32_e32 vcc, s25, v49
	s_nop 1
	v_cndmask_b32_e64 v45, 0, 32, vcc
	v_ldexp_f32 v45, v49, v45
	v_log_f32_e32 v45, v45
	s_nop 0
	v_mul_f32_e32 v46, 0x3f317217, v45
	v_fma_f32 v46, v45, s10, -v46
	v_fmac_f32_e32 v46, 0x3377d1cf, v45
	v_fmac_f32_e32 v46, 0x3f317217, v45
	v_cmp_lt_f32_e64 s[38:39], |v45|, s11
	s_nop 1
	v_cndmask_b32_e64 v45, v45, v46, s[38:39]
	v_cndmask_b32_e32 v46, 0, v171, vcc
	v_sub_f32_e32 v45, v45, v46

; __device__ __forceinline__ float sigmoidf_(float x) { return __builtin_amdgcn_rcpf(1.f + __expf(-x)); }
; template <int MF>
; __device__ __forceinline__ void gemm_in_tile(const Params& p, int l, char* smem, int mt, int nt) {
;     ...
;         if (nt >= 16 && nt < 32) {
;           float4 lb4 = *(const float4*)(p.lb + l * D + ((col - C_HGF) & 1023));
;           acc[m][n][0] = __logf(lb4.x + (1.f - lb4.x) * sigmoidf_(acc[m][n][0]));
;           acc[m][n][1] = __logf(lb4.y + (1.f - lb4.y) * sigmoidf_(acc[m][n][1]));
;           acc[m][n][2] = __logf(lb4.z + (1.f - lb4.z) * sigmoidf_(acc[m][n][2]));
;           acc[m][n][3] = __logf(lb4.w + (1.f - lb4.w) * sigmoidf_(acc[m][n][3]));
;         }
;         uint2 o; o.x = pack2(acc[m][n][0], acc[m][n][1]); o.y = pack2(acc[m][n][2], acc[m][n][3]);
;         *(uint2*)(dbase + (long)row * dld + col) = o;
.LBB0_246:
	s_andn2_b64 vcc, exec, s[38:39]
	s_cbranch_vccnz .LBB0_248
	v_mul_f32_e32 v38, 0xbfb8aa3b, v38
	v_exp_f32_e32 v38, v38
	v_mul_f32_e32 v39, 0xbfb8aa3b, v39
	v_exp_f32_e32 v39, v39
	s_mov_b32 s10, 0x3f317217
	v_add_f32_e32 v38, 1.0, v38
	v_rcp_f32_e32 v38, v38
	v_add_f32_e32 v39, 1.0, v39
	v_rcp_f32_e32 v39, v39
	v_mul_f32_e32 v40, 0xbfb8aa3b, v40
	v_exp_f32_e32 v40, v40
	v_mul_f32_e32 v41, 0xbfb8aa3b, v41
	v_exp_f32_e32 v41, v41
	v_mul_f32_e32 v34, 0xbfb8aa3b, v34
	v_add_f32_e32 v40, 1.0, v40
	v_rcp_f32_e32 v40, v40
	v_add_f32_e32 v41, 1.0, v41
	v_rcp_f32_e32 v41, v41
	v_exp_f32_e32 v34, v34
	v_mul_f32_e32 v35, 0xbfb8aa3b, v35
	v_exp_f32_e32 v35, v35
	v_mul_f32_e32 v36, 0xbfb8aa3b, v36
	v_add_f32_e32 v34, 1.0, v34
	v_rcp_f32_e32 v34, v34
	v_add_f32_e32 v35, 1.0, v35
	v_rcp_f32_e32 v35, v35
	v_exp_f32_e32 v36, v36
	v_mul_f32_e32 v37, 0xbfb8aa3b, v37
	v_exp_f32_e32 v37, v37
	v_add_f32_e32 v36, 1.0, v36
	v_rcp_f32_e32 v36, v36
	v_add_f32_e32 v37, 1.0, v37
	v_rcp_f32_e32 v37, v37
	v_mov_b32_e32 v42, v228
	v_mov_b32_e32 v43, v229
	v_mov_b32_e32 v44, v230
	v_mov_b32_e32 v45, v231
	v_sub_f32_e32 v46, 1.0, v42
	v_fma_f32 v38, v38, v46, v42
	v_cmp_gt_f32_e32 vcc, s25, v38
	s_nop 1
	v_cndmask_b32_e64 v42, 0, 32, vcc
	v_ldexp_f32 v38, v38, v42
	v_log_f32_e32 v38, v38
	s_nop 0
	v_mul_f32_e32 v42, 0x3f317217, v38
	v_fma_f32 v42, v38, s10, -v42
	v_fmac_f32_e32 v42, 0x3377d1cf, v38
	v_fmac_f32_e32 v42, 0x3f317217, v38
	v_cmp_lt_f32_e64 s[38:39], |v38|, s11
	s_nop 1
	v_cndmask_b32_e64 v38, v38, v42, s[38:39]
	v_cndmask_b32_e32 v42, 0, v171, vcc
	v_sub_f32_e32 v38, v38, v42
	v_sub_f32_e32 v42, 1.0, v43
	v_fma_f32 v39, v39, v42, v43
	v_cmp_gt_f32_e32 vcc, s25, v39
	s_nop 1
	v_cndmask_b32_e64 v42, 0, 32, vcc
	v_ldexp_f32 v39, v39, v42
	v_log_f32_e32 v39, v39
	s_nop 0
	v_mul_f32_e32 v42, 0x3f317217, v39
	v_fma_f32 v42, v39, s10, -v42
	v_fmac_f32_e32 v42, 0x3377d1cf, v39
	v_fmac_f32_e32 v42, 0x3f317217, v39
	v_cmp_lt_f32_e64 s[38:39], |v39|, s11
	s_nop 1
	v_cndmask_b32_e64 v39, v39, v42, s[38:39]
	v_cndmask_b32_e32 v42, 0, v171, vcc
	v_sub_f32_e32 v39, v39, v42
	v_sub_f32_e32 v42, 1.0, v44
	v_fma_f32 v40, v40, v42, v44
	v_cmp_gt_f32_e32 vcc, s25, v40
	v_cvt_pk_bf16_f32 v38, v38, v39
	s_nop 0
	v_cndmask_b32_e64 v42, 0, 32, vcc
	v_ldexp_f32 v40, v40, v42
	v_log_f32_e32 v40, v40
	s_nop 0
	v_mul_f32_e32 v42, 0x3f317217, v40
	v_fma_f32 v42, v40, s10, -v42
	v_fmac_f32_e32 v42, 0x3377d1cf, v40
	v_fmac_f32_e32 v42, 0x3f317217, v40
	v_cmp_lt_f32_e64 s[38:39], |v40|, s11
	s_nop 1
	v_cndmask_b32_e64 v40, v40, v42, s[38:39]
	v_cndmask_b32_e32 v42, 0, v171, vcc
	v_sub_f32_e32 v40, v40, v42
	v_sub_f32_e32 v42, 1.0, v45
	v_fmac_f32_e32 v45, v41, v42
	v_cmp_gt_f32_e32 vcc, s25, v45
	s_nop 1
	v_cndmask_b32_e64 v41, 0, 32, vcc
	v_ldexp_f32 v41, v45, v41
	v_log_f32_e32 v41, v41
	s_nop 0
	v_mul_f32_e32 v42, 0x3f317217, v41
	v_fma_f32 v42, v41, s10, -v42
	v_fmac_f32_e32 v42, 0x3377d1cf, v41
	v_fmac_f32_e32 v42, 0x3f317217, v41
	v_cmp_lt_f32_e64 s[38:39], |v41|, s11
	s_nop 1
	v_cndmask_b32_e64 v41, v41, v42, s[38:39]
	v_cndmask_b32_e32 v42, 0, v171, vcc
	v_sub_f32_e32 v41, v41, v42
	v_cvt_pk_bf16_f32 v39, v40, v41
	global_store_dwordx2 v[54:55], v[38:39], off offset:64
	v_mov_b32_e32 v38, v232
	v_mov_b32_e32 v39, v233
	v_mov_b32_e32 v40, v234
	v_mov_b32_e32 v41, v235
	v_sub_f32_e32 v42, 1.0, v38
	v_fma_f32 v34, v34, v42, v38
	v_cmp_gt_f32_e32 vcc, s25, v34
	s_nop 1
	v_cndmask_b32_e64 v38, 0, 32, vcc
	v_ldexp_f32 v34, v34, v38
	v_log_f32_e32 v34, v34
	s_nop 0
	v_mul_f32_e32 v38, 0x3f317217, v34
	v_fma_f32 v38, v34, s10, -v38
	v_fmac_f32_e32 v38, 0x3377d1cf, v34
	v_fmac_f32_e32 v38, 0x3f317217, v34
	v_cmp_lt_f32_e64 s[38:39], |v34|, s11
	s_nop 1
	v_cndmask_b32_e64 v34, v34, v38, s[38:39]
	v_cndmask_b32_e32 v38, 0, v171, vcc
	v_sub_f32_e32 v34, v34, v38
	v_sub_f32_e32 v38, 1.0, v39
	v_fma_f32 v35, v35, v38, v39
	v_cmp_gt_f32_e32 vcc, s25, v35
	s_nop 1
	v_cndmask_b32_e64 v38, 0, 32, vcc
	v_ldexp_f32 v35, v35, v38
	v_log_f32_e32 v35, v35
	s_nop 0
	v_mul_f32_e32 v38, 0x3f317217, v35
	v_fma_f32 v38, v35, s10, -v38
	v_fmac_f32_e32 v38, 0x3377d1cf, v35
	v_fmac_f32_e32 v38, 0x3f317217, v35
	v_cmp_lt_f32_e64 s[38:39], |v35|, s11
	s_nop 1
	v_cndmask_b32_e64 v35, v35, v38, s[38:39]
	v_cndmask_b32_e32 v38, 0, v171, vcc
	v_sub_f32_e32 v35, v35, v38
	v_sub_f32_e32 v38, 1.0, v40
	v_fma_f32 v36, v36, v38, v40
	v_cmp_gt_f32_e32 vcc, s25, v36
	s_nop 1
	v_cndmask_b32_e64 v38, 0, 32, vcc
	v_ldexp_f32 v36, v36, v38
	v_log_f32_e32 v36, v36
	s_nop 0
	v_mul_f32_e32 v38, 0x3f317217, v36
	v_fma_f32 v38, v36, s10, -v38
	v_fmac_f32_e32 v38, 0x3377d1cf, v36
	v_fmac_f32_e32 v38, 0x3f317217, v36
	v_cmp_lt_f32_e64 s[38:39], |v36|, s11
	s_nop 1
	v_cndmask_b32_e64 v36, v36, v38, s[38:39]
	v_cndmask_b32_e32 v38, 0, v171, vcc
	v_sub_f32_e32 v36, v36, v38
	v_sub_f32_e32 v38, 1.0, v41
	v_fmac_f32_e32 v41, v37, v38
	v_cmp_gt_f32_e32 vcc, s25, v41
	s_nop 1
	v_cndmask_b32_e64 v37, 0, 32, vcc
	v_ldexp_f32 v37, v41, v37
	v_log_f32_e32 v37, v37
	s_nop 0
	v_mul_f32_e32 v38, 0x3f317217, v37
	v_fma_f32 v38, v37, s10, -v38
	v_fmac_f32_e32 v38, 0x3377d1cf, v37
	v_fmac_f32_e32 v38, 0x3f317217, v37
	v_cmp_lt_f32_e64 s[38:39], |v37|, s11
	s_nop 1
	v_cndmask_b32_e64 v37, v37, v38, s[38:39]
	v_cndmask_b32_e32 v38, 0, v171, vcc
	v_sub_f32_e32 v37, v37, v38

; __device__ __forceinline__ float sigmoidf_(float x) { return __builtin_amdgcn_rcpf(1.f + __expf(-x)); }
; template <int MF>
; __device__ __forceinline__ void gemm_in_tile(const Params& p, int l, char* smem, int mt, int nt) {
;     ...
;         if (nt >= 16 && nt < 32) {
;           float4 lb4 = *(const float4*)(p.lb + l * D + ((col - C_HGF) & 1023));
;           acc[m][n][0] = __logf(lb4.x + (1.f - lb4.x) * sigmoidf_(acc[m][n][0]));
;           acc[m][n][1] = __logf(lb4.y + (1.f - lb4.y) * sigmoidf_(acc[m][n][1]));
;           acc[m][n][2] = __logf(lb4.z + (1.f - lb4.z) * sigmoidf_(acc[m][n][2]));
;           acc[m][n][3] = __logf(lb4.w + (1.f - lb4.w) * sigmoidf_(acc[m][n][3]));
;         }
;         uint2 o; o.x = pack2(acc[m][n][0], acc[m][n][1]); o.y = pack2(acc[m][n][2], acc[m][n][3]);
;         *(uint2*)(dbase + (long)row * dld + col) = o;
.LBB0_250:
	s_andn2_b64 vcc, exec, s[38:39]
	s_cbranch_vccnz .LBB0_252
	v_mul_f32_e32 v30, 0xbfb8aa3b, v30
	v_exp_f32_e32 v30, v30
	v_mul_f32_e32 v31, 0xbfb8aa3b, v31
	v_exp_f32_e32 v31, v31
	s_mov_b32 s10, 0x3f317217
	v_add_f32_e32 v30, 1.0, v30
	v_rcp_f32_e32 v30, v30
	v_add_f32_e32 v31, 1.0, v31
	v_rcp_f32_e32 v31, v31
	v_mul_f32_e32 v32, 0xbfb8aa3b, v32
	v_exp_f32_e32 v32, v32
	v_mul_f32_e32 v33, 0xbfb8aa3b, v33
	v_exp_f32_e32 v33, v33
	v_mul_f32_e32 v26, 0xbfb8aa3b, v26
	v_add_f32_e32 v32, 1.0, v32
	v_rcp_f32_e32 v32, v32
	v_add_f32_e32 v33, 1.0, v33
	v_rcp_f32_e32 v33, v33
	v_exp_f32_e32 v26, v26
	v_mul_f32_e32 v27, 0xbfb8aa3b, v27
	v_exp_f32_e32 v27, v27
	v_mul_f32_e32 v28, 0xbfb8aa3b, v28
	v_add_f32_e32 v26, 1.0, v26
	v_rcp_f32_e32 v26, v26
	v_add_f32_e32 v27, 1.0, v27
	v_rcp_f32_e32 v27, v27
	v_exp_f32_e32 v28, v28
	v_mul_f32_e32 v29, 0xbfb8aa3b, v29
	v_exp_f32_e32 v29, v29
	v_add_f32_e32 v28, 1.0, v28
	v_rcp_f32_e32 v28, v28
	v_add_f32_e32 v29, 1.0, v29
	v_rcp_f32_e32 v29, v29
	v_mov_b32_e32 v34, v220
	v_mov_b32_e32 v35, v221
	v_mov_b32_e32 v36, v222
	v_mov_b32_e32 v37, v223
	v_sub_f32_e32 v40, 1.0, v34
	v_fma_f32 v30, v30, v40, v34
	v_cmp_gt_f32_e32 vcc, s25, v30
	s_nop 1
	v_cndmask_b32_e64 v34, 0, 32, vcc
	v_ldexp_f32 v30, v30, v34
	v_log_f32_e32 v30, v30
	s_nop 0
	v_mul_f32_e32 v34, 0x3f317217, v30
	v_fma_f32 v34, v30, s10, -v34
	v_fmac_f32_e32 v34, 0x3377d1cf, v30
	v_fmac_f32_e32 v34, 0x3f317217, v30
	v_cmp_lt_f32_e64 s[38:39], |v30|, s11
	s_nop 1
	v_cndmask_b32_e64 v30, v30, v34, s[38:39]
	v_cndmask_b32_e32 v34, 0, v171, vcc
	v_sub_f32_e32 v30, v30, v34
	v_sub_f32_e32 v34, 1.0, v35
	v_fma_f32 v31, v31, v34, v35
	v_cmp_gt_f32_e32 vcc, s25, v31
	s_nop 1
	v_cndmask_b32_e64 v34, 0, 32, vcc
	v_ldexp_f32 v31, v31, v34
	v_log_f32_e32 v31, v31
	s_nop 0
	v_mul_f32_e32 v34, 0x3f317217, v31
	v_fma_f32 v34, v31, s10, -v34
	v_fmac_f32_e32 v34, 0x3377d1cf, v31
	v_fmac_f32_e32 v34, 0x3f317217, v31
	v_cmp_lt_f32_e64 s[38:39], |v31|, s11
	s_nop 1
	v_cndmask_b32_e64 v31, v31, v34, s[38:39]
	v_cndmask_b32_e32 v34, 0, v171, vcc
	v_sub_f32_e32 v31, v31, v34
	v_sub_f32_e32 v34, 1.0, v36
	v_fma_f32 v32, v32, v34, v36
	v_cmp_gt_f32_e32 vcc, s25, v32
	v_cvt_pk_bf16_f32 v30, v30, v31
	s_nop 0
	v_cndmask_b32_e64 v34, 0, 32, vcc
	v_ldexp_f32 v32, v32, v34
	v_log_f32_e32 v32, v32
	s_nop 0
	v_mul_f32_e32 v34, 0x3f317217, v32
	v_fma_f32 v34, v32, s10, -v34
	v_fmac_f32_e32 v34, 0x3377d1cf, v32
	v_fmac_f32_e32 v34, 0x3f317217, v32
	v_cmp_lt_f32_e64 s[38:39], |v32|, s11
	s_nop 1
	v_cndmask_b32_e64 v32, v32, v34, s[38:39]
	v_cndmask_b32_e32 v34, 0, v171, vcc
	v_sub_f32_e32 v32, v32, v34
	v_sub_f32_e32 v34, 1.0, v37
	v_fmac_f32_e32 v37, v33, v34
	v_cmp_gt_f32_e32 vcc, s25, v37
	s_nop 1
	v_cndmask_b32_e64 v33, 0, 32, vcc
	v_ldexp_f32 v33, v37, v33
	v_log_f32_e32 v33, v33
	s_nop 0
	v_mul_f32_e32 v34, 0x3f317217, v33
	v_fma_f32 v34, v33, s10, -v34
	v_fmac_f32_e32 v34, 0x3377d1cf, v33
	v_fmac_f32_e32 v34, 0x3f317217, v33
	v_cmp_lt_f32_e64 s[38:39], |v33|, s11
	s_nop 1
	v_cndmask_b32_e64 v33, v33, v34, s[38:39]
	v_cndmask_b32_e32 v34, 0, v171, vcc
	v_sub_f32_e32 v33, v33, v34
	v_cvt_pk_bf16_f32 v31, v32, v33
	global_store_dwordx2 v[38:39], v[30:31], off
	v_mov_b32_e32 v30, v224
	v_mov_b32_e32 v31, v225
	v_mov_b32_e32 v32, v226
	v_mov_b32_e32 v33, v227
	v_sub_f32_e32 v34, 1.0, v30
	v_fma_f32 v26, v26, v34, v30
	v_cmp_gt_f32_e32 vcc, s25, v26
	s_nop 1
	v_cndmask_b32_e64 v30, 0, 32, vcc
	v_ldexp_f32 v26, v26, v30
	v_log_f32_e32 v26, v26
	s_nop 0
	v_mul_f32_e32 v30, 0x3f317217, v26
	v_fma_f32 v30, v26, s10, -v30
	v_fmac_f32_e32 v30, 0x3377d1cf, v26
	v_fmac_f32_e32 v30, 0x3f317217, v26
	v_cmp_lt_f32_e64 s[38:39], |v26|, s11
	s_nop 1
	v_cndmask_b32_e64 v26, v26, v30, s[38:39]
	v_cndmask_b32_e32 v30, 0, v171, vcc
	v_sub_f32_e32 v26, v26, v30
	v_sub_f32_e32 v30, 1.0, v31
	v_fma_f32 v27, v27, v30, v31
	v_cmp_gt_f32_e32 vcc, s25, v27
	s_nop 1
	v_cndmask_b32_e64 v30, 0, 32, vcc
	v_ldexp_f32 v27, v27, v30
	v_log_f32_e32 v27, v27
	s_nop 0
	v_mul_f32_e32 v30, 0x3f317217, v27
	v_fma_f32 v30, v27, s10, -v30
	v_fmac_f32_e32 v30, 0x3377d1cf, v27
	v_fmac_f32_e32 v30, 0x3f317217, v27
	v_cmp_lt_f32_e64 s[38:39], |v27|, s11
	s_nop 1
	v_cndmask_b32_e64 v27, v27, v30, s[38:39]
	v_cndmask_b32_e32 v30, 0, v171, vcc
	v_sub_f32_e32 v27, v27, v30
	v_sub_f32_e32 v30, 1.0, v32
	v_fma_f32 v28, v28, v30, v32
	v_cmp_gt_f32_e32 vcc, s25, v28
	s_nop 1
	v_cndmask_b32_e64 v30, 0, 32, vcc
	v_ldexp_f32 v28, v28, v30
	v_log_f32_e32 v28, v28
	s_nop 0
	v_mul_f32_e32 v30, 0x3f317217, v28
	v_fma_f32 v30, v28, s10, -v30
	v_fmac_f32_e32 v30, 0x3377d1cf, v28
	v_fmac_f32_e32 v30, 0x3f317217, v28
	v_cmp_lt_f32_e64 s[38:39], |v28|, s11
	s_nop 1
	v_cndmask_b32_e64 v28, v28, v30, s[38:39]
	v_cndmask_b32_e32 v30, 0, v171, vcc
	v_sub_f32_e32 v28, v28, v30
	v_sub_f32_e32 v30, 1.0, v33
	v_fmac_f32_e32 v33, v29, v30
	v_cmp_gt_f32_e32 vcc, s25, v33
	s_nop 1
	v_cndmask_b32_e64 v29, 0, 32, vcc
	v_ldexp_f32 v29, v33, v29
	v_log_f32_e32 v29, v29
	s_nop 0
	v_mul_f32_e32 v30, 0x3f317217, v29
	v_fma_f32 v30, v29, s10, -v30
	v_fmac_f32_e32 v30, 0x3377d1cf, v29
	v_fmac_f32_e32 v30, 0x3f317217, v29
	v_cmp_lt_f32_e64 s[38:39], |v29|, s11
	s_nop 1
	v_cndmask_b32_e64 v29, v29, v30, s[38:39]
	v_cndmask_b32_e32 v30, 0, v171, vcc
	v_sub_f32_e32 v29, v29, v30

; __device__ __forceinline__ float sigmoidf_(float x) { return __builtin_amdgcn_rcpf(1.f + __expf(-x)); }
; template <int MF>
; __device__ __forceinline__ void gemm_in_tile(const Params& p, int l, char* smem, int mt, int nt) {
;     ...
;         if (nt >= 16 && nt < 32) {
;           float4 lb4 = *(const float4*)(p.lb + l * D + ((col - C_HGF) & 1023));
;           acc[m][n][0] = __logf(lb4.x + (1.f - lb4.x) * sigmoidf_(acc[m][n][0]));
;           acc[m][n][1] = __logf(lb4.y + (1.f - lb4.y) * sigmoidf_(acc[m][n][1]));
;           acc[m][n][2] = __logf(lb4.z + (1.f - lb4.z) * sigmoidf_(acc[m][n][2]));
;           acc[m][n][3] = __logf(lb4.w + (1.f - lb4.w) * sigmoidf_(acc[m][n][3]));
;         }
;         uint2 o; o.x = pack2(acc[m][n][0], acc[m][n][1]); o.y = pack2(acc[m][n][2], acc[m][n][3]);
;         *(uint2*)(dbase + (long)row * dld + col) = o;
.LBB0_254:
	s_andn2_b64 vcc, exec, s[38:39]
	s_cbranch_vccnz .LBB0_256
	v_mul_f32_e32 v22, 0xbfb8aa3b, v22
	v_exp_f32_e32 v22, v22
	v_mul_f32_e32 v23, 0xbfb8aa3b, v23
	v_exp_f32_e32 v23, v23
	s_mov_b32 s10, 0x3f317217
	v_add_f32_e32 v22, 1.0, v22
	v_rcp_f32_e32 v22, v22
	v_add_f32_e32 v23, 1.0, v23
	v_rcp_f32_e32 v23, v23
	v_mul_f32_e32 v24, 0xbfb8aa3b, v24
	v_exp_f32_e32 v24, v24
	v_mul_f32_e32 v25, 0xbfb8aa3b, v25
	v_exp_f32_e32 v25, v25
	v_mul_f32_e32 v18, 0xbfb8aa3b, v18
	v_add_f32_e32 v24, 1.0, v24
	v_rcp_f32_e32 v24, v24
	v_add_f32_e32 v25, 1.0, v25
	v_rcp_f32_e32 v25, v25
	v_exp_f32_e32 v18, v18
	v_mul_f32_e32 v19, 0xbfb8aa3b, v19
	v_exp_f32_e32 v19, v19
	v_mul_f32_e32 v20, 0xbfb8aa3b, v20
	v_add_f32_e32 v18, 1.0, v18
	v_rcp_f32_e32 v18, v18
	v_add_f32_e32 v19, 1.0, v19
	v_rcp_f32_e32 v19, v19
	v_exp_f32_e32 v20, v20
	v_mul_f32_e32 v21, 0xbfb8aa3b, v21
	v_exp_f32_e32 v21, v21
	v_add_f32_e32 v20, 1.0, v20
	v_rcp_f32_e32 v20, v20
	v_add_f32_e32 v21, 1.0, v21
	v_rcp_f32_e32 v21, v21
	v_mov_b32_e32 v26, v228
	v_mov_b32_e32 v27, v229
	v_mov_b32_e32 v28, v230
	v_mov_b32_e32 v29, v231
	v_sub_f32_e32 v30, 1.0, v26
	v_fma_f32 v22, v22, v30, v26
	v_cmp_gt_f32_e32 vcc, s25, v22
	s_nop 1
	v_cndmask_b32_e64 v26, 0, 32, vcc
	v_ldexp_f32 v22, v22, v26
	v_log_f32_e32 v22, v22
	s_nop 0
	v_mul_f32_e32 v26, 0x3f317217, v22
	v_fma_f32 v26, v22, s10, -v26
	v_fmac_f32_e32 v26, 0x3377d1cf, v22
	v_fmac_f32_e32 v26, 0x3f317217, v22
	v_cmp_lt_f32_e64 s[38:39], |v22|, s11
	s_nop 1
	v_cndmask_b32_e64 v22, v22, v26, s[38:39]
	v_cndmask_b32_e32 v26, 0, v171, vcc
	v_sub_f32_e32 v22, v22, v26
	v_sub_f32_e32 v26, 1.0, v27
	v_fma_f32 v23, v23, v26, v27
	v_cmp_gt_f32_e32 vcc, s25, v23
	s_nop 1
	v_cndmask_b32_e64 v26, 0, 32, vcc
	v_ldexp_f32 v23, v23, v26
	v_log_f32_e32 v23, v23
	s_nop 0
	v_mul_f32_e32 v26, 0x3f317217, v23
	v_fma_f32 v26, v23, s10, -v26
	v_fmac_f32_e32 v26, 0x3377d1cf, v23
	v_fmac_f32_e32 v26, 0x3f317217, v23
	v_cmp_lt_f32_e64 s[38:39], |v23|, s11
	s_nop 1
	v_cndmask_b32_e64 v23, v23, v26, s[38:39]
	v_cndmask_b32_e32 v26, 0, v171, vcc
	v_sub_f32_e32 v23, v23, v26
	v_sub_f32_e32 v26, 1.0, v28
	v_fma_f32 v24, v24, v26, v28
	v_cmp_gt_f32_e32 vcc, s25, v24
	v_cvt_pk_bf16_f32 v22, v22, v23
	s_nop 0
	v_cndmask_b32_e64 v26, 0, 32, vcc
	v_ldexp_f32 v24, v24, v26
	v_log_f32_e32 v24, v24
	s_nop 0
	v_mul_f32_e32 v26, 0x3f317217, v24
	v_fma_f32 v26, v24, s10, -v26
	v_fmac_f32_e32 v26, 0x3377d1cf, v24
	v_fmac_f32_e32 v26, 0x3f317217, v24
	v_cmp_lt_f32_e64 s[38:39], |v24|, s11
	s_nop 1
	v_cndmask_b32_e64 v24, v24, v26, s[38:39]
	v_cndmask_b32_e32 v26, 0, v171, vcc
	v_sub_f32_e32 v24, v24, v26
	v_sub_f32_e32 v26, 1.0, v29
	v_fmac_f32_e32 v29, v25, v26
	v_cmp_gt_f32_e32 vcc, s25, v29
	s_nop 1
	v_cndmask_b32_e64 v25, 0, 32, vcc
	v_ldexp_f32 v25, v29, v25
	v_log_f32_e32 v25, v25
	s_nop 0
	v_mul_f32_e32 v26, 0x3f317217, v25
	v_fma_f32 v26, v25, s10, -v26
	v_fmac_f32_e32 v26, 0x3377d1cf, v25
	v_fmac_f32_e32 v26, 0x3f317217, v25
	v_cmp_lt_f32_e64 s[38:39], |v25|, s11
	s_nop 1
	v_cndmask_b32_e64 v25, v25, v26, s[38:39]
	v_cndmask_b32_e32 v26, 0, v171, vcc
	v_sub_f32_e32 v25, v25, v26
	v_cvt_pk_bf16_f32 v23, v24, v25
	global_store_dwordx2 v[38:39], v[22:23], off offset:64
	v_mov_b32_e32 v22, v232
	v_mov_b32_e32 v23, v233
	v_mov_b32_e32 v24, v234
	v_mov_b32_e32 v25, v235
	v_sub_f32_e32 v26, 1.0, v22
	v_fma_f32 v18, v18, v26, v22
	v_cmp_gt_f32_e32 vcc, s25, v18
	s_nop 1
	v_cndmask_b32_e64 v22, 0, 32, vcc
	v_ldexp_f32 v18, v18, v22
	v_log_f32_e32 v18, v18
	s_nop 0
	v_mul_f32_e32 v22, 0x3f317217, v18
	v_fma_f32 v22, v18, s10, -v22
	v_fmac_f32_e32 v22, 0x3377d1cf, v18
	v_fmac_f32_e32 v22, 0x3f317217, v18
	v_cmp_lt_f32_e64 s[38:39], |v18|, s11
	s_nop 1
	v_cndmask_b32_e64 v18, v18, v22, s[38:39]
	v_cndmask_b32_e32 v22, 0, v171, vcc
	v_sub_f32_e32 v18, v18, v22
	v_sub_f32_e32 v22, 1.0, v23
	v_fma_f32 v19, v19, v22, v23
	v_cmp_gt_f32_e32 vcc, s25, v19
	s_nop 1
	v_cndmask_b32_e64 v22, 0, 32, vcc
	v_ldexp_f32 v19, v19, v22
	v_log_f32_e32 v19, v19
	s_nop 0
	v_mul_f32_e32 v22, 0x3f317217, v19
	v_fma_f32 v22, v19, s10, -v22
	v_fmac_f32_e32 v22, 0x3377d1cf, v19
	v_fmac_f32_e32 v22, 0x3f317217, v19
	v_cmp_lt_f32_e64 s[38:39], |v19|, s11
	s_nop 1
	v_cndmask_b32_e64 v19, v19, v22, s[38:39]
	v_cndmask_b32_e32 v22, 0, v171, vcc
	v_sub_f32_e32 v19, v19, v22
	v_sub_f32_e32 v22, 1.0, v24
	v_fma_f32 v20, v20, v22, v24
	v_cmp_gt_f32_e32 vcc, s25, v20
	s_nop 1
	v_cndmask_b32_e64 v22, 0, 32, vcc
	v_ldexp_f32 v20, v20, v22
	v_log_f32_e32 v20, v20
	s_nop 0
	v_mul_f32_e32 v22, 0x3f317217, v20
	v_fma_f32 v22, v20, s10, -v22
	v_fmac_f32_e32 v22, 0x3377d1cf, v20
	v_fmac_f32_e32 v22, 0x3f317217, v20
	v_cmp_lt_f32_e64 s[38:39], |v20|, s11
	s_nop 1
	v_cndmask_b32_e64 v20, v20, v22, s[38:39]
	v_cndmask_b32_e32 v22, 0, v171, vcc
	v_sub_f32_e32 v20, v20, v22
	v_sub_f32_e32 v22, 1.0, v25
	v_fmac_f32_e32 v25, v21, v22
	v_cmp_gt_f32_e32 vcc, s25, v25
	s_nop 1
	v_cndmask_b32_e64 v21, 0, 32, vcc
	v_ldexp_f32 v21, v25, v21
	v_log_f32_e32 v21, v21
	s_nop 0
	v_mul_f32_e32 v22, 0x3f317217, v21
	v_fma_f32 v22, v21, s10, -v22
	v_fmac_f32_e32 v22, 0x3377d1cf, v21
	v_fmac_f32_e32 v22, 0x3f317217, v21
	v_cmp_lt_f32_e64 s[38:39], |v21|, s11
	s_nop 1
	v_cndmask_b32_e64 v21, v21, v22, s[38:39]
	v_cndmask_b32_e32 v22, 0, v171, vcc
	v_sub_f32_e32 v21, v21, v22

; __device__ __forceinline__ float sigmoidf_(float x) { return __builtin_amdgcn_rcpf(1.f + __expf(-x)); }
; template <int MF>
; __device__ __forceinline__ void gemm_in_tile(const Params& p, int l, char* smem, int mt, int nt) {
;     ...
;         if (nt >= 16 && nt < 32) {
;           float4 lb4 = *(const float4*)(p.lb + l * D + ((col - C_HGF) & 1023));
;           acc[m][n][0] = __logf(lb4.x + (1.f - lb4.x) * sigmoidf_(acc[m][n][0]));
;           acc[m][n][1] = __logf(lb4.y + (1.f - lb4.y) * sigmoidf_(acc[m][n][1]));
;           acc[m][n][2] = __logf(lb4.z + (1.f - lb4.z) * sigmoidf_(acc[m][n][2]));
;           acc[m][n][3] = __logf(lb4.w + (1.f - lb4.w) * sigmoidf_(acc[m][n][3]));
;         }
;         uint2 o; o.x = pack2(acc[m][n][0], acc[m][n][1]); o.y = pack2(acc[m][n][2], acc[m][n][3]);
;         *(uint2*)(dbase + (long)row * dld + col) = o;
.LBB0_258:
	s_andn2_b64 vcc, exec, s[38:39]
	s_cbranch_vccnz .LBB0_260
	v_mul_f32_e32 v14, 0xbfb8aa3b, v14
	v_exp_f32_e32 v14, v14
	v_mul_f32_e32 v15, 0xbfb8aa3b, v15
	v_exp_f32_e32 v15, v15
	s_mov_b32 s10, 0x3f317217
	v_add_f32_e32 v14, 1.0, v14
	v_rcp_f32_e32 v14, v14
	v_add_f32_e32 v15, 1.0, v15
	v_rcp_f32_e32 v15, v15
	v_mul_f32_e32 v16, 0xbfb8aa3b, v16
	v_exp_f32_e32 v16, v16
	v_mul_f32_e32 v17, 0xbfb8aa3b, v17
	v_exp_f32_e32 v17, v17
	v_mul_f32_e32 v10, 0xbfb8aa3b, v10
	v_add_f32_e32 v16, 1.0, v16
	v_rcp_f32_e32 v16, v16
	v_add_f32_e32 v17, 1.0, v17
	v_rcp_f32_e32 v17, v17
	v_exp_f32_e32 v10, v10
	v_mul_f32_e32 v11, 0xbfb8aa3b, v11
	v_exp_f32_e32 v11, v11
	v_mul_f32_e32 v12, 0xbfb8aa3b, v12
	v_add_f32_e32 v10, 1.0, v10
	v_rcp_f32_e32 v10, v10
	v_add_f32_e32 v11, 1.0, v11
	v_rcp_f32_e32 v11, v11
	v_exp_f32_e32 v12, v12
	v_mul_f32_e32 v13, 0xbfb8aa3b, v13
	v_exp_f32_e32 v13, v13
	v_add_f32_e32 v12, 1.0, v12
	v_rcp_f32_e32 v12, v12
	v_add_f32_e32 v13, 1.0, v13
	v_rcp_f32_e32 v13, v13
	v_mov_b32_e32 v18, v220
	v_mov_b32_e32 v19, v221
	v_mov_b32_e32 v20, v222
	v_mov_b32_e32 v21, v223
	v_sub_f32_e32 v0, 1.0, v18
	v_fma_f32 v0, v14, v0, v18
	v_cmp_gt_f32_e32 vcc, s25, v0
	s_nop 1
	v_cndmask_b32_e64 v14, 0, 32, vcc
	v_ldexp_f32 v0, v0, v14
	v_log_f32_e32 v0, v0
	s_nop 0
	v_mul_f32_e32 v14, 0x3f317217, v0
	v_fma_f32 v14, v0, s10, -v14
	v_fmac_f32_e32 v14, 0x3377d1cf, v0
	v_fmac_f32_e32 v14, 0x3f317217, v0
	v_cmp_lt_f32_e64 s[38:39], |v0|, s11
	s_nop 1
	v_cndmask_b32_e64 v0, v0, v14, s[38:39]
	v_cndmask_b32_e32 v14, 0, v171, vcc
	v_sub_f32_e32 v0, v0, v14
	v_sub_f32_e32 v14, 1.0, v19
	v_fma_f32 v14, v15, v14, v19
	v_cmp_gt_f32_e32 vcc, s25, v14
	s_nop 1
	v_cndmask_b32_e64 v15, 0, 32, vcc
	v_ldexp_f32 v14, v14, v15
	v_log_f32_e32 v14, v14
	s_nop 0
	v_mul_f32_e32 v15, 0x3f317217, v14
	v_fma_f32 v15, v14, s10, -v15
	v_fmac_f32_e32 v15, 0x3377d1cf, v14
	v_fmac_f32_e32 v15, 0x3f317217, v14
	v_cmp_lt_f32_e64 s[38:39], |v14|, s11
	s_nop 1
	v_cndmask_b32_e64 v14, v14, v15, s[38:39]
	v_cndmask_b32_e32 v15, 0, v171, vcc
	v_sub_f32_e32 v14, v14, v15
	v_sub_f32_e32 v15, 1.0, v20
	v_fma_f32 v15, v16, v15, v20
	v_cmp_gt_f32_e32 vcc, s25, v15
	v_cvt_pk_bf16_f32 v14, v0, v14
	s_nop 0
	v_cndmask_b32_e64 v16, 0, 32, vcc
	v_ldexp_f32 v15, v15, v16
	v_log_f32_e32 v15, v15
	s_nop 0
	v_mul_f32_e32 v16, 0x3f317217, v15
	v_fma_f32 v16, v15, s10, -v16
	v_fmac_f32_e32 v16, 0x3377d1cf, v15
	v_fmac_f32_e32 v16, 0x3f317217, v15
	v_cmp_lt_f32_e64 s[38:39], |v15|, s11
	s_nop 1
	v_cndmask_b32_e64 v15, v15, v16, s[38:39]
	v_cndmask_b32_e32 v16, 0, v171, vcc
	v_sub_f32_e32 v15, v15, v16
	v_sub_f32_e32 v16, 1.0, v21
	v_fmac_f32_e32 v21, v17, v16
	v_cmp_gt_f32_e32 vcc, s25, v21
	s_nop 1
	v_cndmask_b32_e64 v16, 0, 32, vcc
	v_ldexp_f32 v16, v21, v16
	v_log_f32_e32 v16, v16
	s_nop 0
	v_mul_f32_e32 v17, 0x3f317217, v16
	v_fma_f32 v17, v16, s10, -v17
	v_fmac_f32_e32 v17, 0x3377d1cf, v16
	v_fmac_f32_e32 v17, 0x3f317217, v16
	v_cmp_lt_f32_e64 s[38:39], |v16|, s11
	s_nop 1
	v_cndmask_b32_e64 v16, v16, v17, s[38:39]
	v_cndmask_b32_e32 v17, 0, v171, vcc
	v_sub_f32_e32 v16, v16, v17
	v_cvt_pk_bf16_f32 v15, v15, v16
	global_store_dwordx2 v[22:23], v[14:15], off
	v_mov_b32_e32 v14, v224
	v_mov_b32_e32 v15, v225
	v_mov_b32_e32 v16, v226
	v_mov_b32_e32 v17, v227
	v_sub_f32_e32 v0, 1.0, v14
	v_fma_f32 v0, v10, v0, v14
	v_cmp_gt_f32_e32 vcc, s25, v0
	s_nop 1
	v_cndmask_b32_e64 v10, 0, 32, vcc
	v_ldexp_f32 v0, v0, v10
	v_log_f32_e32 v0, v0
	s_nop 0
	v_mul_f32_e32 v10, 0x3f317217, v0
	v_fma_f32 v10, v0, s10, -v10
	v_fmac_f32_e32 v10, 0x3377d1cf, v0
	v_fmac_f32_e32 v10, 0x3f317217, v0
	v_cmp_lt_f32_e64 s[38:39], |v0|, s11
	s_nop 1
	v_cndmask_b32_e64 v0, v0, v10, s[38:39]
	v_cndmask_b32_e32 v10, 0, v171, vcc
	v_sub_f32_e32 v10, v0, v10
	v_sub_f32_e32 v0, 1.0, v15
	v_fma_f32 v0, v11, v0, v15
	v_cmp_gt_f32_e32 vcc, s25, v0
	s_nop 1
	v_cndmask_b32_e64 v11, 0, 32, vcc
	v_ldexp_f32 v0, v0, v11
	v_log_f32_e32 v0, v0
	s_nop 0
	v_mul_f32_e32 v11, 0x3f317217, v0
	v_fma_f32 v11, v0, s10, -v11
	v_fmac_f32_e32 v11, 0x3377d1cf, v0
	v_fmac_f32_e32 v11, 0x3f317217, v0
	v_cmp_lt_f32_e64 s[38:39], |v0|, s11
	s_nop 1
	v_cndmask_b32_e64 v0, v0, v11, s[38:39]
	v_cndmask_b32_e32 v11, 0, v171, vcc
	v_sub_f32_e32 v11, v0, v11
	v_sub_f32_e32 v0, 1.0, v16
	v_fma_f32 v0, v12, v0, v16
	v_cmp_gt_f32_e32 vcc, s25, v0
	s_nop 1
	v_cndmask_b32_e64 v12, 0, 32, vcc
	v_ldexp_f32 v0, v0, v12
	v_log_f32_e32 v0, v0
	s_nop 0
	v_mul_f32_e32 v12, 0x3f317217, v0
	v_fma_f32 v12, v0, s10, -v12
	v_fmac_f32_e32 v12, 0x3377d1cf, v0
	v_fmac_f32_e32 v12, 0x3f317217, v0
	v_cmp_lt_f32_e64 s[38:39], |v0|, s11
	s_nop 1
	v_cndmask_b32_e64 v0, v0, v12, s[38:39]
	v_cndmask_b32_e32 v12, 0, v171, vcc
	v_sub_f32_e32 v12, v0, v12
	v_sub_f32_e32 v0, 1.0, v17
	v_fmac_f32_e32 v17, v13, v0
	v_cmp_gt_f32_e32 vcc, s25, v17
	s_nop 1
	v_cndmask_b32_e64 v0, 0, 32, vcc
	v_ldexp_f32 v0, v17, v0
	v_log_f32_e32 v0, v0
	s_nop 0
	v_mul_f32_e32 v13, 0x3f317217, v0
	v_fma_f32 v13, v0, s10, -v13
	v_fmac_f32_e32 v13, 0x3377d1cf, v0
	v_fmac_f32_e32 v13, 0x3f317217, v0
	v_cmp_lt_f32_e64 s[38:39], |v0|, s11
	s_nop 1
	v_cndmask_b32_e64 v0, v0, v13, s[38:39]
	v_cndmask_b32_e32 v13, 0, v171, vcc
	v_sub_f32_e32 v13, v0, v13

; __device__ __forceinline__ float sigmoidf_(float x) { return __builtin_amdgcn_rcpf(1.f + __expf(-x)); }
; template <int MF>
; __device__ __forceinline__ void gemm_in_tile(const Params& p, int l, char* smem, int mt, int nt) {
;     ...
;         if (nt >= 16 && nt < 32) {
;           float4 lb4 = *(const float4*)(p.lb + l * D + ((col - C_HGF) & 1023));
;           acc[m][n][0] = __logf(lb4.x + (1.f - lb4.x) * sigmoidf_(acc[m][n][0]));
;           acc[m][n][1] = __logf(lb4.y + (1.f - lb4.y) * sigmoidf_(acc[m][n][1]));
;           acc[m][n][2] = __logf(lb4.z + (1.f - lb4.z) * sigmoidf_(acc[m][n][2]));
;           acc[m][n][3] = __logf(lb4.w + (1.f - lb4.w) * sigmoidf_(acc[m][n][3]));
;         }
;         uint2 o; o.x = pack2(acc[m][n][0], acc[m][n][1]); o.y = pack2(acc[m][n][2], acc[m][n][3]);
;         *(uint2*)(dbase + (long)row * dld + col) = o;
.LBB0_262:
	s_andn2_b64 vcc, exec, s[38:39]
	s_cbranch_vccnz .LBB0_178
	v_mul_f32_e32 v6, 0xbfb8aa3b, v6
	v_exp_f32_e32 v6, v6
	v_mul_f32_e32 v7, 0xbfb8aa3b, v7
	v_exp_f32_e32 v7, v7
	s_mov_b32 s10, 0x3f317217
	v_add_f32_e32 v6, 1.0, v6
	v_rcp_f32_e32 v6, v6
	v_add_f32_e32 v7, 1.0, v7
	v_rcp_f32_e32 v7, v7
	v_mul_f32_e32 v8, 0xbfb8aa3b, v8
	v_exp_f32_e32 v8, v8
	v_mul_f32_e32 v9, 0xbfb8aa3b, v9
	v_exp_f32_e32 v9, v9
	v_mul_f32_e32 v2, 0xbfb8aa3b, v2
	v_add_f32_e32 v8, 1.0, v8
	v_rcp_f32_e32 v8, v8
	v_add_f32_e32 v9, 1.0, v9
	v_rcp_f32_e32 v9, v9
	v_exp_f32_e32 v2, v2
	v_mul_f32_e32 v3, 0xbfb8aa3b, v3
	v_exp_f32_e32 v3, v3
	v_mul_f32_e32 v4, 0xbfb8aa3b, v4
	v_add_f32_e32 v2, 1.0, v2
	v_rcp_f32_e32 v2, v2
	v_add_f32_e32 v3, 1.0, v3
	v_rcp_f32_e32 v3, v3
	v_exp_f32_e32 v4, v4
	v_mul_f32_e32 v5, 0xbfb8aa3b, v5
	v_exp_f32_e32 v5, v5
	v_add_f32_e32 v4, 1.0, v4
	v_rcp_f32_e32 v4, v4
	v_add_f32_e32 v5, 1.0, v5
	v_rcp_f32_e32 v5, v5
	v_mov_b32_e32 v10, v228
	v_mov_b32_e32 v11, v229
	v_mov_b32_e32 v12, v230
	v_mov_b32_e32 v13, v231
	v_sub_f32_e32 v0, 1.0, v10
	v_fma_f32 v0, v6, v0, v10
	v_cmp_gt_f32_e32 vcc, s25, v0
	s_nop 1
	v_cndmask_b32_e64 v6, 0, 32, vcc
	v_ldexp_f32 v0, v0, v6
	v_log_f32_e32 v0, v0
	s_nop 0
	v_mul_f32_e32 v6, 0x3f317217, v0
	v_fma_f32 v6, v0, s10, -v6
	v_fmac_f32_e32 v6, 0x3377d1cf, v0
	v_fmac_f32_e32 v6, 0x3f317217, v0
	v_cmp_lt_f32_e64 s[38:39], |v0|, s11
	s_nop 1
	v_cndmask_b32_e64 v0, v0, v6, s[38:39]
	v_cndmask_b32_e32 v6, 0, v171, vcc
	v_sub_f32_e32 v0, v0, v6
	v_sub_f32_e32 v6, 1.0, v11
	v_fma_f32 v6, v7, v6, v11
	v_cmp_gt_f32_e32 vcc, s25, v6
	s_nop 1
	v_cndmask_b32_e64 v7, 0, 32, vcc
	v_ldexp_f32 v6, v6, v7
	v_log_f32_e32 v6, v6
	s_nop 0
	v_mul_f32_e32 v7, 0x3f317217, v6
	v_fma_f32 v7, v6, s10, -v7
	v_fmac_f32_e32 v7, 0x3377d1cf, v6
	v_fmac_f32_e32 v7, 0x3f317217, v6
	v_cmp_lt_f32_e64 s[38:39], |v6|, s11
	s_nop 1
	v_cndmask_b32_e64 v6, v6, v7, s[38:39]
	v_cndmask_b32_e32 v7, 0, v171, vcc
	v_sub_f32_e32 v6, v6, v7
	v_sub_f32_e32 v7, 1.0, v12
	v_fma_f32 v7, v8, v7, v12
	v_cmp_gt_f32_e32 vcc, s25, v7
	v_cvt_pk_bf16_f32 v6, v0, v6
	s_nop 0
	v_cndmask_b32_e64 v8, 0, 32, vcc
	v_ldexp_f32 v7, v7, v8
	v_log_f32_e32 v7, v7
	s_nop 0
	v_mul_f32_e32 v8, 0x3f317217, v7
	v_fma_f32 v8, v7, s10, -v8
	v_fmac_f32_e32 v8, 0x3377d1cf, v7
	v_fmac_f32_e32 v8, 0x3f317217, v7
	v_cmp_lt_f32_e64 s[38:39], |v7|, s11
	s_nop 1
	v_cndmask_b32_e64 v7, v7, v8, s[38:39]
	v_cndmask_b32_e32 v8, 0, v171, vcc
	v_sub_f32_e32 v7, v7, v8
	v_sub_f32_e32 v8, 1.0, v13
	v_fmac_f32_e32 v13, v9, v8
	v_cmp_gt_f32_e32 vcc, s25, v13
	s_nop 1
	v_cndmask_b32_e64 v8, 0, 32, vcc
	v_ldexp_f32 v8, v13, v8
	v_log_f32_e32 v8, v8
	s_nop 0
	v_mul_f32_e32 v9, 0x3f317217, v8
	v_fma_f32 v9, v8, s10, -v9
	v_fmac_f32_e32 v9, 0x3377d1cf, v8
	v_fmac_f32_e32 v9, 0x3f317217, v8
	v_cmp_lt_f32_e64 s[38:39], |v8|, s11
	s_nop 1
	v_cndmask_b32_e64 v8, v8, v9, s[38:39]
	v_cndmask_b32_e32 v9, 0, v171, vcc
	v_sub_f32_e32 v8, v8, v9
	v_cvt_pk_bf16_f32 v7, v7, v8
	global_store_dwordx2 v[22:23], v[6:7], off offset:64
	v_mov_b32_e32 v6, v232
	v_mov_b32_e32 v7, v233
	v_mov_b32_e32 v8, v234
	v_mov_b32_e32 v9, v235
	v_sub_f32_e32 v0, 1.0, v6
	v_fma_f32 v0, v2, v0, v6
	v_cmp_gt_f32_e32 vcc, s25, v0
	s_nop 1
	v_cndmask_b32_e64 v2, 0, 32, vcc
	v_ldexp_f32 v0, v0, v2
	v_log_f32_e32 v0, v0
	s_nop 0
	v_mul_f32_e32 v2, 0x3f317217, v0
	v_fma_f32 v2, v0, s10, -v2
	v_fmac_f32_e32 v2, 0x3377d1cf, v0
	v_fmac_f32_e32 v2, 0x3f317217, v0
	v_cmp_lt_f32_e64 s[38:39], |v0|, s11
	s_nop 1
	v_cndmask_b32_e64 v0, v0, v2, s[38:39]
	v_cndmask_b32_e32 v2, 0, v171, vcc
	v_sub_f32_e32 v2, v0, v2
	v_sub_f32_e32 v0, 1.0, v7
	v_fma_f32 v0, v3, v0, v7
	v_cmp_gt_f32_e32 vcc, s25, v0
	s_nop 1
	v_cndmask_b32_e64 v3, 0, 32, vcc
	v_ldexp_f32 v0, v0, v3
	v_log_f32_e32 v0, v0
	s_nop 0
	v_mul_f32_e32 v3, 0x3f317217, v0
	v_fma_f32 v3, v0, s10, -v3
	v_fmac_f32_e32 v3, 0x3377d1cf, v0
	v_fmac_f32_e32 v3, 0x3f317217, v0
	v_cmp_lt_f32_e64 s[38:39], |v0|, s11
	s_nop 1
	v_cndmask_b32_e64 v0, v0, v3, s[38:39]
	v_cndmask_b32_e32 v3, 0, v171, vcc
	v_sub_f32_e32 v3, v0, v3
	v_sub_f32_e32 v0, 1.0, v8
	v_fma_f32 v0, v4, v0, v8
	v_cmp_gt_f32_e32 vcc, s25, v0
	s_nop 1
	v_cndmask_b32_e64 v4, 0, 32, vcc
	v_ldexp_f32 v0, v0, v4
	v_log_f32_e32 v0, v0
	s_nop 0
	v_mul_f32_e32 v4, 0x3f317217, v0
	v_fma_f32 v4, v0, s10, -v4
	v_fmac_f32_e32 v4, 0x3377d1cf, v0
	v_fmac_f32_e32 v4, 0x3f317217, v0
	v_cmp_lt_f32_e64 s[38:39], |v0|, s11
	s_nop 1
	v_cndmask_b32_e64 v0, v0, v4, s[38:39]
	v_cndmask_b32_e32 v4, 0, v171, vcc
	v_sub_f32_e32 v4, v0, v4
	v_sub_f32_e32 v0, 1.0, v9
	v_fmac_f32_e32 v9, v5, v0
	v_cmp_gt_f32_e32 vcc, s25, v9
	s_nop 1
	v_cndmask_b32_e64 v0, 0, 32, vcc
	v_ldexp_f32 v0, v9, v0
	v_log_f32_e32 v0, v0
	s_nop 0
	v_mul_f32_e32 v5, 0x3f317217, v0
	v_fma_f32 v5, v0, s10, -v5
	v_fmac_f32_e32 v5, 0x3377d1cf, v0
	v_fmac_f32_e32 v5, 0x3f317217, v0
	v_cmp_lt_f32_e64 s[38:39], |v0|, s11
	s_nop 1
	v_cndmask_b32_e64 v0, v0, v5, s[38:39]
	v_cndmask_b32_e32 v5, 0, v171, vcc
	v_sub_f32_e32 v5, v0, v5
	s_branch .LBB0_178

; __device__ void scan_unit_mma(const Params& p, int l, int g, int u, CSmem& sm) {
;     ...
;   const int mixer = u / 128, r = u % 128;
;   int bl, h, dir, vs;
;   bl = r / 32;
;   if (mixer < 2) { h = (r % 32) / 4; dir = (r % 4) / 2; vs = r % 2; }
;   else { h = (r % 32) / 8; dir = (r % 8) / 4; vs = r % 4; }
.LBB0_612:
	s_ashr_i32 s38, s70, 31
	s_lshr_b32 s38, s38, 25
	s_add_i32 s38, s70, s38
	s_and_b32 s38, s38, 0xffffff80
	s_sub_i32 s40, s70, s38
	s_cmpk_gt_i32 s70, 0xff
	s_cbranch_scc1 .Lperm_ml
	s_and_b32 s38, s40, 31
	s_lshl_b32 s38, s38, 2
	s_lshr_b32 s40, s40, 5
	s_or_b32 s40, s40, s38
	s_branch .Lperm_done
.Lperm_ml:
	s_and_b32 s38, s40, 15
	s_lshl_b32 s38, s38, 3
	s_lshr_b32 s40, s40, 4
	s_or_b32 s40, s40, s38
.Lperm_done:
	v_mov_b32_e32 v2, v156
	s_cmpk_gt_i32 s70, 0xff
	s_mov_b64 s[38:39], -1
	s_cbranch_scc0 .LBB0_614
	s_bfe_u32 s41, s40, 0x20003
	s_bfe_u32 s43, s40, 0x10002
	s_and_b32 s48, s40, 3
	s_mov_b64 s[38:39], 0

; __device__ void ph_gemm_merge(const Params& p, int l, char* smem) {
;   for (int t = blockIdx.x; t < 72 * 8; t += gridDim.x) {
;     int nt = t / 72, mt = t % 72;
;     if (l == 1 && (mt % 18) < 2) continue;
.LBB0_995:
	v_readlane_b32 s12, v240, 2
	v_readlane_b32 s13, v240, 3
	v_readlane_b32 s40, v242, 3
	s_and_b64 vcc, exec, s[12:13]
	s_cbranch_vccz .Lmg_l0
	s_cmpk_lg_i32 s40, 0x200
	s_cbranch_scc1 .Lmg_l0
	s_cmpk_lt_i32 s65, 0x200
	s_cbranch_scc0 .LBB0_1001
	s_lshr_b32 s40, s65, 6
	s_and_b32 s42, s65, 63
	s_lshr_b32 s41, s42, 4
	s_mul_i32 s41, s41, 18
	s_and_b32 s42, s42, 15
	s_add_i32 s42, s42, s41
	s_add_i32 s42, s42, 2
	s_branch .Lmg_tile

; __device__ void ph_gemm_merge(const Params& p, int l, char* smem) {
;     ...
;     f32x4 tot[4][4];
; #pragma unroll
;     for (int m = 0; m < 4; ++m)
; #pragma unroll
;       for (int n = 0; n < 4; ++n) tot[m][n] = f32x4{0.f, 0.f, 0.f, 0.f};
;     for (int i = 0; i < 3; ++i) {
;       f32x4 acc[4][4];
; #pragma unroll
;       for (int m = 0; m < 4; ++m)
; #pragma unroll
;         for (int n = 0; n < 4; ++n) acc[m][n] = f32x4{0.f, 0.f, 0.f, 0.f};
;       gemm_kloopT<4, 4>(p.obuf + (long)mt * 128 * 3072 + i * 1024, 3072, 32, p.WbrT + (long)i * D * D + (long)nt * 128 * 32, 32, (long)D * 32, D, smem, acc);
.Lmg_tile:
	s_mul_i32 s44, s42, 0x60000
	s_ashr_i32 s45, s44, 31
	s_ashr_i32 s41, s40, 31
	s_lshl_b64 s[58:59], s[40:41], 13
	s_lshl_b32 s67, s42, 7
	s_lshl_b32 s66, s40, 7
	s_lshl_b64 s[62:63], s[44:45], 1
	s_add_u32 s68, s88, s62
	s_addc_u32 s69, s89, s63
	s_add_u32 s70, s80, s58
	s_addc_u32 s71, s81, s59
	v_readlane_b32 s12, v241, 35
	s_add_u32 s40, s12, s58
	v_readlane_b32 s12, v241, 36
	s_addc_u32 s41, s12, s59
	v_readlane_b32 s12, v241, 37
	s_add_u32 s42, s12, s58
	v_readlane_b32 s12, v241, 38
	s_addc_u32 s43, s12, s59
	v_readlane_b32 s12, v241, 39
	s_add_u32 s44, s12, s62
	v_readlane_b32 s12, v241, 40
	s_addc_u32 s45, s12, s63
	v_readlane_b32 s12, v241, 41
	s_add_u32 s46, s12, s62
	v_readlane_b32 s12, v241, 42
	s_addc_u32 s47, s12, s63
	v_readlane_b32 s12, v241, 43
	s_add_u32 s48, s12, s58
	v_readlane_b32 s12, v241, 44
	s_addc_u32 s49, s12, s59
	v_readlane_b32 s12, v241, 45
	s_add_u32 s50, s12, s58
	v_readlane_b32 s12, v241, 46
	s_addc_u32 s51, s12, s59
	v_readlane_b32 s12, v241, 47
	s_add_u32 s52, s12, s62
	v_readlane_b32 s12, v241, 48
	s_addc_u32 s53, s12, s63
	v_readlane_b32 s12, v241, 49
	s_add_u32 s54, s12, s62
	v_readlane_b32 s12, v241, 50
	s_addc_u32 s55, s12, s63
	v_readlane_b32 s12, v241, 51
	s_add_u32 s56, s12, s58
	v_readlane_b32 s12, v241, 52
	s_addc_u32 s57, s12, s59
	v_readlane_b32 s12, v241, 53
	s_add_u32 s58, s12, s58
	v_readlane_b32 s12, v241, 54
	s_addc_u32 s59, s12, s59
	v_readlane_b32 s12, v241, 55
	s_add_u32 s60, s12, s62
	v_readlane_b32 s12, v241, 56
	s_addc_u32 s61, s12, s63
	v_readlane_b32 s12, v241, 57
	s_add_u32 s62, s12, s62
	v_readlane_b32 s12, v241, 58
	v_mov_b32_e32 v187, 0
	s_addc_u32 s63, s12, s63
	s_mov_b32 s72, 0
	v_mov_b32_e32 v66, 0
	v_mov_b32_e32 v67, v187
	v_mov_b32_e32 v68, 0
	v_mov_b32_e32 v69, v187
	v_mov_b32_e32 v70, 0
	v_mov_b32_e32 v71, v187
	v_mov_b32_e32 v72, 0
	v_mov_b32_e32 v73, v187
	v_mov_b32_e32 v74, 0
	v_mov_b32_e32 v75, v187
	v_mov_b32_e32 v76, 0
	v_mov_b32_e32 v77, v187
	v_mov_b32_e32 v78, 0
	v_mov_b32_e32 v79, v187
	v_mov_b32_e32 v80, 0
	v_mov_b32_e32 v81, v187
	v_mov_b32_e32 v82, 0
	v_mov_b32_e32 v83, v187
	v_mov_b32_e32 v84, 0
	v_mov_b32_e32 v85, v187
	v_mov_b32_e32 v86, 0
	v_mov_b32_e32 v87, v187
	v_mov_b32_e32 v88, 0
	v_mov_b32_e32 v89, v187
	v_mov_b32_e32 v90, 0
	v_mov_b32_e32 v91, v187
	v_mov_b32_e32 v92, 0
	v_mov_b32_e32 v93, v187
	v_mov_b32_e32 v94, 0
	v_mov_b32_e32 v95, v187
	v_mov_b32_e32 v96, 0
	v_mov_b32_e32 v97, v187
	v_mov_b32_e32 v98, 0
	v_mov_b32_e32 v99, v187
	v_mov_b32_e32 v100, 0
	v_mov_b32_e32 v101, v187
	v_mov_b32_e32 v102, 0
	v_mov_b32_e32 v103, v187
	v_mov_b32_e32 v104, 0
	v_mov_b32_e32 v105, v187
	v_mov_b32_e32 v106, 0
	v_mov_b32_e32 v107, v187
	v_mov_b32_e32 v108, 0
	v_mov_b32_e32 v109, v187
	v_mov_b32_e32 v110, 0
	v_mov_b32_e32 v111, v187
	v_mov_b32_e32 v112, 0
	v_mov_b32_e32 v113, v187
	v_mov_b32_e32 v114, 0
	v_mov_b32_e32 v115, v187
	v_mov_b32_e32 v116, 0
	v_mov_b32_e32 v117, v187
	v_mov_b32_e32 v118, 0
	v_mov_b32_e32 v119, v187
	v_mov_b32_e32 v120, 0
	v_mov_b32_e32 v121, v187
	v_mov_b32_e32 v122, 0
	v_mov_b32_e32 v123, v187
	v_mov_b32_e32 v124, 0
	v_mov_b32_e32 v125, v187
	v_mov_b32_e32 v126, 0
	v_mov_b32_e32 v127, v187
	v_mov_b32_e32 v128, 0
	v_mov_b32_e32 v129, v187
	s_mov_b32 s12, 0x3ffffc0
